# speedup vs baseline: 1.0042x; 1.0007x over previous
; DEVINL void ret_out_phase(CParams& p, const Ctx& cx, int l, const GI& gi) {
;     ...
;     const float* gn = p.gn_gain + (size_t)l * DM + h * 256 + fr * 16;
;     float gv[16];
; #pragma unroll
;     for (int q4 = 0; q4 < 4; ++q4) { const float4 g4 = *(const float4*)(gn + q4 * 4); gv[q4 * 4] = g4.x; gv[q4 * 4 + 1] = g4.y; gv[q4 * 4 + 2] = g4.z; gv[q4 * 4 + 3] = g4.w; }
; #pragma unroll
;     for (int j = 0; j < 4; ++j) {
;       float sm = 0.f;
; #pragma unroll
;       for (int et = 0; et < 16; ++et) sm += o[et][j];
; #pragma unroll
;       for (int x = 1; x < 16; x <<= 1) sm += shflx(sm, x, lane);
;       const float mu = sm * (1.f / 256.f);
;       float vs = 0.f;
; #pragma unroll
;       for (int et = 0; et < 16; ++et) { const float d = o[et][j] - mu; vs += d * d; }
; #pragma unroll
;       for (int x = 1; x < 16; x <<= 1) vs += shflx(vs, x, lane);
;       const float rsd = rsqrtf(vs * (1.f / 256.f) + 1e-5f);
;       const size_t ro = (size_t)(row0 + wave * 16 + fq * 4 + j) * DM + h * 256 + fr * 16;
;       const bf16x8 s0 = *(const bf16x8*)(p.sg + ro), s1 = *(const bf16x8*)(p.sg + ro + 8);
.LBB0_268:
	v_add_u32_e32 v0, s28, v99
	s_waitcnt vmcnt(2)
	v_or_b32_e32 v22, v0, v137
	v_ashrrev_i32_e32 v23, 31, v22
	v_lshlrev_b64 v[2:3], 10, v[22:23]
	v_or3_b32 v2, v2, v98, s96
	v_lshlrev_b64 v[24:25], 1, v[2:3]
	s_waitcnt vmcnt(1)
	v_lshl_add_u64 v[26:27], s[6:7], 0, v[24:25]
	v_mov_b32_e32 v170, v26
	v_mov_b32_e32 v171, v27
	global_load_dwordx4 v[18:21], v[26:27], off offset:16
	v_add_f32_e32 v0, 0, v94
	v_lshlrev_b32_e32 v2, 2, v134
	v_add_f32_e32 v3, 0, v95
	v_add_f32_e32 v4, v0, v90
	v_bfrev_b32_e32 v0, 0.5
	v_mov_b32_e32 v104, v94
	v_bitop3_b32 v99, v2, 4, v0 bitop3:0x6c
	v_bitop3_b32 v94, v2, 8, v0 bitop3:0x6c
	v_bitop3_b32 v23, v2, 16, v0 bitop3:0x6c
	v_bitop3_b32 v0, v2, 32, v0 bitop3:0x6c
	v_add_f32_e32 v2, v3, v91
	v_add_f32_e32 v3, v4, v86
	v_add_f32_e32 v11, v3, v78
	v_add_f32_e32 v11, v11, v70
	v_add_f32_e32 v11, v11, v62
	v_add_f32_e32 v11, v11, v54
	v_add_f32_e32 v11, v11, v46
	v_add_f32_e32 v11, v11, v82
	v_add_f32_e32 v11, v11, v74
	v_add_f32_e32 v11, v11, v66
	v_add_f32_e32 v11, v11, v58
	v_add_f32_e32 v11, v11, v50
	v_add_f32_e32 v11, v11, v42
	v_add_f32_e32 v11, v11, v38
	v_add_f32_e32 v11, v11, v34
	ds_bpermute_b32 v12, v99, v11
	v_add_f32_e32 v10, v2, v87
	v_add_f32_e32 v10, v10, v79
	v_add_f32_e32 v10, v10, v71
	v_add_f32_e32 v10, v10, v63
	s_waitcnt lgkmcnt(0)
	v_add_f32_e32 v11, v11, v12
	ds_bpermute_b32 v12, v94, v11
	v_add_f32_e32 v10, v10, v55
	v_add_f32_e32 v10, v10, v47
	v_add_f32_e32 v10, v10, v83
	v_add_f32_e32 v10, v10, v75
	s_waitcnt lgkmcnt(0)
	v_add_f32_e32 v11, v11, v12
	v_add_f32_e32 v10, v10, v67
	ds_bpermute_b32 v12, v23, v11
	v_add_f32_e32 v10, v10, v59
	s_lshl_b32 s16, s27, 10
	v_add_f32_e32 v10, v10, v51
	s_add_u32 s16, s24, s16
	v_add_f32_e32 v10, v10, v43
	v_lshlrev_b32_e32 v14, 2, v98
	s_addc_u32 s17, s25, 0
	v_add_f32_e32 v10, v10, v39
	v_mov_b32_e32 v101, v42
	v_mov_b32_e32 v103, v34
	global_load_dwordx4 v[2:5], v14, s[16:17] offset:48
	global_load_dwordx4 v[6:9], v14, s[16:17] offset:32
	v_add_f32_e32 v34, v10, v35
	s_waitcnt lgkmcnt(0)
	v_add_f32_e32 v42, v11, v12
	global_load_dwordx4 v[10:13], v14, s[16:17] offset:16
	s_nop 0
	global_load_dwordx4 v[14:17], v14, s[16:17]
	s_nop 0
	global_load_dwordx4 v[26:29], v[26:27], off
	v_mov_b32_e32 v102, v38
	ds_bpermute_b32 v38, v99, v34
	s_waitcnt vmcnt(6)
	v_mov_b32_e32 v33, v58
	v_mov_b32_e32 v100, v50
	ds_bpermute_b32 v50, v0, v42
	v_mov_b32_e32 v105, v90
	s_waitcnt lgkmcnt(1)
	v_add_f32_e32 v38, v34, v38
	ds_bpermute_b32 v58, v94, v38
	v_mov_b32_e32 v90, v95
	s_waitcnt lgkmcnt(1)
	v_add_f32_e32 v34, v42, v50
	v_mul_f32_e32 v34, 0x3b800000, v34
	v_mov_b32_e32 v30, v82
	s_waitcnt lgkmcnt(0)
	v_add_f32_e32 v38, v38, v58
	ds_bpermute_b32 v42, v23, v38
	v_mov_b32_e32 v31, v74
	v_pk_add_f32 v[104:105], v[104:105], v[34:35] op_sel_hi:[1,0] neg_lo:[0,1] neg_hi:[0,1]
	v_mov_b32_e32 v74, v83
	v_mov_b32_e32 v32, v66
	s_waitcnt lgkmcnt(0)
	v_add_f32_e32 v38, v38, v42
	ds_bpermute_b32 v42, v0, v38
	v_pk_add_f32 v[30:31], v[30:31], v[34:35] op_sel_hi:[1,0] neg_lo:[0,1] neg_hi:[0,1]
	v_pk_add_f32 v[32:33], v[32:33], v[34:35] op_sel_hi:[1,0] neg_lo:[0,1] neg_hi:[0,1]
	v_pk_add_f32 v[100:101], v[100:101], v[34:35] op_sel_hi:[1,0] neg_lo:[0,1] neg_hi:[0,1]
	v_pk_add_f32 v[102:103], v[102:103], v[34:35] op_sel_hi:[1,0] neg_lo:[0,1] neg_hi:[0,1]
	v_mov_b32_e32 v58, v67
	v_pk_mul_f32 v[106:107], v[32:33], v[32:33]
	s_waitcnt vmcnt(5)
	s_mov_b32 s100, 0x1000
	s_mov_b32 s101, 0
	v_lshl_add_u64 v[168:169], v[170:171], 0, s[100:101]
	global_load_dwordx4 v[172:175], v[170:171], off offset:2064
	global_load_dwordx4 v[176:179], v[170:171], off offset:2048
	global_load_dwordx4 v[180:183], v[168:169], off offset:16
	global_load_dwordx4 v[184:187], v[168:169], off
	global_load_dwordx4 v[188:191], v[168:169], off offset:2064
	global_load_dwordx4 v[192:195], v[168:169], off offset:2048
	v_and_b32_e32 v113, 0xffff0000, v18
	v_lshlrev_b32_e32 v112, 16, v18
	v_and_b32_e32 v115, 0xffff0000, v19
	v_lshlrev_b32_e32 v114, 16, v19
	v_mov_b32_e32 v18, v86
	v_mov_b32_e32 v19, v78
	v_pk_add_f32 v[116:117], v[18:19], v[34:35] op_sel_hi:[1,0] neg_lo:[0,1] neg_hi:[0,1]
	v_mov_b32_e32 v18, v70
	v_mov_b32_e32 v19, v62
	v_pk_add_f32 v[118:119], v[18:19], v[34:35] op_sel_hi:[1,0] neg_lo:[0,1] neg_hi:[0,1]
	v_mov_b32_e32 v18, v54
	v_mov_b32_e32 v19, v46
	v_pk_add_f32 v[120:121], v[18:19], v[34:35] op_sel_hi:[1,0] neg_lo:[0,1] neg_hi:[0,1]
	s_waitcnt lgkmcnt(0)
; DEVINL float bf2f(u16 h) { return __uint_as_float(((unsigned)h) << 16); }
; DEVINL void ret_out_phase(CParams& p, const Ctx& cx, int l, const GI& gi) {
;     ...
;       float vs = 0.f;
; #pragma unroll
;       for (int et = 0; et < 16; ++et) { const float d = o[et][j] - mu; vs += d * d; }
; #pragma unroll
;       for (int x = 1; x < 16; x <<= 1) vs += shflx(vs, x, lane);
;       const float rsd = rsqrtf(vs * (1.f / 256.f) + 1e-5f);
;       const size_t ro = (size_t)(row0 + wave * 16 + fq * 4 + j) * DM + h * 256 + fr * 16;
;       const bf16x8 s0 = *(const bf16x8*)(p.sg + ro), s1 = *(const bf16x8*)(p.sg + ro + 8);
;       bf16x8 y0, y1;
; #pragma unroll
;       for (int et = 0; et < 8; ++et) {
;         y0[et] = (short)f2bf(bf2f((u16)s0[et]) * ((o[et][j] - mu) * rsd * gv[et]));
;         y1[et] = (short)f2bf(bf2f((u16)s1[et]) * ((o[et + 8][j] - mu) * rsd * gv[et + 8]));
	v_add_f32_e32 v18, v38, v42
	v_mul_f32_e32 v18, 0x3b800000, v18
	v_pk_add_f32 v[82:83], v[90:91], v[18:19] op_sel_hi:[1,0] neg_lo:[0,1] neg_hi:[0,1]
	v_mov_b32_e32 v78, v87
	v_mov_b32_e32 v86, v83
	v_mov_b32_e32 v87, v105
	v_pk_add_f32 v[78:79], v[78:79], v[18:19] op_sel_hi:[1,0] neg_lo:[0,1] neg_hi:[0,1]
	v_mov_b32_e32 v62, v71
	v_mov_b32_e32 v70, v82
	v_mov_b32_e32 v71, v104
	v_pk_mul_f32 v[86:87], v[86:87], v[86:87]
	v_pk_add_f32 v[62:63], v[62:63], v[18:19] op_sel_hi:[1,0] neg_lo:[0,1] neg_hi:[0,1]
	v_pk_fma_f32 v[70:71], v[70:71], v[70:71], v[86:87]
	v_mov_b32_e32 v86, v78
	v_mov_b32_e32 v87, v116
	v_mov_b32_e32 v90, v79
	v_mov_b32_e32 v91, v117
	v_pk_fma_f32 v[70:71], v[86:87], v[86:87], v[70:71]
	v_mov_b32_e32 v46, v55
	v_pk_fma_f32 v[70:71], v[90:91], v[90:91], v[70:71]
	v_mov_b32_e32 v86, v62
	v_mov_b32_e32 v87, v118
	v_pk_add_f32 v[46:47], v[46:47], v[18:19] op_sel_hi:[1,0] neg_lo:[0,1] neg_hi:[0,1]
	v_mov_b32_e32 v90, v63
	v_mov_b32_e32 v91, v119
	v_pk_fma_f32 v[70:71], v[86:87], v[86:87], v[70:71]
	v_mov_b32_e32 v86, v46
	v_pk_fma_f32 v[70:71], v[90:91], v[90:91], v[70:71]
	v_mov_b32_e32 v87, v120
	v_pk_add_f32 v[74:75], v[74:75], v[18:19] op_sel_hi:[1,0] neg_lo:[0,1] neg_hi:[0,1]
	v_mov_b32_e32 v42, v51
	v_mov_b32_e32 v34, v39
	v_mov_b32_e32 v90, v47
	v_mov_b32_e32 v91, v121
	v_pk_fma_f32 v[70:71], v[86:87], v[86:87], v[70:71]
	v_pk_add_f32 v[58:59], v[58:59], v[18:19] op_sel_hi:[1,0] neg_lo:[0,1] neg_hi:[0,1]
	v_pk_add_f32 v[42:43], v[42:43], v[18:19] op_sel_hi:[1,0] neg_lo:[0,1] neg_hi:[0,1]
	v_pk_add_f32 v[34:35], v[34:35], v[18:19] op_sel_hi:[1,0] neg_lo:[0,1] neg_hi:[0,1]
	v_mov_b32_e32 v18, v74
	v_mov_b32_e32 v19, v30
	v_pk_fma_f32 v[70:71], v[90:91], v[90:91], v[70:71]
	v_pk_mul_f32 v[66:67], v[58:59], v[58:59]
	v_mov_b32_e32 v54, v75
	v_mov_b32_e32 v55, v31
	v_pk_fma_f32 v[18:19], v[18:19], v[18:19], v[70:71]
	v_pk_mul_f32 v[108:109], v[100:101], v[100:101]
	v_pk_fma_f32 v[18:19], v[54:55], v[54:55], v[18:19]
	v_mov_b32_e32 v54, v66
	v_mov_b32_e32 v55, v106
	v_pk_mul_f32 v[50:51], v[42:43], v[42:43]
	v_pk_add_f32 v[18:19], v[54:55], v[18:19]
	v_mov_b32_e32 v106, v67
	v_pk_add_f32 v[18:19], v[106:107], v[18:19]
	v_mov_b32_e32 v54, v50
	v_mov_b32_e32 v55, v108
	v_pk_mul_f32 v[110:111], v[102:103], v[102:103]
	v_pk_mul_f32 v[38:39], v[34:35], v[34:35]
	v_pk_add_f32 v[18:19], v[54:55], v[18:19]
	v_mov_b32_e32 v108, v51
	v_pk_add_f32 v[18:19], v[108:109], v[18:19]
	v_mov_b32_e32 v50, v38
	v_mov_b32_e32 v51, v110
	v_pk_add_f32 v[18:19], v[50:51], v[18:19]
	v_mov_b32_e32 v110, v39
	v_pk_add_f32 v[18:19], v[110:111], v[18:19]
	ds_bpermute_b32 v39, v99, v19
	ds_bpermute_b32 v38, v99, v18
	s_waitcnt vmcnt(0)
	v_and_b32_e32 v55, 0xffff0000, v26
	v_lshlrev_b32_e32 v54, 16, v26
	v_and_b32_e32 v67, 0xffff0000, v27
	v_lshlrev_b32_e32 v66, 16, v27
	s_waitcnt lgkmcnt(0)
	v_pk_add_f32 v[18:19], v[18:19], v[38:39]
	ds_bpermute_b32 v39, v94, v19
	ds_bpermute_b32 v38, v94, v18
	v_and_b32_e32 v51, 0xffff0000, v20
	v_lshlrev_b32_e32 v50, 16, v20
	v_lshl_add_u64 v[90:91], s[14:15], 0, v[24:25]
	v_or_b32_e32 v24, 1, v22
	s_waitcnt lgkmcnt(0)
	v_pk_add_f32 v[18:19], v[18:19], v[38:39]
	ds_bpermute_b32 v27, v23, v19
	ds_bpermute_b32 v26, v23, v18
	v_and_b32_e32 v39, 0xffff0000, v21
	v_lshlrev_b32_e32 v38, 16, v21
	v_ashrrev_i32_e32 v25, 31, v24
	s_mov_b32 s16, 0x3727c5ac
	s_waitcnt lgkmcnt(0)
	v_pk_add_f32 v[18:19], v[18:19], v[26:27]
	ds_bpermute_b32 v21, v0, v19
	ds_bpermute_b32 v20, v0, v18
	v_lshlrev_b64 v[26:27], 10, v[24:25]
	v_mov_b64_e32 v[24:25], s[16:17]
	v_or3_b32 v26, v26, v98, s96
	v_lshlrev_b64 v[108:109], 1, v[26:27]
	s_waitcnt lgkmcnt(0)
	v_pk_add_f32 v[18:19], v[18:19], v[20:21]
	v_and_b32_e32 v71, 0xffff0000, v28
	v_pk_fma_f32 v[106:107], v[18:19], s[38:39], v[24:25] op_sel_hi:[1,0,0]
	v_lshlrev_b32_e32 v70, 16, v28
	v_mul_f32_e32 v18, 0x4b800000, v107
	v_cmp_gt_f32_e32 vcc, s35, v107
	v_and_b32_e32 v87, 0xffff0000, v29
	v_lshlrev_b32_e32 v86, 16, v29
	v_cndmask_b32_e32 v18, v107, v18, vcc
	v_rsq_f32_e32 v18, v18
	v_lshl_add_u64 v[110:111], s[6:7], 0, v[108:109]
	s_add_i32 s26, s26, s33
	s_cmp_ge_i32 s26, s22
	v_mul_f32_e32 v19, 0x45800000, v18
	v_cndmask_b32_e32 v122, v18, v19, vcc
	v_pk_mul_f32 v[20:21], v[30:31], v[122:123] op_sel_hi:[1,0]
	v_pk_mul_f32 v[18:19], v[104:105], v[122:123] op_sel_hi:[1,0]
	v_pk_mul_f32 v[20:21], v[6:7], v[20:21]
	v_pk_mul_f32 v[18:19], v[14:15], v[18:19]
	v_pk_mul_f32 v[20:21], v[20:21], v[112:113]
	v_pk_mul_f32 v[18:19], v[18:19], v[54:55]
	v_cvt_pk_bf16_f32 v26, v20, v21
	v_pk_mul_f32 v[20:21], v[116:117], v[122:123] op_sel_hi:[1,0]
	v_cvt_pk_bf16_f32 v18, v18, v19
	v_pk_mul_f32 v[20:21], v[16:17], v[20:21]
	v_pk_mul_f32 v[30:31], v[120:121], v[122:123] op_sel_hi:[1,0]
	v_pk_mul_f32 v[20:21], v[20:21], v[66:67]
	v_pk_mul_f32 v[30:31], v[12:13], v[30:31]
	v_cvt_pk_bf16_f32 v19, v20, v21
	v_pk_mul_f32 v[20:21], v[32:33], v[122:123] op_sel_hi:[1,0]
	v_pk_mul_f32 v[30:31], v[30:31], v[86:87]
	v_pk_mul_f32 v[20:21], v[8:9], v[20:21]
	v_pk_mul_f32 v[28:29], v[100:101], v[122:123] op_sel_hi:[1,0]
	v_pk_mul_f32 v[20:21], v[20:21], v[114:115]
	v_pk_mul_f32 v[28:29], v[2:3], v[28:29]
	v_cvt_pk_bf16_f32 v27, v20, v21
	v_pk_mul_f32 v[20:21], v[118:119], v[122:123] op_sel_hi:[1,0]
	v_pk_mul_f32 v[28:29], v[28:29], v[50:51]
	v_pk_mul_f32 v[20:21], v[10:11], v[20:21]
	v_cvt_pk_bf16_f32 v28, v28, v29
	v_pk_mul_f32 v[20:21], v[20:21], v[70:71]
	v_cmp_gt_f32_e32 vcc, s35, v106
	v_cvt_pk_bf16_f32 v20, v20, v21
	v_cvt_pk_bf16_f32 v21, v30, v31
	v_pk_mul_f32 v[30:31], v[102:103], v[122:123] op_sel_hi:[1,0]
	s_nop 0
	v_pk_mul_f32 v[30:31], v[4:5], v[30:31]
	s_nop 0
	v_pk_mul_f32 v[30:31], v[30:31], v[38:39]
; DEVINL float bf2f(u16 h) { return __uint_as_float(((unsigned)h) << 16); }
; DEVINL void ret_out_phase(CParams& p, const Ctx& cx, int l, const GI& gi) {
;     ...
;     for (int j = 0; j < 4; ++j) {
;       float sm = 0.f;
; #pragma unroll
;       for (int et = 0; et < 16; ++et) sm += o[et][j];
; #pragma unroll
;       for (int x = 1; x < 16; x <<= 1) sm += shflx(sm, x, lane);
;       const float mu = sm * (1.f / 256.f);
;       float vs = 0.f;
; #pragma unroll
;       for (int et = 0; et < 16; ++et) { const float d = o[et][j] - mu; vs += d * d; }
; #pragma unroll
;       for (int x = 1; x < 16; x <<= 1) vs += shflx(vs, x, lane);
;       const float rsd = rsqrtf(vs * (1.f / 256.f) + 1e-5f);
;       const size_t ro = (size_t)(row0 + wave * 16 + fq * 4 + j) * DM + h * 256 + fr * 16;
;       const bf16x8 s0 = *(const bf16x8*)(p.sg + ro), s1 = *(const bf16x8*)(p.sg + ro + 8);
;       bf16x8 y0, y1;
; #pragma unroll
;       for (int et = 0; et < 8; ++et) {
;         y0[et] = (short)f2bf(bf2f((u16)s0[et]) * ((o[et][j] - mu) * rsd * gv[et]));
;         y1[et] = (short)f2bf(bf2f((u16)s1[et]) * ((o[et + 8][j] - mu) * rsd * gv[et + 8]));
;       }
;       *(bf16x8*)(p.y + ro) = y0; *(bf16x8*)(p.y + ro + 8) = y1;
	s_nop 0
	v_cvt_pk_bf16_f32 v29, v30, v31
	global_store_dwordx4 v[90:91], v[18:21], off
	global_store_dwordx4 v[90:91], v[26:29], off offset:16
	s_nop 1
	v_mov_b32_e32 v18, v172
	v_mov_b32_e32 v19, v173
	v_mov_b32_e32 v20, v174
	v_mov_b32_e32 v21, v175
	v_mov_b32_e32 v26, v176
	v_mov_b32_e32 v27, v177
	v_mov_b32_e32 v28, v178
	v_mov_b32_e32 v29, v179
	v_and_b32_e32 v39, 0xffff0000, v20
	v_lshlrev_b32_e32 v38, 16, v20
	v_mul_f32_e32 v20, 0x4b800000, v106
	v_cndmask_b32_e32 v20, v106, v20, vcc
	v_rsq_f32_e32 v20, v20
	v_and_b32_e32 v67, 0xffff0000, v21
	v_lshlrev_b32_e32 v66, 16, v21
	v_and_b32_e32 v31, 0xffff0000, v18
	v_mul_f32_e32 v21, 0x45800000, v20
	v_cndmask_b32_e32 v86, v20, v21, vcc
	v_pk_mul_f32 v[20:21], v[82:83], v[86:87] op_sel_hi:[1,0]
	v_lshlrev_b32_e32 v30, 16, v18
	v_and_b32_e32 v33, 0xffff0000, v19
	v_lshlrev_b32_e32 v32, 16, v19
	v_and_b32_e32 v19, 0xffff0000, v26
	v_lshlrev_b32_e32 v18, 16, v26
	v_pk_mul_f32 v[20:21], v[14:15], v[20:21]
	v_and_b32_e32 v51, 0xffff0000, v27
	v_pk_mul_f32 v[18:19], v[20:21], v[18:19]
	v_pk_mul_f32 v[20:21], v[74:75], v[86:87] op_sel_hi:[1,0]
	v_lshlrev_b32_e32 v50, 16, v27
	v_pk_mul_f32 v[20:21], v[6:7], v[20:21]
	v_cvt_pk_bf16_f32 v18, v18, v19
	v_pk_mul_f32 v[20:21], v[20:21], v[30:31]
	v_pk_mul_f32 v[30:31], v[46:47], v[86:87] op_sel_hi:[1,0]
	v_cvt_pk_bf16_f32 v26, v20, v21
	v_pk_mul_f32 v[20:21], v[78:79], v[86:87] op_sel_hi:[1,0]
	v_and_b32_e32 v55, 0xffff0000, v28
	v_pk_mul_f32 v[20:21], v[16:17], v[20:21]
	v_lshlrev_b32_e32 v54, 16, v28
	v_pk_mul_f32 v[20:21], v[20:21], v[50:51]
	v_and_b32_e32 v71, 0xffff0000, v29
	v_cvt_pk_bf16_f32 v19, v20, v21
	v_pk_mul_f32 v[20:21], v[58:59], v[86:87] op_sel_hi:[1,0]
	v_lshlrev_b32_e32 v70, 16, v29
	v_pk_mul_f32 v[20:21], v[8:9], v[20:21]
	v_pk_mul_f32 v[30:31], v[12:13], v[30:31]
	v_pk_mul_f32 v[20:21], v[20:21], v[32:33]
	v_pk_mul_f32 v[30:31], v[30:31], v[70:71]
	v_cvt_pk_bf16_f32 v27, v20, v21
	v_pk_mul_f32 v[20:21], v[62:63], v[86:87] op_sel_hi:[1,0]
	v_pk_mul_f32 v[28:29], v[42:43], v[86:87] op_sel_hi:[1,0]
	v_pk_mul_f32 v[20:21], v[10:11], v[20:21]
	v_pk_mul_f32 v[28:29], v[2:3], v[28:29]
	v_pk_mul_f32 v[20:21], v[20:21], v[54:55]
	v_pk_mul_f32 v[28:29], v[28:29], v[38:39]
	v_cvt_pk_bf16_f32 v20, v20, v21
	v_cvt_pk_bf16_f32 v21, v30, v31
	v_pk_mul_f32 v[30:31], v[34:35], v[86:87] op_sel_hi:[1,0]
	v_cvt_pk_bf16_f32 v28, v28, v29
	v_pk_mul_f32 v[30:31], v[4:5], v[30:31]
	v_mov_b32_e32 v32, v68
	v_pk_mul_f32 v[30:31], v[30:31], v[66:67]
	v_mov_b32_e32 v33, v60
	v_cvt_pk_bf16_f32 v29, v30, v31
	v_lshl_add_u64 v[30:31], s[14:15], 0, v[108:109]
	global_store_dwordx4 v[30:31], v[18:21], off
	global_store_dwordx4 v[30:31], v[26:29], off offset:16
	v_add_f32_e32 v30, 0, v96
	v_or_b32_e32 v18, 2, v22
	v_ashrrev_i32_e32 v19, 31, v18
	v_lshlrev_b64 v[18:19], 10, v[18:19]
	v_or3_b32 v18, v18, v98, s96
	v_lshlrev_b64 v[26:27], 1, v[18:19]
	v_lshl_add_u64 v[28:29], s[6:7], 0, v[26:27]
	s_nop 1
	v_mov_b32_e32 v18, v180
	v_mov_b32_e32 v19, v181
	v_mov_b32_e32 v20, v182
	v_mov_b32_e32 v21, v183
	v_mov_b32_e32 v100, v184
	v_mov_b32_e32 v101, v185
	v_mov_b32_e32 v102, v186
	v_mov_b32_e32 v103, v187
	v_add_f32_e32 v30, v30, v92
	v_add_f32_e32 v30, v30, v88
	v_add_f32_e32 v30, v30, v80
	v_add_f32_e32 v30, v30, v72
	v_add_f32_e32 v30, v30, v64
	v_add_f32_e32 v30, v30, v56
	v_add_f32_e32 v30, v30, v48
	v_add_f32_e32 v30, v30, v84
	v_add_f32_e32 v30, v30, v76
	v_add_f32_e32 v30, v30, v68
	v_add_f32_e32 v30, v30, v60
	v_add_f32_e32 v30, v30, v52
	v_add_f32_e32 v30, v30, v44
	v_add_f32_e32 v30, v30, v40
	v_add_f32_e32 v30, v30, v36
	ds_bpermute_b32 v31, v99, v30
	v_mov_b32_e32 v29, v76
	v_mov_b32_e32 v50, v40
	v_mov_b32_e32 v51, v36
	v_mov_b32_e32 v58, v96
	s_waitcnt lgkmcnt(0)
	v_add_f32_e32 v30, v30, v31
	ds_bpermute_b32 v31, v94, v30
	v_mov_b32_e32 v59, v92
	v_mov_b32_e32 v62, v88
	v_mov_b32_e32 v63, v80
	v_mov_b32_e32 v66, v72
	s_waitcnt lgkmcnt(0)
	v_add_f32_e32 v30, v30, v31
	ds_bpermute_b32 v31, v23, v30
	v_mov_b32_e32 v67, v64
	v_mov_b32_e32 v70, v56
	v_mov_b32_e32 v71, v48
	v_mov_b32_e32 v76, v85
	s_waitcnt lgkmcnt(0)
	v_add_f32_e32 v30, v30, v31
	ds_bpermute_b32 v31, v0, v30
	v_mov_b32_e32 v92, v97
	v_mov_b32_e32 v80, v89
	v_mov_b32_e32 v64, v73
	v_mov_b32_e32 v60, v69
	s_waitcnt lgkmcnt(0)
	v_add_f32_e32 v28, v30, v31
	v_mul_f32_e32 v38, 0x3b800000, v28
	v_mov_b32_e32 v28, v84
	v_pk_add_f32 v[30:31], v[28:29], v[38:39] op_sel_hi:[1,0] neg_lo:[0,1] neg_hi:[0,1]
	v_pk_add_f32 v[32:33], v[32:33], v[38:39] op_sel_hi:[1,0] neg_lo:[0,1] neg_hi:[0,1]
	v_mov_b32_e32 v48, v57
	v_pk_mul_f32 v[42:43], v[32:33], v[32:33]
	v_or_b32_e32 v22, 3, v22
	v_and_b32_e32 v29, 0xffff0000, v18
	v_lshlrev_b32_e32 v28, 16, v18
	v_and_b32_e32 v35, 0xffff0000, v19
	v_lshlrev_b32_e32 v34, 16, v19
	v_mov_b32_e32 v18, v52
	v_mov_b32_e32 v19, v44
	v_pk_add_f32 v[18:19], v[18:19], v[38:39] op_sel_hi:[1,0] neg_lo:[0,1] neg_hi:[0,1]
	v_add_f32_e32 v39, 0, v97
	v_add_f32_e32 v39, v39, v93
	v_add_f32_e32 v39, v39, v89
	v_add_f32_e32 v39, v39, v81
	v_add_f32_e32 v39, v39, v73
	v_add_f32_e32 v39, v39, v65
	v_add_f32_e32 v39, v39, v57
	v_add_f32_e32 v39, v39, v49
	v_add_f32_e32 v39, v39, v85
	v_add_f32_e32 v39, v39, v77
	v_add_f32_e32 v39, v39, v69
	v_add_f32_e32 v39, v39, v61
	v_add_f32_e32 v39, v39, v53
	v_add_f32_e32 v39, v39, v45
	v_add_f32_e32 v39, v39, v41
	v_add_f32_e32 v39, v39, v37
	ds_bpermute_b32 v44, v99, v39
	v_pk_add_f32 v[50:51], v[50:51], v[38:39] op_sel_hi:[1,0] neg_lo:[0,1] neg_hi:[0,1]
	v_mov_b32_e32 v57, v31
	v_pk_mul_f32 v[46:47], v[18:19], v[18:19]
	v_pk_mul_f32 v[54:55], v[50:51], v[50:51]
	s_waitcnt lgkmcnt(0)
	v_add_f32_e32 v36, v39, v44
	ds_bpermute_b32 v39, v94, v36
	v_mov_b32_e32 v44, v53
	s_waitcnt lgkmcnt(0)
; DEVINL float bf2f(u16 h) { return __uint_as_float(((unsigned)h) << 16); }
; DEVINL void ret_out_phase(CParams& p, const Ctx& cx, int l, const GI& gi) {
;     ...
;     for (int j = 0; j < 4; ++j) {
;       float sm = 0.f;
; #pragma unroll
;       for (int et = 0; et < 16; ++et) sm += o[et][j];
; #pragma unroll
;       for (int x = 1; x < 16; x <<= 1) sm += shflx(sm, x, lane);
;       const float mu = sm * (1.f / 256.f);
;       float vs = 0.f;
; #pragma unroll
;       for (int et = 0; et < 16; ++et) { const float d = o[et][j] - mu; vs += d * d; }
; #pragma unroll
;       for (int x = 1; x < 16; x <<= 1) vs += shflx(vs, x, lane);
;       const float rsd = rsqrtf(vs * (1.f / 256.f) + 1e-5f);
;       const size_t ro = (size_t)(row0 + wave * 16 + fq * 4 + j) * DM + h * 256 + fr * 16;
;       const bf16x8 s0 = *(const bf16x8*)(p.sg + ro), s1 = *(const bf16x8*)(p.sg + ro + 8);
;       bf16x8 y0, y1;
; #pragma unroll
;       for (int et = 0; et < 8; ++et) {
;         y0[et] = (short)f2bf(bf2f((u16)s0[et]) * ((o[et][j] - mu) * rsd * gv[et]));
;         y1[et] = (short)f2bf(bf2f((u16)s1[et]) * ((o[et + 8][j] - mu) * rsd * gv[et + 8]));
;       }
;       *(bf16x8*)(p.y + ro) = y0; *(bf16x8*)(p.y + ro + 8) = y1;
	v_add_f32_e32 v36, v36, v39
	v_pk_add_f32 v[58:59], v[58:59], v[38:39] op_sel_hi:[1,0] neg_lo:[0,1] neg_hi:[0,1]
	ds_bpermute_b32 v39, v23, v36
	v_mov_b32_e32 v73, v58
	s_waitcnt lgkmcnt(0)
	v_add_f32_e32 v36, v36, v39
	ds_bpermute_b32 v40, v0, v36
	v_pk_add_f32 v[62:63], v[62:63], v[38:39] op_sel_hi:[1,0] neg_lo:[0,1] neg_hi:[0,1]
	v_pk_add_f32 v[66:67], v[66:67], v[38:39] op_sel_hi:[1,0] neg_lo:[0,1] neg_hi:[0,1]
	v_pk_add_f32 v[38:39], v[70:71], v[38:39] op_sel_hi:[1,0] neg_lo:[0,1] neg_hi:[0,1]
	v_mov_b32_e32 v83, v63
	s_waitcnt lgkmcnt(0)
	v_add_f32_e32 v36, v36, v40
	v_mul_f32_e32 v40, 0x3b800000, v36
	v_pk_add_f32 v[70:71], v[76:77], v[40:41] op_sel_hi:[1,0] neg_lo:[0,1] neg_hi:[0,1]
	v_pk_add_f32 v[76:77], v[92:93], v[40:41] op_sel_hi:[1,0] neg_lo:[0,1] neg_hi:[0,1]
	v_pk_add_f32 v[78:79], v[80:81], v[40:41] op_sel_hi:[1,0] neg_lo:[0,1] neg_hi:[0,1]
	v_mov_b32_e32 v80, v77
	v_mov_b32_e32 v81, v59
	v_mov_b32_e32 v72, v76
	v_pk_mul_f32 v[80:81], v[80:81], v[80:81]
	v_pk_add_f32 v[64:65], v[64:65], v[40:41] op_sel_hi:[1,0] neg_lo:[0,1] neg_hi:[0,1]
	v_pk_fma_f32 v[72:73], v[72:73], v[72:73], v[80:81]
	v_mov_b32_e32 v80, v78
	v_mov_b32_e32 v81, v62
	v_mov_b32_e32 v82, v79
	v_pk_fma_f32 v[72:73], v[80:81], v[80:81], v[72:73]
	v_mov_b32_e32 v36, v41
	v_pk_fma_f32 v[72:73], v[82:83], v[82:83], v[72:73]
	v_mov_b32_e32 v80, v64
	v_mov_b32_e32 v81, v66
	v_pk_add_f32 v[60:61], v[60:61], v[40:41] op_sel_hi:[1,0] neg_lo:[0,1] neg_hi:[0,1]
	v_pk_add_f32 v[44:45], v[44:45], v[40:41] op_sel_hi:[1,0] neg_lo:[0,1] neg_hi:[0,1]
	v_pk_add_f32 v[36:37], v[36:37], v[40:41] op_sel_hi:[1,0] neg_lo:[0,1] neg_hi:[0,1]
	v_pk_add_f32 v[40:41], v[48:49], v[40:41] op_sel_hi:[1,0] neg_lo:[0,1] neg_hi:[0,1]
	v_mov_b32_e32 v82, v65
	v_mov_b32_e32 v83, v67
	v_pk_fma_f32 v[72:73], v[80:81], v[80:81], v[72:73]
	v_mov_b32_e32 v80, v40
	v_pk_fma_f32 v[72:73], v[82:83], v[82:83], v[72:73]
	v_mov_b32_e32 v81, v38
	v_mov_b32_e32 v82, v41
	v_mov_b32_e32 v83, v39
	v_pk_fma_f32 v[72:73], v[80:81], v[80:81], v[72:73]
	v_mov_b32_e32 v48, v70
	v_mov_b32_e32 v49, v30
	v_pk_fma_f32 v[72:73], v[82:83], v[82:83], v[72:73]
	v_pk_mul_f32 v[68:69], v[60:61], v[60:61]
	v_mov_b32_e32 v56, v71
	v_pk_fma_f32 v[48:49], v[48:49], v[48:49], v[72:73]
	v_pk_mul_f32 v[52:53], v[44:45], v[44:45]
	v_pk_fma_f32 v[48:49], v[56:57], v[56:57], v[48:49]
	v_mov_b32_e32 v56, v68
	v_mov_b32_e32 v57, v42
	v_pk_add_f32 v[48:49], v[56:57], v[48:49]
	v_mov_b32_e32 v42, v69
	v_pk_add_f32 v[42:43], v[42:43], v[48:49]
	v_mov_b32_e32 v48, v52
	v_mov_b32_e32 v49, v46
	v_pk_mul_f32 v[74:75], v[36:37], v[36:37]
	v_pk_add_f32 v[42:43], v[48:49], v[42:43]
	v_mov_b32_e32 v46, v53
	v_pk_add_f32 v[42:43], v[46:47], v[42:43]
	v_mov_b32_e32 v46, v74
	v_mov_b32_e32 v47, v54
	v_pk_add_f32 v[42:43], v[46:47], v[42:43]
	v_mov_b32_e32 v54, v75
	v_pk_add_f32 v[42:43], v[54:55], v[42:43]
	ds_bpermute_b32 v47, v99, v43
	ds_bpermute_b32 v46, v99, v42
	v_and_b32_e32 v49, 0xffff0000, v20
	v_lshlrev_b32_e32 v48, 16, v20
	v_and_b32_e32 v69, 0xffff0000, v21
	v_lshlrev_b32_e32 v68, 16, v21
	s_waitcnt lgkmcnt(0)
	v_pk_add_f32 v[42:43], v[42:43], v[46:47]
	ds_bpermute_b32 v47, v94, v43
	ds_bpermute_b32 v46, v94, v42
	v_and_b32_e32 v53, 0xffff0000, v100
	v_lshlrev_b32_e32 v52, 16, v100
	v_and_b32_e32 v55, 0xffff0000, v101
	v_lshlrev_b32_e32 v54, 16, v101
	s_waitcnt lgkmcnt(0)
	v_pk_add_f32 v[42:43], v[42:43], v[46:47]
	ds_bpermute_b32 v47, v23, v43
	ds_bpermute_b32 v46, v23, v42
	v_ashrrev_i32_e32 v23, 31, v22
	v_lshlrev_b64 v[22:23], 10, v[22:23]
	v_or3_b32 v22, v22, v98, s96
	v_lshlrev_b64 v[74:75], 1, v[22:23]
	s_waitcnt lgkmcnt(0)
	v_pk_add_f32 v[20:21], v[42:43], v[46:47]
	ds_bpermute_b32 v43, v0, v21
	ds_bpermute_b32 v42, v0, v20
	v_lshl_add_u64 v[46:47], s[14:15], 0, v[26:27]
	v_and_b32_e32 v57, 0xffff0000, v102
	v_lshlrev_b32_e32 v56, 16, v102
	v_and_b32_e32 v73, 0xffff0000, v103
	s_waitcnt lgkmcnt(0)
	v_pk_add_f32 v[20:21], v[20:21], v[42:43]
	v_lshlrev_b32_e32 v72, 16, v103
	v_pk_fma_f32 v[42:43], v[20:21], s[38:39], v[24:25] op_sel_hi:[1,0,0]
	v_lshl_add_u64 v[80:81], s[6:7], 0, v[74:75]
	v_mul_f32_e32 v0, 0x4b800000, v43
	v_cmp_gt_f32_e32 vcc, s35, v43
	s_nop 1
	v_cndmask_b32_e32 v0, v43, v0, vcc
	v_rsq_f32_e32 v0, v0
	s_nop 0
	v_mul_f32_e32 v20, 0x45800000, v0
	v_cndmask_b32_e32 v0, v0, v20, vcc
	v_pk_mul_f32 v[22:23], v[30:31], v[0:1] op_sel_hi:[1,0]
	v_pk_mul_f32 v[20:21], v[58:59], v[0:1] op_sel_hi:[1,0]
	v_pk_mul_f32 v[22:23], v[6:7], v[22:23]
	v_pk_mul_f32 v[20:21], v[14:15], v[20:21]
	v_pk_mul_f32 v[22:23], v[22:23], v[28:29]
	v_pk_mul_f32 v[20:21], v[20:21], v[52:53]
	v_cvt_pk_bf16_f32 v24, v22, v23
	v_pk_mul_f32 v[22:23], v[62:63], v[0:1] op_sel_hi:[1,0]
	v_cvt_pk_bf16_f32 v20, v20, v21
	v_pk_mul_f32 v[22:23], v[16:17], v[22:23]
	v_pk_mul_f32 v[18:19], v[18:19], v[0:1] op_sel_hi:[1,0]
	v_pk_mul_f32 v[22:23], v[22:23], v[54:55]
	v_pk_mul_f32 v[18:19], v[2:3], v[18:19]
	v_cvt_pk_bf16_f32 v21, v22, v23
	v_pk_mul_f32 v[22:23], v[32:33], v[0:1] op_sel_hi:[1,0]
	v_pk_mul_f32 v[18:19], v[18:19], v[48:49]
	v_pk_mul_f32 v[22:23], v[8:9], v[22:23]
	v_cvt_pk_bf16_f32 v26, v18, v19
	v_pk_mul_f32 v[22:23], v[22:23], v[34:35]
	v_pk_mul_f32 v[18:19], v[38:39], v[0:1] op_sel_hi:[1,0]
	v_cvt_pk_bf16_f32 v25, v22, v23
	v_pk_mul_f32 v[22:23], v[66:67], v[0:1] op_sel_hi:[1,0]
	v_pk_mul_f32 v[18:19], v[12:13], v[18:19]
	v_pk_mul_f32 v[22:23], v[10:11], v[22:23]
	v_pk_mul_f32 v[18:19], v[18:19], v[72:73]
	v_pk_mul_f32 v[22:23], v[22:23], v[56:57]
	v_cmp_gt_f32_e32 vcc, s35, v42
	v_cvt_pk_bf16_f32 v22, v22, v23
	v_cvt_pk_bf16_f32 v23, v18, v19
	v_pk_mul_f32 v[18:19], v[50:51], v[0:1] op_sel_hi:[1,0]
	v_mul_f32_e32 v0, 0x4b800000, v42
; DEVINL float bf2f(u16 h) { return __uint_as_float(((unsigned)h) << 16); }
; DEVINL void ret_out_phase(CParams& p, const Ctx& cx, int l, const GI& gi) {
;     ...
;   for (int it = cx.bid; it < nitems; it += cx.nb) {
;     int tid = cx.tid; asm volatile("" : "+v"(tid));
;     const int wave = tid >> 6, lane = tid & 63, fr = lane & 15, fq = lane >> 4;
;     const int srow = tid >> 4, sch = tid & 15;
;     const int chunk = it >> 2, h = it & 3, row0 = chunk * 128;
;     const size_t ch = (size_t)chunk * 4 + h;
;     const float lgf = p.lg2[(l * 2 + 0) * 4 + h], lgb = p.lg2[(l * 2 + 1) * 4 + h];
;     bf16x8 ra[4], rb[8];
;     {
;       const u16* qg = p.q + (size_t)(row0 + srow) * 512 + h * 128 + sch * 8;
;       const u16* kg = p.k + (size_t)(row0 + srow) * 512 + h * 128 + sch * 8;
; #pragma unroll
;       for (int i = 0; i < 4; ++i) { ra[i] = *(const bf16x8*)(qg + (size_t)i * 32 * 512); rb[i] = *(const bf16x8*)(kg + (size_t)i * 32 * 512); }
; #pragma unroll
;       for (int i = 0; i < 4; ++i) { *(bf16x8*)(Ab + (srow + i * 32) * 272 + sch * 16) = ra[i]; *(bf16x8*)(Bb + (srow + i * 32) * 272 + sch * 16) = rb[i]; }
;     }
;     __syncthreads();
;     ...
;       for (int et = 0; et < 8; ++et) {
;         y0[et] = (short)f2bf(bf2f((u16)s0[et]) * ((o[et][j] - mu) * rsd * gv[et]));
;         y1[et] = (short)f2bf(bf2f((u16)s1[et]) * ((o[et + 8][j] - mu) * rsd * gv[et + 8]));
;       }
;       *(bf16x8*)(p.y + ro) = y0; *(bf16x8*)(p.y + ro + 8) = y1;
	v_pk_mul_f32 v[18:19], v[4:5], v[18:19]
	v_cndmask_b32_e32 v0, v42, v0, vcc
	v_pk_mul_f32 v[18:19], v[18:19], v[68:69]
	v_rsq_f32_e32 v0, v0
	v_cvt_pk_bf16_f32 v27, v18, v19
	global_store_dwordx4 v[46:47], v[20:23], off
	global_store_dwordx4 v[46:47], v[24:27], off offset:16
	s_nop 1
	v_mov_b32_e32 v18, v188
	v_mov_b32_e32 v19, v189
	v_mov_b32_e32 v20, v190
	v_mov_b32_e32 v21, v191
	v_mov_b32_e32 v22, v192
	v_mov_b32_e32 v23, v193
	v_mov_b32_e32 v24, v194
	v_mov_b32_e32 v25, v195
	v_and_b32_e32 v27, 0xffff0000, v18
	v_and_b32_e32 v31, 0xffff0000, v22
	v_lshlrev_b32_e32 v30, 16, v22
	v_and_b32_e32 v33, 0xffff0000, v23
	v_lshlrev_b32_e32 v32, 16, v23
	v_and_b32_e32 v23, 0xffff0000, v24
	v_lshlrev_b32_e32 v22, 16, v24
	v_mul_f32_e32 v24, 0x45800000, v0
	v_cndmask_b32_e32 v0, v0, v24, vcc
	v_lshlrev_b32_e32 v26, 16, v18
	v_and_b32_e32 v29, 0xffff0000, v19
	v_lshlrev_b32_e32 v28, 16, v19
	v_and_b32_e32 v19, 0xffff0000, v20
	v_lshlrev_b32_e32 v18, 16, v20
	v_and_b32_e32 v35, 0xffff0000, v21
	v_lshlrev_b32_e32 v34, 16, v21
	v_and_b32_e32 v21, 0xffff0000, v25
	v_lshlrev_b32_e32 v20, 16, v25
	v_pk_mul_f32 v[24:25], v[76:77], v[0:1] op_sel_hi:[1,0]
	s_nop 0
	v_pk_mul_f32 v[14:15], v[14:15], v[24:25]
	v_pk_mul_f32 v[24:25], v[70:71], v[0:1] op_sel_hi:[1,0]
	v_pk_mul_f32 v[14:15], v[14:15], v[30:31]
	v_pk_mul_f32 v[6:7], v[6:7], v[24:25]
	v_pk_mul_f32 v[24:25], v[78:79], v[0:1] op_sel_hi:[1,0]
	v_cvt_pk_bf16_f32 v14, v14, v15
	v_pk_mul_f32 v[16:17], v[16:17], v[24:25]
	v_pk_mul_f32 v[6:7], v[6:7], v[26:27]
	v_pk_mul_f32 v[16:17], v[16:17], v[32:33]
	v_cvt_pk_bf16_f32 v6, v6, v7
	v_cvt_pk_bf16_f32 v15, v16, v17
	v_pk_mul_f32 v[16:17], v[60:61], v[0:1] op_sel_hi:[1,0]
	s_nop 0
	v_pk_mul_f32 v[8:9], v[8:9], v[16:17]
	s_nop 0
	v_pk_mul_f32 v[8:9], v[8:9], v[28:29]
	s_nop 0
	v_cvt_pk_bf16_f32 v7, v8, v9
	v_pk_mul_f32 v[8:9], v[64:65], v[0:1] op_sel_hi:[1,0]
	s_nop 0
	v_pk_mul_f32 v[8:9], v[10:11], v[8:9]
	s_nop 0
	v_pk_mul_f32 v[8:9], v[8:9], v[22:23]
	s_nop 0
	v_cvt_pk_bf16_f32 v16, v8, v9
	v_pk_mul_f32 v[8:9], v[44:45], v[0:1] op_sel_hi:[1,0]
	s_nop 0
	v_pk_mul_f32 v[2:3], v[2:3], v[8:9]
	s_nop 0
	v_pk_mul_f32 v[2:3], v[2:3], v[18:19]
	s_nop 0
	v_cvt_pk_bf16_f32 v8, v2, v3
	v_pk_mul_f32 v[2:3], v[40:41], v[0:1] op_sel_hi:[1,0]
	s_nop 0
	v_pk_mul_f32 v[2:3], v[12:13], v[2:3]
	s_nop 0
	v_pk_mul_f32 v[2:3], v[2:3], v[20:21]
	s_nop 0
	v_cvt_pk_bf16_f32 v17, v2, v3
	v_pk_mul_f32 v[2:3], v[36:37], v[0:1] op_sel_hi:[1,0]
	s_nop 0
	v_pk_mul_f32 v[2:3], v[4:5], v[2:3]
	s_nop 0
	v_pk_mul_f32 v[2:3], v[2:3], v[34:35]
	s_nop 0
	v_cvt_pk_bf16_f32 v9, v2, v3
	v_lshl_add_u64 v[2:3], s[14:15], 0, v[74:75]
	global_store_dwordx4 v[2:3], v[14:17], off
	global_store_dwordx4 v[2:3], v[6:9], off offset:16
	s_cbranch_scc1 .LBB0_275
.LBB0_269:
	v_readfirstlane_b32 s100, v234
	s_nop 3
	s_lshr_b32 s100, s100, 6
	s_cmp_ge_u32 s100, 4
	s_cbranch_scc1 .Lprio_269_done
	s_setprio 1
.Lprio_269_done:
	s_and_b32 s27, s26, 3
	s_or_b32 s18, s27, s23
	s_ashr_i32 s16, s26, 2
	s_ashr_i32 s19, s18, 31
	s_lshl_b32 s28, s16, 7
	s_lshl_b64 s[18:19], s[18:19], 2
	s_add_u32 s18, s8, s18
	v_mov_b32_e32 v134, v150
	s_addc_u32 s19, s9, s19
	global_load_dword v84, v1, s[18:19]
	global_load_dword v86, v1, s[18:19] offset:16
	s_load_dwordx2 s[18:19], s[88:89], 0x178
	v_ashrrev_i32_e32 v85, 4, v134
	v_add_u32_e32 v2, s28, v85
	v_ashrrev_i32_e32 v3, 31, v2
	v_lshlrev_b64 v[2:3], 10, v[2:3]
	s_waitcnt lgkmcnt(0)
	v_lshl_add_u64 v[4:5], s[18:19], 0, v[2:3]
	s_load_dwordx2 s[18:19], s[88:89], 0x190
	v_and_b32_e32 v82, 15, v134
	s_lshl_b32 s96, s27, 8
	v_lshl_add_u64 v[4:5], v[4:5], 0, s[96:97]
	v_lshlrev_b32_e32 v98, 4, v82
	v_mov_b32_e32 v99, v1
	v_lshl_add_u64 v[14:15], v[4:5], 0, v[98:99]
	s_waitcnt lgkmcnt(0)
	v_lshl_add_u64 v[2:3], s[18:19], 0, v[2:3]
	v_lshl_add_u64 v[2:3], v[2:3], 0, s[96:97]
	v_add_co_u32_e32 v6, vcc, s34, v14
	v_lshl_add_u64 v[16:17], v[2:3], 0, v[98:99]
	s_nop 0
	v_addc_co_u32_e32 v7, vcc, 0, v15, vcc
	global_load_dwordx4 v[46:49], v[14:15], off
	global_load_dwordx4 v[2:5], v[16:17], off
	global_load_dwordx4 v[42:45], v[6:7], off
	v_add_co_u32_e32 v6, vcc, s34, v16
	s_mov_b32 s17, 0x10000
	s_nop 0
	v_addc_co_u32_e32 v7, vcc, 0, v17, vcc
	v_add_co_u32_e32 v10, vcc, s17, v14
	global_load_dwordx4 v[6:9], v[6:7], off
	s_nop 0
	v_addc_co_u32_e32 v11, vcc, 0, v15, vcc
	global_load_dwordx4 v[38:41], v[10:11], off
	v_add_co_u32_e32 v10, vcc, s17, v16
	s_mov_b32 s17, 0x18000
	s_nop 0
	v_addc_co_u32_e32 v11, vcc, 0, v17, vcc
	v_add_co_u32_e32 v14, vcc, s17, v14
	global_load_dwordx4 v[10:13], v[10:11], off
	s_nop 0
	v_addc_co_u32_e32 v15, vcc, 0, v15, vcc
	global_load_dwordx4 v[34:37], v[14:15], off
	v_add_co_u32_e32 v14, vcc, s17, v16
	s_ashr_i32 s17, s16, 31
	s_nop 0
	v_addc_co_u32_e32 v15, vcc, 0, v17, vcc
	global_load_dwordx4 v[14:17], v[14:15], off
	s_lshl_b64 s[16:17], s[16:17], 17
	s_lshl_b32 s18, s27, 15
	s_or_b32 s16, s16, s18
	s_lshl_b64 s[16:17], s[16:17], 1
	v_add_u32_e32 v18, 0, v98
	v_mul_lo_u32 v88, v85, s36
	s_add_u32 s18, s4, s16
	v_lshlrev_b32_e32 v100, 7, v85
	v_add_u32_e32 v135, v18, v88
	s_addc_u32 s19, s5, s17
	v_ashrrev_i32_e32 v101, 31, v100
	v_ashrrev_i32_e32 v50, 2, v134
	v_and_b32_e32 v51, 48, v134
	v_bfe_u32 v87, v134, 4, 2
	v_lshlrev_b32_e32 v137, 2, v87
	v_lshl_add_u32 v107, v82, 1, 0
	v_or_b32_e32 v106, 16, v82
	v_or_b32_e32 v105, 32, v82
	v_or_b32_e32 v104, 48, v82
	v_or_b32_e32 v95, 64, v82
	v_or_b32_e32 v94, 0x50, v82
	v_or_b32_e32 v93, 0x60, v82
	v_or_b32_e32 v92, 0x70, v82
	v_lshrrev_b32_e32 v83, 4, v134
	v_add_u32_e32 v89, 32, v85
	v_add_u32_e32 v90, 64, v85
	v_add_u32_e32 v91, 0x60, v85
	v_lshlrev_b32_e32 v0, 3, v82
	s_mov_b32 s29, 1
	v_lshlrev_b32_e32 v0, 1, v0
	s_waitcnt vmcnt(0)
	ds_write_b128 v135, v[46:49]
	ds_write_b128 v135, v[2:5] offset:34816
	v_lshl_add_u64 v[2:3], v[100:101], 1, s[18:19]
	v_lshl_add_u64 v[30:31], v[2:3], 0, v[98:99]
	s_movk_i32 s18, 0x2000
	ds_write_b128 v135, v[42:45] offset:8704
	ds_write_b128 v135, v[6:9] offset:43520
	v_add_co_u32_e32 v6, vcc, s18, v30
	v_and_b32_e32 v99, -16, v50
	s_nop 0
	v_addc_co_u32_e32 v7, vcc, 0, v31, vcc
	v_bfi_b32 v50, -16, v50, v134
	ds_write_b128 v135, v[38:41] offset:17408
	ds_write_b128 v135, v[10:13] offset:52224
	v_add_co_u32_e32 v10, vcc, s30, v30
	v_mul_lo_u32 v50, v50, s36
	s_nop 0
	v_addc_co_u32_e32 v11, vcc, 0, v31, vcc
	v_add_u32_e32 v50, 0, v50
	ds_write_b128 v135, v[34:37] offset:26112
	ds_write_b128 v135, v[14:17] offset:60928
	v_add_co_u32_e32 v14, vcc, s31, v30
	v_add_u32_e32 v136, v50, v51
	s_waitcnt lgkmcnt(0)
	s_barrier
; DEVINL void ret_out_phase(CParams& p, const Ctx& cx, int l, const GI& gi) {
;     ...
;     {
;       const u16* g = p.vT + ch * 32768 + srow * 128 + sch * 8;
; #pragma unroll
;       for (int i = 0; i < 8; ++i) rb[i] = *(const bf16x8*)(g + i * 32 * 128);
;     }
;     {
;       f32x4 s[8];
; #pragma unroll
;       for (int mt = 0; mt < 8; ++mt) s[mt] = f32x4{0.f, 0.f, 0.f, 0.f};
; #pragma unroll
;       for (int ks = 0; ks < 4; ++ks) {
;         const bf16x8 a = *(const bf16x8*)(Ab + (wave * 16 + fr) * 272 + ks * 64 + fq * 16);
; #pragma unroll
;         for (int mt = 0; mt < 8; ++mt) {
;           const bf16x8 bb = *(const bf16x8*)(Bb + (mt * 16 + fr) * 272 + ks * 64 + fq * 16);
;           s[mt] = __builtin_amdgcn_mfma_f32_16x16x32_bf16(a, bb, s[mt], 0, 0, 0);
;         }
;       }
; #pragma unroll
;       for (int mt = 0; mt < 8; ++mt)
; #pragma unroll
;         for (int j = 0; j < 4; ++j) {
;           const int n = wave * 16 + fq * 4 + j, m = mt * 16 + fr, d = n - m;
;           const float dec = d >= 0 ? exp2f((float)d * lgf) : exp2f((float)(-d) * lgb);
;           *(u16*)(Ab + n * 272 + m * 2) = f2bf(s[mt][j] * dec);
;         }
	v_addc_co_u32_e32 v15, vcc, 0, v31, vcc
	ds_read_b128 v[52:55], v136
	v_add_co_u32_e32 v18, vcc, s34, v30
	s_mov_b32 s18, 0xa000
	s_nop 0
	v_addc_co_u32_e32 v19, vcc, 0, v31, vcc
	v_mul_u32_u24_e32 v50, 0x110, v82
	v_add_co_u32_e32 v22, vcc, s18, v30
	v_add3_u32 v50, 0, v51, v50
	s_nop 0
	v_addc_co_u32_e32 v23, vcc, 0, v31, vcc
	s_mov_b32 s18, 0xc000
	ds_read_b128 v[56:59], v50 offset:34816
	ds_read_b128 v[60:63], v50 offset:39168
	ds_read_b128 v[64:67], v50 offset:43520
	ds_read_b128 v[68:71], v50 offset:47872
	ds_read_b128 v[72:75], v50 offset:52224
	ds_read_b128 v[76:79], v50 offset:56576
	ds_read_b128 v[108:111], v50 offset:60928
	ds_read_b128 v[112:115], v50 offset:65280
	v_add_co_u32_e32 v26, vcc, s18, v30
	s_mov_b32 s18, 0xe000
	s_nop 0
	v_addc_co_u32_e32 v27, vcc, 0, v31, vcc
	global_load_dwordx4 v[2:5], v[30:31], off
	v_add_co_u32_e32 v30, vcc, s18, v30
	global_load_dwordx4 v[6:9], v[6:7], off
	s_nop 0
	v_addc_co_u32_e32 v31, vcc, 0, v31, vcc
	global_load_dwordx4 v[10:13], v[10:11], off
	s_waitcnt lgkmcnt(7)
	v_mfma_f32_16x16x32_bf16 v[56:59], v[52:55], v[56:59], 0
	global_load_dwordx4 v[14:17], v[14:15], off
	v_or_b32_e32 v96, v137, v99
	global_load_dwordx4 v[18:21], v[18:19], off
	s_waitcnt lgkmcnt(6)
	v_mfma_f32_16x16x32_bf16 v[60:63], v[52:55], v[60:63], 0
	global_load_dwordx4 v[22:25], v[22:23], off
	v_sub_u32_e32 v97, v96, v82
	global_load_dwordx4 v[26:29], v[26:27], off
	s_waitcnt lgkmcnt(5)
	v_mfma_f32_16x16x32_bf16 v[64:67], v[52:55], v[64:67], 0
	global_load_dwordx4 v[30:33], v[30:31], off
	v_sub_u32_e32 v102, 0, v97
	v_max_i32_e32 v102, v97, v102
	s_waitcnt lgkmcnt(4)
	v_mfma_f32_16x16x32_bf16 v[68:71], v[52:55], v[68:71], 0
	v_cvt_f32_u32_e32 v102, v102
	v_cmp_gt_i32_e32 vcc, 0, v97
	s_movk_i32 s18, 0x1100
	s_waitcnt lgkmcnt(3)
	v_mfma_f32_16x16x32_bf16 v[72:75], v[52:55], v[72:75], 0
	v_cndmask_b32_e32 v97, v84, v86, vcc
	v_mul_f32_e32 v103, v97, v102
	v_cmp_gt_f32_e32 vcc, s37, v103
	s_waitcnt lgkmcnt(2)
	v_mfma_f32_16x16x32_bf16 v[76:79], v[52:55], v[76:79], 0
	v_and_b32_e32 v133, 0xffff0000, v37
	v_cndmask_b32_e32 v103, 0, v253, vcc
	v_fmac_f32_e32 v103, v97, v102
	s_waitcnt lgkmcnt(1)
	v_mfma_f32_16x16x32_bf16 v[108:111], v[52:55], v[108:111], 0
	v_exp_f32_e32 v97, v103
	v_cndmask_b32_e32 v102, 0, v252, vcc
	v_lshlrev_b32_e32 v132, 16, v37
	s_waitcnt lgkmcnt(0)
	v_mfma_f32_16x16x32_bf16 v[52:55], v[52:55], v[112:115], 0
	ds_read_b128 v[112:115], v136 offset:64
	ds_read_b128 v[116:119], v50 offset:34880
	v_ldexp_f32 v97, v97, v102
	s_waitcnt lgkmcnt(0)
	v_mfma_f32_16x16x32_bf16 v[56:59], v[112:115], v[116:119], v[56:59]
	ds_read_b128 v[116:119], v50 offset:39232
	s_waitcnt lgkmcnt(0)
	v_mfma_f32_16x16x32_bf16 v[60:63], v[112:115], v[116:119], v[60:63]
	ds_read_b128 v[116:119], v50 offset:43584
	s_waitcnt lgkmcnt(0)
	v_mfma_f32_16x16x32_bf16 v[64:67], v[112:115], v[116:119], v[64:67]
	ds_read_b128 v[116:119], v50 offset:47936
	s_waitcnt lgkmcnt(0)
	v_mfma_f32_16x16x32_bf16 v[68:71], v[112:115], v[116:119], v[68:71]
	ds_read_b128 v[116:119], v50 offset:52288
	s_waitcnt lgkmcnt(0)
	v_mfma_f32_16x16x32_bf16 v[72:75], v[112:115], v[116:119], v[72:75]
	ds_read_b128 v[116:119], v50 offset:56640
	s_waitcnt lgkmcnt(0)
	v_mfma_f32_16x16x32_bf16 v[76:79], v[112:115], v[116:119], v[76:79]
	ds_read_b128 v[116:119], v50 offset:60992
	s_waitcnt lgkmcnt(0)
	v_mfma_f32_16x16x32_bf16 v[108:111], v[112:115], v[116:119], v[108:111]
	ds_read_b128 v[116:119], v50 offset:65344
	s_waitcnt lgkmcnt(0)
	v_mfma_f32_16x16x32_bf16 v[52:55], v[112:115], v[116:119], v[52:55]
	ds_read_b128 v[112:115], v136 offset:128
	ds_read_b128 v[116:119], v50 offset:34944
	s_waitcnt lgkmcnt(0)
	v_mfma_f32_16x16x32_bf16 v[56:59], v[112:115], v[116:119], v[56:59]
	ds_read_b128 v[116:119], v50 offset:39296
	s_waitcnt lgkmcnt(0)
	v_mfma_f32_16x16x32_bf16 v[60:63], v[112:115], v[116:119], v[60:63]
	ds_read_b128 v[116:119], v50 offset:43648
	s_waitcnt lgkmcnt(0)
	v_mfma_f32_16x16x32_bf16 v[64:67], v[112:115], v[116:119], v[64:67]
	ds_read_b128 v[116:119], v50 offset:48000
	s_waitcnt lgkmcnt(0)
	v_mfma_f32_16x16x32_bf16 v[116:119], v[112:115], v[116:119], v[68:71]
	s_nop 2
	ds_read_b128 v[68:71], v50 offset:52352
	s_waitcnt lgkmcnt(0)
	v_mfma_f32_16x16x32_bf16 v[120:123], v[112:115], v[68:71], v[72:75]
	ds_read_b128 v[68:71], v50 offset:56704
	s_waitcnt lgkmcnt(0)
	v_mfma_f32_16x16x32_bf16 v[124:127], v[112:115], v[68:71], v[76:79]
	ds_read_b128 v[68:71], v50 offset:61056
	s_waitcnt lgkmcnt(0)
	v_mfma_f32_16x16x32_bf16 v[108:111], v[112:115], v[68:71], v[108:111]
	ds_read_b128 v[68:71], v50 offset:65408
	s_waitcnt lgkmcnt(0)
	v_mfma_f32_16x16x32_bf16 v[112:115], v[112:115], v[68:71], v[52:55]
	ds_read_b128 v[128:131], v136 offset:192
	s_nop 1
	ds_read_b128 v[52:55], v50 offset:35008
	s_waitcnt lgkmcnt(0)
	v_mfma_f32_16x16x32_bf16 v[78:81], v[128:131], v[52:55], v[56:59]
	ds_read_b128 v[52:55], v50 offset:39360
	s_waitcnt lgkmcnt(0)
	v_mfma_f32_16x16x32_bf16 v[74:77], v[128:131], v[52:55], v[60:63]
	ds_read_b128 v[52:55], v50 offset:43712
	s_nop 3
	v_mul_f32_e32 v78, v97, v78
	v_cvt_pk_bf16_f32 v97, v78, s0
	s_waitcnt lgkmcnt(0)
	v_mfma_f32_16x16x32_bf16 v[70:73], v[128:131], v[52:55], v[64:67]
	ds_read_b128 v[52:55], v50 offset:48064
	v_mul_lo_u32 v78, v96, s36
	v_add_u32_e32 v102, v107, v78
	s_waitcnt lgkmcnt(0)
	v_mfma_f32_16x16x32_bf16 v[66:69], v[128:131], v[52:55], v[116:119]
	ds_read_b128 v[52:55], v50 offset:52416
	s_nop 1
	v_and_b32_e32 v119, 0xffff0000, v38
	v_lshlrev_b32_e32 v118, 16, v38
	s_waitcnt lgkmcnt(0)
	v_mfma_f32_16x16x32_bf16 v[62:65], v[128:131], v[52:55], v[120:123]
	ds_read_b128 v[52:55], v50 offset:56768
	v_sub_u32_e32 v38, 32, v85
	v_cvt_f32_i32_e32 v38, v38
	s_waitcnt lgkmcnt(0)
; DEVINL void ret_out_phase(CParams& p, const Ctx& cx, int l, const GI& gi) {
;     ...
;       for (int mt = 0; mt < 8; ++mt)
; #pragma unroll
;         for (int j = 0; j < 4; ++j) {
;           const int n = wave * 16 + fq * 4 + j, m = mt * 16 + fr, d = n - m;
;           const float dec = d >= 0 ? exp2f((float)d * lgf) : exp2f((float)(-d) * lgb);
;           *(u16*)(Ab + n * 272 + m * 2) = f2bf(s[mt][j] * dec);
;         }
;     }
;     __syncthreads();
;     f32x4 o[16];
; #pragma unroll
;     for (int et = 0; et < 16; ++et) o[et] = f32x4{0.f, 0.f, 0.f, 0.f};
; #pragma unroll 1
;     for (int part = 0; part < 3; ++part) {
; #pragma unroll
;       for (int i = 0; i < 8; ++i) *(bf16x8*)(Bb + (srow + i * 32) * 272 + ((sch ^ ((srow + i * 32) >> 4)) * 16)) = rb[i];
;       if (part > 0) {
; #pragma unroll
;         for (int i = 0; i < 4; ++i) {
;           const int nl = srow + i * 32;
;           const float fsc = __builtin_amdgcn_exp2f(part == 1 ? (float)(nl + 1) * lgf : (float)(128 - nl) * lgb);
	v_mfma_f32_16x16x32_bf16 v[58:61], v[128:131], v[52:55], v[124:127]
	ds_read_b128 v[52:55], v50 offset:61120
	v_mul_f32_e32 v144, v86, v38
	v_add_u32_e32 v38, 0x61, v85
	s_waitcnt lgkmcnt(0)
	v_mfma_f32_16x16x32_bf16 v[54:57], v[128:131], v[52:55], v[108:111]
	ds_read_b128 v[50:53], v50 offset:65472
	ds_write_b16 v102, v97
	v_or_b32_e32 v97, 1, v96
	v_sub_u32_e32 v102, v97, v82
	v_sub_u32_e32 v103, 0, v102
	v_max_i32_e32 v103, v102, v103
	v_cvt_f32_u32_e32 v103, v103
	v_cmp_gt_i32_e32 vcc, 0, v102
	s_waitcnt lgkmcnt(1)
	v_mfma_f32_16x16x32_bf16 v[50:53], v[128:131], v[50:53], v[112:115]
	v_and_b32_e32 v111, 0xffff0000, v42
	v_cndmask_b32_e32 v102, v84, v86, vcc
	v_mul_f32_e32 v108, v102, v103
	v_cmp_gt_f32_e32 vcc, s37, v108
	v_cvt_f32_i32_e32 v38, v38
	v_and_b32_e32 v127, 0xffff0000, v34
	v_cndmask_b32_e32 v108, 0, v253, vcc
	v_fmac_f32_e32 v108, v102, v103
	v_exp_f32_e32 v102, v108
	v_cndmask_b32_e32 v103, 0, v252, vcc
	v_lshlrev_b32_e32 v126, 16, v34
	v_bitop3_b32 v34, v83, v82, 3 bitop3:0x6c
	v_ldexp_f32 v102, v102, v103
	v_mul_f32_e32 v79, v102, v79
	v_cvt_pk_bf16_f32 v102, v79, s0
	v_add_u32_e32 v79, 0x110, v78
	v_add_u32_e32 v103, v107, v79
	ds_write_b16 v103, v102
	v_or_b32_e32 v102, 2, v96
	v_sub_u32_e32 v103, v102, v82
	v_sub_u32_e32 v108, 0, v103
	v_max_i32_e32 v108, v103, v108
	v_cvt_f32_u32_e32 v108, v108
	v_cmp_gt_i32_e32 vcc, 0, v103
	v_and_b32_e32 v129, 0xffff0000, v35
	v_lshlrev_b32_e32 v128, 16, v35
	v_cndmask_b32_e32 v103, v84, v86, vcc
	v_mul_f32_e32 v109, v103, v108
	v_cmp_gt_f32_e32 vcc, s37, v109
	v_lshlrev_b32_e32 v35, 4, v34
	v_bitop3_b32 v34, v87, v82, 4 bitop3:0x36
	v_cndmask_b32_e32 v109, 0, v253, vcc
	v_fmac_f32_e32 v109, v103, v108
	v_exp_f32_e32 v103, v109
	v_cndmask_b32_e32 v108, 0, v252, vcc
	v_and_b32_e32 v131, 0xffff0000, v36
	v_lshlrev_b32_e32 v130, 16, v36
	v_ldexp_f32 v103, v103, v108
	v_mul_f32_e32 v80, v103, v80
	v_cvt_pk_bf16_f32 v103, v80, s0
	v_add_u32_e32 v80, 0x220, v78
	v_add_u32_e32 v108, v107, v80
	ds_write_b16 v108, v103
	v_or_b32_e32 v103, 3, v96
	v_sub_u32_e32 v108, v103, v82
	v_sub_u32_e32 v109, 0, v108
	v_max_i32_e32 v109, v108, v109
	v_cvt_f32_u32_e32 v109, v109
	v_cmp_gt_i32_e32 vcc, 0, v108
	v_lshlrev_b32_e32 v36, 4, v34
	v_bitop3_b32 v34, v87, v82, 8 bitop3:0x36
	v_cndmask_b32_e32 v108, v84, v86, vcc
	v_mul_f32_e32 v110, v108, v109
	v_cmp_gt_f32_e32 vcc, s37, v110
	v_lshlrev_b32_e32 v37, 4, v34
	v_bitop3_b32 v34, v87, v82, 12 bitop3:0x36
	v_cndmask_b32_e32 v110, 0, v253, vcc
	v_fmac_f32_e32 v110, v108, v109
	v_exp_f32_e32 v108, v110
	v_cndmask_b32_e32 v109, 0, v252, vcc
	v_mul_f32_e32 v145, v84, v38
	v_lshlrev_b32_e32 v38, 4, v34
	v_ldexp_f32 v108, v108, v109
	v_mul_f32_e32 v81, v108, v81
	v_cvt_pk_bf16_f32 v108, v81, s0
	v_add_u32_e32 v81, 0x330, v78
	v_add_u32_e32 v107, v107, v81
	ds_write_b16 v107, v108
	v_sub_u32_e32 v108, v96, v106
	v_sub_u32_e32 v109, 0, v108
	v_max_i32_e32 v109, v108, v109
	v_cvt_f32_u32_e32 v109, v109
	v_cmp_gt_i32_e32 vcc, 0, v108
	v_lshl_add_u32 v107, v106, 1, 0
	v_mov_b32_e32 v34, 0
	v_cndmask_b32_e32 v108, v84, v86, vcc
	v_mul_f32_e32 v110, v108, v109
	v_cmp_gt_f32_e32 vcc, s37, v110
	v_and_b32_e32 v113, 0xffff0000, v43
	v_lshlrev_b32_e32 v112, 16, v43
	v_cndmask_b32_e32 v110, 0, v253, vcc
	v_fmac_f32_e32 v110, v108, v109
	v_exp_f32_e32 v108, v110
	v_cndmask_b32_e32 v109, 0, v252, vcc
	v_lshlrev_b32_e32 v110, 16, v42
	v_sub_u32_e32 v42, 64, v85
	v_ldexp_f32 v108, v108, v109
	v_mul_f32_e32 v74, v108, v74
	v_cvt_pk_bf16_f32 v74, v74, s0
	v_add_u32_e32 v108, v107, v78
	ds_write_b16 v108, v74
	v_sub_u32_e32 v74, v97, v106
	v_sub_u32_e32 v108, 0, v74
	v_max_i32_e32 v108, v74, v108
	v_cvt_f32_u32_e32 v108, v108
	v_cmp_gt_i32_e32 vcc, 0, v74
	v_cvt_f32_i32_e32 v42, v42
	v_and_b32_e32 v115, 0xffff0000, v44
	v_cndmask_b32_e32 v74, v84, v86, vcc
	v_mul_f32_e32 v109, v74, v108
	v_cmp_gt_f32_e32 vcc, s37, v109
	v_mul_f32_e32 v142, v86, v42
	v_add_u32_e32 v42, 0x41, v85
	v_cndmask_b32_e32 v109, 0, v253, vcc
	v_fmac_f32_e32 v109, v74, v108
	v_exp_f32_e32 v74, v109
	v_cndmask_b32_e32 v108, 0, v252, vcc
	v_cvt_f32_i32_e32 v42, v42
	v_and_b32_e32 v109, 0xffff0000, v49
	v_ldexp_f32 v74, v74, v108
	v_mul_f32_e32 v74, v74, v75
	v_cvt_pk_bf16_f32 v74, v74, s0
	v_add_u32_e32 v75, v107, v79
	ds_write_b16 v75, v74
	v_sub_u32_e32 v74, v102, v106
	v_sub_u32_e32 v75, 0, v74
	v_max_i32_e32 v75, v74, v75
	v_cvt_f32_u32_e32 v75, v75
	v_cmp_gt_i32_e32 vcc, 0, v74
	v_lshlrev_b32_e32 v114, 16, v44
	v_and_b32_e32 v117, 0xffff0000, v45
	v_cndmask_b32_e32 v74, v84, v86, vcc
	v_mul_f32_e32 v108, v74, v75
	v_cmp_gt_f32_e32 vcc, s37, v108
	v_lshlrev_b32_e32 v116, 16, v45
	v_mul_f32_e32 v143, v84, v42
	v_cndmask_b32_e32 v108, 0, v253, vcc
	v_fmac_f32_e32 v108, v74, v75
	v_exp_f32_e32 v74, v108
	v_cndmask_b32_e32 v75, 0, v252, vcc
	v_lshlrev_b32_e32 v108, 16, v49
	v_and_b32_e32 v121, 0xffff0000, v39
	v_ldexp_f32 v74, v74, v75
	v_mul_f32_e32 v74, v74, v76
	v_cvt_pk_bf16_f32 v74, v74, s0
	v_add_u32_e32 v75, v107, v80
	ds_write_b16 v75, v74
	v_sub_u32_e32 v74, v103, v106
	v_sub_u32_e32 v75, 0, v74
	v_max_i32_e32 v75, v74, v75
	v_cvt_f32_u32_e32 v75, v75
	v_cmp_gt_i32_e32 vcc, 0, v74
	v_lshlrev_b32_e32 v106, 16, v48
	v_lshlrev_b32_e32 v120, 16, v39
	v_cndmask_b32_e32 v74, v84, v86, vcc
	v_mul_f32_e32 v76, v74, v75
	v_cmp_gt_f32_e32 vcc, s37, v76
	v_and_b32_e32 v123, 0xffff0000, v40
	v_lshlrev_b32_e32 v122, 16, v40
	v_cndmask_b32_e32 v76, 0, v253, vcc
	v_fmac_f32_e32 v76, v74, v75
	v_exp_f32_e32 v74, v76
	v_cndmask_b32_e32 v75, 0, v252, vcc
	v_and_b32_e32 v125, 0xffff0000, v41
	v_lshlrev_b32_e32 v124, 16, v41
	v_ldexp_f32 v74, v74, v75
	v_mul_f32_e32 v74, v74, v77
	v_cvt_pk_bf16_f32 v74, v74, s0
; DEVINL void ret_out_phase(CParams& p, const Ctx& cx, int l, const GI& gi) {
;     ...
;       for (int mt = 0; mt < 8; ++mt)
; #pragma unroll
;         for (int j = 0; j < 4; ++j) {
;           const int n = wave * 16 + fq * 4 + j, m = mt * 16 + fr, d = n - m;
;           const float dec = d >= 0 ? exp2f((float)d * lgf) : exp2f((float)(-d) * lgb);
;           *(u16*)(Ab + n * 272 + m * 2) = f2bf(s[mt][j] * dec);
;         }
	v_add_u32_e32 v75, v107, v81
	ds_write_b16 v75, v74
	v_sub_u32_e32 v75, v96, v105
	v_sub_u32_e32 v76, 0, v75
	v_max_i32_e32 v76, v75, v76
	v_cvt_f32_u32_e32 v76, v76
	v_cmp_gt_i32_e32 vcc, 0, v75
	v_lshl_add_u32 v74, v105, 1, 0
	v_and_b32_e32 v107, 0xffff0000, v48
	v_cndmask_b32_e32 v75, v84, v86, vcc
	v_mul_f32_e32 v77, v75, v76
	v_cmp_gt_f32_e32 vcc, s37, v77
	v_mov_b32_e32 v39, v34
	v_mov_b32_e32 v40, v34
	v_cndmask_b32_e32 v77, 0, v253, vcc
	v_fmac_f32_e32 v77, v75, v76
	v_exp_f32_e32 v75, v77
	v_cndmask_b32_e32 v76, 0, v252, vcc
	v_mov_b32_e32 v41, v34
	v_mov_b32_e32 v42, v34
	v_ldexp_f32 v75, v75, v76
	v_mul_f32_e32 v70, v75, v70
	v_cvt_pk_bf16_f32 v70, v70, s0
	v_add_u32_e32 v75, v74, v78
	ds_write_b16 v75, v70
	v_sub_u32_e32 v70, v97, v105
	v_sub_u32_e32 v75, 0, v70
	v_max_i32_e32 v75, v70, v75
	v_cvt_f32_u32_e32 v75, v75
	v_cmp_gt_i32_e32 vcc, 0, v70
	v_mov_b32_e32 v43, v34
	v_mov_b32_e32 v44, v34
	v_cndmask_b32_e32 v70, v84, v86, vcc
	v_mul_f32_e32 v76, v70, v75
	v_cmp_gt_f32_e32 vcc, s37, v76
	v_mov_b32_e32 v45, v34
	v_mov_b32_e32 v77, v34
	v_cndmask_b32_e32 v76, 0, v253, vcc
	v_fmac_f32_e32 v76, v70, v75
	v_exp_f32_e32 v70, v76
	v_cndmask_b32_e32 v75, 0, v252, vcc
	v_mov_b32_e32 v76, v34
	v_mov_b32_e32 v83, v34
	v_ldexp_f32 v70, v70, v75
	v_mul_f32_e32 v70, v70, v71
	v_cvt_pk_bf16_f32 v70, v70, s0
	v_add_u32_e32 v71, v74, v79
	ds_write_b16 v71, v70
	v_sub_u32_e32 v70, v102, v105
	v_sub_u32_e32 v71, 0, v70
	v_max_i32_e32 v71, v70, v71
	v_cvt_f32_u32_e32 v71, v71
	v_cmp_gt_i32_e32 vcc, 0, v70
	v_mov_b32_e32 v48, v34
	v_mov_b32_e32 v49, v34
	v_cndmask_b32_e32 v70, v84, v86, vcc
	v_mul_f32_e32 v75, v70, v71
	v_cmp_gt_f32_e32 vcc, s37, v75
	v_mov_b32_e32 v87, v34
	s_nop 0
	v_cndmask_b32_e32 v75, 0, v253, vcc
	v_fmac_f32_e32 v75, v70, v71
	v_exp_f32_e32 v70, v75
	v_cndmask_b32_e32 v71, 0, v252, vcc
	v_mov_b32_e32 v75, v34
	v_ldexp_f32 v70, v70, v71
	v_mul_f32_e32 v70, v70, v72
	v_cvt_pk_bf16_f32 v70, v70, s0
	v_add_u32_e32 v71, v74, v80
	ds_write_b16 v71, v70
	v_sub_u32_e32 v70, v103, v105
	v_sub_u32_e32 v71, 0, v70
	v_max_i32_e32 v71, v70, v71
	v_cvt_f32_u32_e32 v71, v71
	v_cmp_gt_i32_e32 vcc, 0, v70
	v_and_b32_e32 v105, 0xffff0000, v47
	s_nop 0
	v_cndmask_b32_e32 v70, v84, v86, vcc
	v_mul_f32_e32 v72, v70, v71
	v_cmp_gt_f32_e32 vcc, s37, v72
	s_nop 1
	v_cndmask_b32_e32 v72, 0, v253, vcc
	v_fmac_f32_e32 v72, v70, v71
	v_exp_f32_e32 v70, v72
	v_cndmask_b32_e32 v71, 0, v252, vcc
	v_ldexp_f32 v70, v70, v71
	v_mul_f32_e32 v70, v70, v73
	v_cvt_pk_bf16_f32 v70, v70, s0
	v_add_u32_e32 v71, v74, v81
	ds_write_b16 v71, v70
	v_sub_u32_e32 v71, v96, v104
	v_sub_u32_e32 v72, 0, v71
	v_max_i32_e32 v72, v71, v72
	v_cvt_f32_u32_e32 v72, v72
	v_cmp_gt_i32_e32 vcc, 0, v71
	v_lshl_add_u32 v70, v104, 1, 0
	v_mov_b32_e32 v74, v34
	v_cndmask_b32_e32 v71, v84, v86, vcc
	v_mul_f32_e32 v73, v71, v72
	v_cmp_gt_f32_e32 vcc, s37, v73
	s_nop 1
	v_cndmask_b32_e32 v73, 0, v253, vcc
	v_fmac_f32_e32 v73, v71, v72
	v_exp_f32_e32 v71, v73
	v_cndmask_b32_e32 v72, 0, v252, vcc
	v_mov_b32_e32 v73, v34
	v_ldexp_f32 v71, v71, v72
	v_mul_f32_e32 v66, v71, v66
	v_cvt_pk_bf16_f32 v66, v66, s0
	v_add_u32_e32 v71, v70, v78
	ds_write_b16 v71, v66
	v_sub_u32_e32 v66, v97, v104
	v_sub_u32_e32 v71, 0, v66
	v_max_i32_e32 v71, v66, v71
	v_cvt_f32_u32_e32 v71, v71
	v_cmp_gt_i32_e32 vcc, 0, v66
	s_nop 1
	v_cndmask_b32_e32 v66, v84, v86, vcc
	v_mul_f32_e32 v72, v66, v71
	v_cmp_gt_f32_e32 vcc, s37, v72
	s_nop 1
	v_cndmask_b32_e32 v72, 0, v253, vcc
	v_fmac_f32_e32 v72, v66, v71
	v_exp_f32_e32 v66, v72
	v_cndmask_b32_e32 v71, 0, v252, vcc
	v_mov_b32_e32 v72, v34
	v_ldexp_f32 v66, v66, v71
	v_mul_f32_e32 v66, v66, v67
	v_cvt_pk_bf16_f32 v66, v66, s0
	v_add_u32_e32 v67, v70, v79
	ds_write_b16 v67, v66
	v_sub_u32_e32 v66, v102, v104
	v_sub_u32_e32 v67, 0, v66
	v_max_i32_e32 v67, v66, v67
	v_cvt_f32_u32_e32 v67, v67
	v_cmp_gt_i32_e32 vcc, 0, v66
	s_nop 1
	v_cndmask_b32_e32 v66, v84, v86, vcc
	v_mul_f32_e32 v71, v66, v67
	v_cmp_gt_f32_e32 vcc, s37, v71
	s_nop 1
	v_cndmask_b32_e32 v71, 0, v253, vcc
	v_fmac_f32_e32 v71, v66, v67
	v_exp_f32_e32 v66, v71
	v_cndmask_b32_e32 v67, 0, v252, vcc
	v_mov_b32_e32 v71, v34
	v_ldexp_f32 v66, v66, v67
	v_mul_f32_e32 v66, v66, v68
	v_cvt_pk_bf16_f32 v66, v66, s0
	v_add_u32_e32 v67, v70, v80
	ds_write_b16 v67, v66
	v_sub_u32_e32 v66, v103, v104
	v_sub_u32_e32 v67, 0, v66
	v_max_i32_e32 v67, v66, v67
	v_cvt_f32_u32_e32 v67, v67
	v_cmp_gt_i32_e32 vcc, 0, v66
	v_lshlrev_b32_e32 v104, 16, v47
	v_mov_b32_e32 v47, v34
	v_cndmask_b32_e32 v66, v84, v86, vcc
	v_mul_f32_e32 v68, v66, v67
	v_cmp_gt_f32_e32 vcc, s37, v68
	s_nop 1
	v_cndmask_b32_e32 v68, 0, v253, vcc
	v_fmac_f32_e32 v68, v66, v67
	v_exp_f32_e32 v66, v68
	v_cndmask_b32_e32 v67, 0, v252, vcc
	v_ldexp_f32 v66, v66, v67
	v_mul_f32_e32 v66, v66, v69
	v_cvt_pk_bf16_f32 v66, v66, s0
	v_add_u32_e32 v67, v70, v81
	ds_write_b16 v67, v66
	v_sub_u32_e32 v67, v96, v95
	v_sub_u32_e32 v68, 0, v67
	v_max_i32_e32 v68, v67, v68
	v_cvt_f32_u32_e32 v68, v68
	v_cmp_gt_i32_e32 vcc, 0, v67
	v_lshl_add_u32 v66, v95, 1, 0
	v_mov_b32_e32 v70, v34
	v_cndmask_b32_e32 v67, v84, v86, vcc
	v_mul_f32_e32 v69, v67, v68
	v_cmp_gt_f32_e32 vcc, s37, v69
	s_nop 1
	v_cndmask_b32_e32 v69, 0, v253, vcc
	v_fmac_f32_e32 v69, v67, v68
	v_exp_f32_e32 v67, v69
	v_cndmask_b32_e32 v68, 0, v252, vcc
	v_mov_b32_e32 v69, v34
	v_ldexp_f32 v67, v67, v68
	v_mul_f32_e32 v62, v67, v62
	v_cvt_pk_bf16_f32 v62, v62, s0
	v_add_u32_e32 v67, v66, v78
	ds_write_b16 v67, v62
	v_sub_u32_e32 v62, v97, v95
	v_sub_u32_e32 v67, 0, v62
	v_max_i32_e32 v67, v62, v67
	v_cvt_f32_u32_e32 v67, v67
	v_cmp_gt_i32_e32 vcc, 0, v62
	s_nop 1
	v_cndmask_b32_e32 v62, v84, v86, vcc
; DEVINL void ret_out_phase(CParams& p, const Ctx& cx, int l, const GI& gi) {
;     ...
;       for (int mt = 0; mt < 8; ++mt)
; #pragma unroll
;         for (int j = 0; j < 4; ++j) {
;           const int n = wave * 16 + fq * 4 + j, m = mt * 16 + fr, d = n - m;
;           const float dec = d >= 0 ? exp2f((float)d * lgf) : exp2f((float)(-d) * lgb);
;           *(u16*)(Ab + n * 272 + m * 2) = f2bf(s[mt][j] * dec);
;         }
	v_mul_f32_e32 v68, v62, v67
	v_cmp_gt_f32_e32 vcc, s37, v68
	s_nop 1
	v_cndmask_b32_e32 v68, 0, v253, vcc
	v_fmac_f32_e32 v68, v62, v67
	v_exp_f32_e32 v62, v68
	v_cndmask_b32_e32 v67, 0, v252, vcc
	v_mov_b32_e32 v68, v34
	v_ldexp_f32 v62, v62, v67
	v_mul_f32_e32 v62, v62, v63
	v_cvt_pk_bf16_f32 v62, v62, s0
	v_add_u32_e32 v63, v66, v79
	ds_write_b16 v63, v62
	v_sub_u32_e32 v62, v102, v95
	v_sub_u32_e32 v63, 0, v62
	v_max_i32_e32 v63, v62, v63
	v_cvt_f32_u32_e32 v63, v63
	v_cmp_gt_i32_e32 vcc, 0, v62
	s_nop 1
	v_cndmask_b32_e32 v62, v84, v86, vcc
	v_mul_f32_e32 v67, v62, v63
	v_cmp_gt_f32_e32 vcc, s37, v67
	s_nop 1
	v_cndmask_b32_e32 v67, 0, v253, vcc
	v_fmac_f32_e32 v67, v62, v63
	v_exp_f32_e32 v62, v67
	v_cndmask_b32_e32 v63, 0, v252, vcc
	v_mov_b32_e32 v67, v34
	v_ldexp_f32 v62, v62, v63
	v_mul_f32_e32 v62, v62, v64
	v_cvt_pk_bf16_f32 v62, v62, s0
	v_add_u32_e32 v63, v66, v80
	ds_write_b16 v63, v62
	v_sub_u32_e32 v62, v103, v95
	v_sub_u32_e32 v63, 0, v62
	v_max_i32_e32 v63, v62, v63
	v_cvt_f32_u32_e32 v63, v63
	v_cmp_gt_i32_e32 vcc, 0, v62
	v_mov_b32_e32 v95, v34
	s_nop 0
	v_cndmask_b32_e32 v62, v84, v86, vcc
	v_mul_f32_e32 v64, v62, v63
	v_cmp_gt_f32_e32 vcc, s37, v64
	s_nop 1
	v_cndmask_b32_e32 v64, 0, v253, vcc
	v_fmac_f32_e32 v64, v62, v63
	v_exp_f32_e32 v62, v64
	v_cndmask_b32_e32 v63, 0, v252, vcc
	v_ldexp_f32 v62, v62, v63
	v_mul_f32_e32 v62, v62, v65
	v_cvt_pk_bf16_f32 v62, v62, s0
	v_add_u32_e32 v63, v66, v81
	ds_write_b16 v63, v62
	v_sub_u32_e32 v63, v96, v94
	v_sub_u32_e32 v64, 0, v63
	v_max_i32_e32 v64, v63, v64
	v_cvt_f32_u32_e32 v64, v64
	v_cmp_gt_i32_e32 vcc, 0, v63
	v_lshl_add_u32 v62, v94, 1, 0
	v_mov_b32_e32 v66, v34
	v_cndmask_b32_e32 v63, v84, v86, vcc
	v_mul_f32_e32 v65, v63, v64
	v_cmp_gt_f32_e32 vcc, s37, v65
	s_nop 1
	v_cndmask_b32_e32 v65, 0, v253, vcc
	v_fmac_f32_e32 v65, v63, v64
	v_exp_f32_e32 v63, v65
	v_cndmask_b32_e32 v64, 0, v252, vcc
	v_mov_b32_e32 v65, v34
	v_ldexp_f32 v63, v63, v64
	v_mul_f32_e32 v58, v63, v58
	v_cvt_pk_bf16_f32 v58, v58, s0
	v_add_u32_e32 v63, v62, v78
	ds_write_b16 v63, v58
	v_sub_u32_e32 v58, v97, v94
	v_sub_u32_e32 v63, 0, v58
	v_max_i32_e32 v63, v58, v63
	v_cvt_f32_u32_e32 v63, v63
	v_cmp_gt_i32_e32 vcc, 0, v58
	s_nop 1
	v_cndmask_b32_e32 v58, v84, v86, vcc
	v_mul_f32_e32 v64, v58, v63
	v_cmp_gt_f32_e32 vcc, s37, v64
	s_nop 1
	v_cndmask_b32_e32 v64, 0, v253, vcc
	v_fmac_f32_e32 v64, v58, v63
	v_exp_f32_e32 v58, v64
	v_cndmask_b32_e32 v63, 0, v252, vcc
	v_mov_b32_e32 v64, v34
	v_ldexp_f32 v58, v58, v63
	v_mul_f32_e32 v58, v58, v59
	v_cvt_pk_bf16_f32 v58, v58, s0
	v_add_u32_e32 v59, v62, v79
	ds_write_b16 v59, v58
	v_sub_u32_e32 v58, v102, v94
	v_sub_u32_e32 v59, 0, v58
	v_max_i32_e32 v59, v58, v59
	v_cvt_f32_u32_e32 v59, v59
	v_cmp_gt_i32_e32 vcc, 0, v58
	s_nop 1
	v_cndmask_b32_e32 v58, v84, v86, vcc
	v_mul_f32_e32 v63, v58, v59
	v_cmp_gt_f32_e32 vcc, s37, v63
	s_nop 1
	v_cndmask_b32_e32 v63, 0, v253, vcc
	v_fmac_f32_e32 v63, v58, v59
	v_exp_f32_e32 v58, v63
	v_cndmask_b32_e32 v59, 0, v252, vcc
	v_mov_b32_e32 v63, v34
	v_ldexp_f32 v58, v58, v59
	v_mul_f32_e32 v58, v58, v60
	v_cvt_pk_bf16_f32 v58, v58, s0
	v_add_u32_e32 v59, v62, v80
	ds_write_b16 v59, v58
	v_sub_u32_e32 v58, v103, v94
	v_sub_u32_e32 v59, 0, v58
	v_max_i32_e32 v59, v58, v59
	v_cvt_f32_u32_e32 v59, v59
	v_cmp_gt_i32_e32 vcc, 0, v58
	v_mov_b32_e32 v94, v34
	s_nop 0
	v_cndmask_b32_e32 v58, v84, v86, vcc
	v_mul_f32_e32 v60, v58, v59
	v_cmp_gt_f32_e32 vcc, s37, v60
	s_nop 1
	v_cndmask_b32_e32 v60, 0, v253, vcc
	v_fmac_f32_e32 v60, v58, v59
	v_exp_f32_e32 v58, v60
	v_cndmask_b32_e32 v59, 0, v252, vcc
	v_ldexp_f32 v58, v58, v59
	v_mul_f32_e32 v58, v58, v61
	v_cvt_pk_bf16_f32 v58, v58, s0
	v_add_u32_e32 v59, v62, v81
	ds_write_b16 v59, v58
	v_sub_u32_e32 v59, v96, v93
	v_sub_u32_e32 v60, 0, v59
	v_max_i32_e32 v60, v59, v60
	v_cvt_f32_u32_e32 v60, v60
	v_cmp_gt_i32_e32 vcc, 0, v59
	v_lshl_add_u32 v58, v93, 1, 0
	v_mov_b32_e32 v62, v34
	v_cndmask_b32_e32 v59, v84, v86, vcc
	v_mul_f32_e32 v61, v59, v60
	v_cmp_gt_f32_e32 vcc, s37, v61
	s_nop 1
	v_cndmask_b32_e32 v61, 0, v253, vcc
	v_fmac_f32_e32 v61, v59, v60
	v_exp_f32_e32 v59, v61
	v_cndmask_b32_e32 v60, 0, v252, vcc
	v_sub_u32_e32 v61, 0x80, v85
	v_cvt_f32_i32_e32 v61, v61
	v_ldexp_f32 v59, v59, v60
	v_mul_f32_e32 v54, v59, v54
	v_cvt_pk_bf16_f32 v54, v54, s0
	v_add_u32_e32 v59, v58, v78
	ds_write_b16 v59, v54
	v_sub_u32_e32 v54, v97, v93
	v_sub_u32_e32 v59, 0, v54
	v_max_i32_e32 v59, v54, v59
	v_cvt_f32_u32_e32 v59, v59
	v_cmp_gt_i32_e32 vcc, 0, v54
	v_mul_f32_e32 v138, v86, v61
	v_add_u32_e32 v61, 1, v85
	v_cndmask_b32_e32 v54, v84, v86, vcc
	v_mul_f32_e32 v60, v54, v59
	v_cmp_gt_f32_e32 vcc, s37, v60
	v_cvt_f32_i32_e32 v61, v61
	v_mul_f32_e32 v139, v84, v61
	v_cndmask_b32_e32 v60, 0, v253, vcc
	v_fmac_f32_e32 v60, v54, v59
	v_exp_f32_e32 v54, v60
	v_cndmask_b32_e32 v59, 0, v252, vcc
	v_add_u32_e32 v60, 0xe0, v85
	v_bitop3_b32 v60, v60, v98, -16 bitop3:0x6c
	v_ldexp_f32 v54, v54, v59
	v_mul_f32_e32 v54, v54, v55
	v_cvt_pk_bf16_f32 v54, v54, s0
	v_add_u32_e32 v55, v58, v79
	ds_write_b16 v55, v54
	v_sub_u32_e32 v54, v102, v93
; DEVINL void ret_out_phase(CParams& p, const Ctx& cx, int l, const GI& gi) {
;     ...
;       for (int mt = 0; mt < 8; ++mt)
; #pragma unroll
;         for (int j = 0; j < 4; ++j) {
;           const int n = wave * 16 + fq * 4 + j, m = mt * 16 + fr, d = n - m;
;           const float dec = d >= 0 ? exp2f((float)d * lgf) : exp2f((float)(-d) * lgb);
;           *(u16*)(Ab + n * 272 + m * 2) = f2bf(s[mt][j] * dec);
;         }
;     }
;     __syncthreads();
;     f32x4 o[16];
; #pragma unroll
;     for (int et = 0; et < 16; ++et) o[et] = f32x4{0.f, 0.f, 0.f, 0.f};
; #pragma unroll 1
;     for (int part = 0; part < 3; ++part) {
; #pragma unroll
;       for (int i = 0; i < 8; ++i) *(bf16x8*)(Bb + (srow + i * 32) * 272 + ((sch ^ ((srow + i * 32) >> 4)) * 16)) = rb[i];
	v_sub_u32_e32 v55, 0, v54
	v_max_i32_e32 v55, v54, v55
	v_cvt_f32_u32_e32 v55, v55
	v_cmp_gt_i32_e32 vcc, 0, v54
	v_mov_b32_e32 v61, v34
	s_nop 0
	v_cndmask_b32_e32 v54, v84, v86, vcc
	v_mul_f32_e32 v59, v54, v55
	v_cmp_gt_f32_e32 vcc, s37, v59
	s_nop 1
	v_cndmask_b32_e32 v59, 0, v253, vcc
	v_fmac_f32_e32 v59, v54, v55
	v_exp_f32_e32 v54, v59
	v_cndmask_b32_e32 v55, 0, v252, vcc
	v_add_u32_e32 v59, 0xc0, v85
	v_bitop3_b32 v59, v59, v98, -16 bitop3:0x6c
	v_ldexp_f32 v54, v54, v55
	v_mul_f32_e32 v54, v54, v56
	v_cvt_pk_bf16_f32 v54, v54, s0
	v_add_u32_e32 v55, v58, v80
	ds_write_b16 v55, v54
	v_sub_u32_e32 v54, v103, v93
	v_sub_u32_e32 v55, 0, v54
	v_max_i32_e32 v55, v54, v55
	v_cvt_f32_u32_e32 v55, v55
	v_cmp_gt_i32_e32 vcc, 0, v54
	v_mov_b32_e32 v93, v34
	s_nop 0
	v_cndmask_b32_e32 v54, v84, v86, vcc
	v_mul_f32_e32 v56, v54, v55
	v_cmp_gt_f32_e32 vcc, s37, v56
	s_nop 1
	v_cndmask_b32_e32 v56, 0, v253, vcc
	v_fmac_f32_e32 v56, v54, v55
	v_exp_f32_e32 v54, v56
	v_cndmask_b32_e32 v55, 0, v252, vcc
	v_ldexp_f32 v54, v54, v55
	v_mul_f32_e32 v54, v54, v57
	v_cvt_pk_bf16_f32 v54, v54, s0
	v_add_u32_e32 v55, v58, v81
	ds_write_b16 v55, v54
	v_sub_u32_e32 v55, v96, v92
	v_sub_u32_e32 v56, 0, v55
	v_max_i32_e32 v56, v55, v56
	v_cvt_f32_u32_e32 v56, v56
	v_cmp_gt_i32_e32 vcc, 0, v55
	v_lshl_add_u32 v54, v92, 1, 0
	v_add_u32_e32 v58, 0xa0, v85
	v_cndmask_b32_e32 v55, v84, v86, vcc
	v_mul_f32_e32 v57, v55, v56
	v_cmp_gt_f32_e32 vcc, s37, v57
	v_bitop3_b32 v58, v58, v98, -16 bitop3:0x6c
	v_mov_b32_e32 v96, v34
	v_cndmask_b32_e32 v57, 0, v253, vcc
	v_fmac_f32_e32 v57, v55, v56
	v_exp_f32_e32 v55, v57
	v_cndmask_b32_e32 v56, 0, v252, vcc
	v_ldexp_f32 v55, v55, v56
	v_mul_f32_e32 v50, v55, v50
	v_cvt_pk_bf16_f32 v50, v50, s0
	v_add_u32_e32 v55, v54, v78
	ds_write_b16 v55, v50
	v_sub_u32_e32 v50, v97, v92
	v_sub_u32_e32 v55, 0, v50
	v_max_i32_e32 v55, v50, v55
	v_cvt_f32_u32_e32 v55, v55
	v_cmp_gt_i32_e32 vcc, 0, v50
	v_mov_b32_e32 v78, v34
	v_mov_b32_e32 v97, v34
	v_cndmask_b32_e32 v50, v84, v86, vcc
	v_mul_f32_e32 v56, v50, v55
	v_cmp_gt_f32_e32 vcc, s37, v56
	s_nop 1
	v_cndmask_b32_e32 v56, 0, v253, vcc
	v_fmac_f32_e32 v56, v50, v55
	v_exp_f32_e32 v50, v56
	v_cndmask_b32_e32 v55, 0, v252, vcc
	v_add_u32_e32 v56, 0x80, v85
	v_bitop3_b32 v56, v56, v98, -16 bitop3:0x6c
	v_ldexp_f32 v50, v50, v55
	v_mul_f32_e32 v50, v50, v51
	v_cvt_pk_bf16_f32 v50, v50, s0
	v_add_u32_e32 v51, v54, v79
	ds_write_b16 v51, v50
	v_sub_u32_e32 v50, v102, v92
	v_sub_u32_e32 v51, 0, v50
	v_max_i32_e32 v51, v50, v51
	v_cvt_f32_u32_e32 v51, v51
	v_cmp_gt_i32_e32 vcc, 0, v50
	v_lshlrev_b32_e32 v102, 16, v46
	v_mov_b32_e32 v79, v34
	v_cndmask_b32_e32 v50, v84, v86, vcc
	v_mul_f32_e32 v55, v50, v51
	v_cmp_gt_f32_e32 vcc, s37, v55
	s_nop 1
	v_cndmask_b32_e32 v55, 0, v253, vcc
	v_fmac_f32_e32 v55, v50, v51
	v_exp_f32_e32 v50, v55
	v_cndmask_b32_e32 v51, 0, v252, vcc
	v_bitop3_b32 v55, v91, v98, -16 bitop3:0x6c
	v_mov_b32_e32 v91, v34
	v_ldexp_f32 v50, v50, v51
	v_mul_f32_e32 v50, v50, v52
	v_cvt_pk_bf16_f32 v50, v50, s0
	v_add_u32_e32 v51, v54, v80
	ds_write_b16 v51, v50
	v_sub_u32_e32 v50, v103, v92
	v_sub_u32_e32 v51, 0, v50
	v_max_i32_e32 v51, v50, v51
	v_cvt_f32_u32_e32 v51, v51
	v_cmp_gt_i32_e32 vcc, 0, v50
	v_and_b32_e32 v103, 0xffff0000, v46
	v_sub_u32_e32 v46, 0x60, v85
	v_cndmask_b32_e32 v50, v84, v86, vcc
	v_mul_f32_e32 v52, v50, v51
	v_cmp_gt_f32_e32 vcc, s37, v52
	v_cvt_f32_i32_e32 v46, v46
	v_mov_b32_e32 v80, v34
	v_cndmask_b32_e32 v52, 0, v253, vcc
	v_fmac_f32_e32 v52, v50, v51
	v_exp_f32_e32 v50, v52
	v_cndmask_b32_e32 v51, 0, v252, vcc
	v_mul_f32_e32 v140, v86, v46
	v_add_u32_e32 v46, 33, v85
	v_ldexp_f32 v50, v50, v51
	v_mul_f32_e32 v50, v50, v53
	v_cvt_f32_i32_e32 v46, v46
	v_cvt_pk_bf16_f32 v50, v50, s0
	v_add_u32_e32 v51, v54, v81
	ds_write_b16 v51, v50
	v_add_u32_e32 v51, 0, v88
	v_mad_u32_u24 v50, v82, s18, 0
	v_bitop3_b32 v52, v85, v98, -16 bitop3:0x6c
	v_bitop3_b32 v53, v89, v98, -16 bitop3:0x6c
	v_bitop3_b32 v54, v90, v98, -16 bitop3:0x6c
	v_add_u32_e32 v57, 0x8800, v51
	v_mul_f32_e32 v141, v84, v46
	v_add_u32_e32 v146, v51, v52
	v_add_u32_e32 v147, v51, v53
	v_add_u32_e32 v148, v51, v54
	v_add_u32_e32 v149, v51, v55
	v_add_u32_e32 v151, v57, v56
	v_add_u32_e32 v152, v57, v58
	v_add_u32_e32 v153, v57, v59
	v_add_u32_e32 v154, v57, v60
	v_add_u32_e32 v155, v50, v35
	v_add_u32_e32 v156, v50, v36
	v_add_u32_e32 v157, v50, v37
	v_add_u32_e32 v158, v50, v38
	v_mov_b32_e32 v35, v34
	v_mov_b32_e32 v36, v34
	v_mov_b32_e32 v37, v34
	v_mov_b32_e32 v38, v34
	v_mov_b32_e32 v50, v34
	v_mov_b32_e32 v51, v34
	v_mov_b32_e32 v52, v34
	v_mov_b32_e32 v53, v34
	v_mov_b32_e32 v58, v34
	v_mov_b32_e32 v59, v34
	v_mov_b32_e32 v60, v34
	v_mov_b32_e32 v82, v34
	v_mov_b32_e32 v84, v34
	v_mov_b32_e32 v85, v34
	v_mov_b32_e32 v46, v34
	v_mov_b32_e32 v54, v34
	v_mov_b32_e32 v55, v34
	v_mov_b32_e32 v56, v34
	v_mov_b32_e32 v57, v34
	v_mov_b32_e32 v81, v34
	v_mov_b32_e32 v86, v34
	v_mov_b32_e32 v88, v34
	v_mov_b32_e32 v89, v34
	v_mov_b32_e32 v90, v34
	v_mov_b32_e32 v92, v34
	s_waitcnt lgkmcnt(0)
	s_barrier
	s_branch .LBB0_271

; DEVINL void ret_state_phase(CParams& p, const Ctx& cx, int l, const GI& gi) {
;     ...
;   for (int it = cx.bid; it < nitems; it += cx.nb) {
;     const int es = it & 3, dir = (it >> 2) & 1, h = (it >> 3) & 3, sq = it >> 5;
;     const float gC = exp2f(128.f * p.lg2[(l * 2 + dir) * 4 + h]);
;     const u16* kT = dir == 0 ? p.kTf : p.kTb;
;     u16* S = dir == 0 ? p.Sf : p.Sb;
;     f32x4 acc[2][2];
; #pragma unroll
;     for (int et = 0; et < 2; ++et)
; #pragma unroll
;       for (int n = 0; n < 2; ++n) acc[et][n] = f32x4{0.f, 0.f, 0.f, 0.f};
;     struct Regs { bf16x8 v[2]; bf16x8 k[4]; };
;     auto chof = [&](int cc) -> size_t { const int c = dir == 0 ? cc : nchunk - 1 - cc; return (size_t)(sq * nchunk + c) * 4 + h; };
;     auto gload = [&](int cc, Regs& r) {
;       const size_t ch = chof(cc);
;       const u16* vg = p.vT + (ch * 256 + es * 64 + srow) * 128 + sch * 8;
;       const u16* kg = kT + (ch * 128 + srow) * 128 + sch * 8;
; #pragma unroll
;       for (int i = 0; i < 2; ++i) r.v[i] = *(const bf16x8*)(vg + i * 32 * 128);
; #pragma unroll
;       for (int i = 0; i < 4; ++i) r.k[i] = *(const bf16x8*)(kg + i * 32 * 128);
;     };
;     auto lstore = [&](int buf, const Regs& r) {
;       char* Vb = (char*)shm + buf * 52224;
;       char* Kb = Vb + 17408;
; #pragma unroll
;       for (int i = 0; i < 2; ++i) *(bf16x8*)(Vb + (srow + i * 32) * 272 + sch * 16) = r.v[i];
; #pragma unroll
;       for (int i = 0; i < 4; ++i) *(bf16x8*)(Kb + (srow + i * 32) * 272 + sch * 16) = r.k[i];
;     };
;     auto compute = [&](int cc, int buf) {
;       u16* Sd = S + chof(cc) * 32768;
; #pragma unroll
;       for (int et = 0; et < 2; ++et)
; #pragma unroll
;         for (int j = 0; j < 4; ++j)
;           *(unsigned*)(Sd + (es * 64 + (ep * 2 + et) * 16 + fq * 4 + j) * 128 + dq * 32 + fr * 2) = pack2(acc[et][0][j], acc[et][1][j]);
; #pragma unroll
;       for (int et = 0; et < 2; ++et)
; #pragma unroll
;         for (int n = 0; n < 2; ++n) acc[et][n] *= gC;
;       const char* Vb = (const char*)shm + buf * 52224;
;       const char* Kb = Vb + 17408;
; #pragma unroll
;       for (int ks = 0; ks < 4; ++ks) {
;         bf16x8 a[2], bb[2];
; #pragma unroll
;         for (int et = 0; et < 2; ++et) a[et] = *(const bf16x8*)(Vb + ((ep * 2 + et) * 16 + fr) * 272 + ks * 64 + fq * 16);
; #pragma unroll
.LBB0_281:
	s_add_i32 s18, s18, s33
	s_cmp_ge_i32 s18, s12
	s_cbranch_scc1 .LBB0_290
.LBB0_282:
	v_readfirstlane_b32 s100, v234
	s_nop 3
	s_lshr_b32 s100, s100, 6
	s_cmp_ge_u32 s100, 4
	s_cbranch_scc1 .Lprio_282_done
	s_setprio 1
.Lprio_282_done:
	s_bfe_u32 s8, s18, 0x10002
	s_lshl_b32 s6, s8, 2
	s_bfe_u32 s96, s18, 0x20003
	s_or_b32 s6, s6, s14
	s_or_b32 s6, s6, s96
	s_ashr_i32 s7, s6, 31
	s_bfe_i32 s20, s18, 0x10002
	s_lshl_b64 s[6:7], s[6:7], 2
	s_add_u32 s6, s4, s6
	s_addc_u32 s7, s5, s7
	s_cmp_eq_u32 s8, 0
	global_load_dword v0, v1, s[6:7]
	s_cselect_b64 s[6:7], -1, 0
	s_and_b64 s[8:9], s[6:7], exec
	s_movk_i32 s8, 0x198
	s_cselect_b32 s8, s8, 0x1a0
	s_movk_i32 s9, 0x1e0
	s_cselect_b32 s19, s9, 0x1e8
	s_cselect_b32 s23, 1, s16
	s_add_u32 s8, s88, s8
	s_addc_u32 s9, s89, 0
	s_load_dwordx2 s[10:11], s[8:9], 0x0
	s_add_u32 s8, s88, s19
	s_addc_u32 s9, s89, 0
	s_ashr_i32 s19, s18, 5
	s_mul_i32 s19, s19, s13
	s_and_b32 s20, s20, s15
	s_add_i32 s20, s20, s19
	s_ashr_i32 s21, s20, 31
	s_and_b32 s22, s18, 3
	s_lshl_b64 s[20:21], s[20:21], 2
	s_or_b32 s20, s20, s96
	s_lshl_b32 s26, s22, 6
	s_mov_b32 s27, s97
	v_lshl_add_u64 v[2:3], s[26:27], 0, v[66:67]
	s_lshl_b64 s[26:27], s[20:21], 16
	s_lshl_b64 s[20:21], s[20:21], 15
	v_lshlrev_b64 v[52:53], 8, v[2:3]
	v_lshl_add_u64 v[2:3], v[68:69], 0, s[26:27]
	s_waitcnt lgkmcnt(0)
	s_add_u32 s20, s10, s20
	v_lshl_add_u64 v[6:7], v[2:3], 0, v[52:53]
	s_addc_u32 s21, s11, s21
	s_movk_i32 s25, 0x2000
	v_lshl_add_u64 v[10:11], s[20:21], 0, v[70:71]
	global_load_dwordx4 v[2:5], v[6:7], off
	v_add_co_u32_e32 v6, vcc, s25, v6
	v_mov_b32_e32 v73, v1
	s_nop 0
	v_addc_co_u32_e32 v7, vcc, 0, v7, vcc
	v_lshl_add_u64 v[22:23], v[10:11], 0, v[72:73]
	v_add_co_u32_e32 v14, vcc, s25, v22
	global_load_dwordx4 v[6:9], v[6:7], off
	s_nop 0
	v_addc_co_u32_e32 v15, vcc, 0, v23, vcc
	v_add_co_u32_e32 v18, vcc, s30, v22
	global_load_dwordx4 v[10:13], v[22:23], off
	s_nop 0
	v_addc_co_u32_e32 v19, vcc, 0, v23, vcc
	global_load_dwordx4 v[14:17], v[14:15], off
	v_add_co_u32_e32 v22, vcc, s31, v22
	global_load_dwordx4 v[18:21], v[18:19], off
	s_nop 0
	v_addc_co_u32_e32 v23, vcc, 0, v23, vcc
	global_load_dwordx4 v[22:25], v[22:23], off
	s_add_i32 s20, s23, s19
	s_ashr_i32 s21, s20, 31
	s_lshl_b64 s[20:21], s[20:21], 2
	s_or_b32 s20, s20, s96
	s_lshl_b64 s[26:27], s[20:21], 16
	s_lshl_b64 s[20:21], s[20:21], 15
	s_waitcnt vmcnt(0)
	v_lshl_add_u64 v[26:27], v[68:69], 0, s[26:27]
	s_add_u32 s20, s10, s20
	s_load_dwordx2 s[8:9], s[8:9], 0x0
	s_waitcnt vmcnt(0) lgkmcnt(0)
	s_barrier
	v_lshl_add_u64 v[30:31], v[26:27], 0, v[52:53]
	s_addc_u32 s21, s11, s21
	v_lshl_add_u64 v[34:35], s[20:21], 0, v[70:71]
	v_lshl_add_u64 v[46:47], v[34:35], 0, v[72:73]
	v_lshl_add_u64 v[50:51], s[10:11], 0, v[70:71]
	v_lshl_add_u64 v[78:79], v[50:51], 0, v[72:73]
	s_mov_b32 s24, 0
	v_lshl_add_u64 v[84:85], v[68:69], 0, v[52:53]
	ds_write_b128 v103, v[2:5]
	ds_write_b128 v103, v[6:9] offset:8704
	ds_write_b128 v103, v[10:13] offset:17408
	ds_write_b128 v103, v[14:17] offset:26112
	ds_write_b128 v103, v[18:21] offset:34816
	ds_write_b128 v103, v[22:25] offset:43520
	global_load_dwordx4 v[26:29], v[30:31], off
	v_add_co_u32_e32 v30, vcc, s25, v30
	global_load_dwordx4 v[34:37], v[46:47], off
	s_nop 0
	v_addc_co_u32_e32 v31, vcc, 0, v31, vcc
	v_add_co_u32_e32 v38, vcc, s25, v46
	global_load_dwordx4 v[30:33], v[30:31], off
	s_nop 0
	v_addc_co_u32_e32 v39, vcc, 0, v47, vcc
	v_add_co_u32_e32 v42, vcc, s30, v46
	global_load_dwordx4 v[38:41], v[38:39], off
	s_nop 0
	v_addc_co_u32_e32 v43, vcc, 0, v47, vcc
	v_add_co_u32_e32 v46, vcc, s31, v46
	global_load_dwordx4 v[42:45], v[42:43], off
	s_nop 0
	v_addc_co_u32_e32 v47, vcc, 0, v47, vcc
	global_load_dwordx4 v[46:49], v[46:47], off
	v_mul_f32_e32 v50, 0x43000000, v0
	v_cmp_gt_f32_e32 vcc, s34, v50
	s_and_b64 s[10:11], vcc, exec
	s_cselect_b32 s10, 0xffffffc0, 0
	v_cndmask_b32_e32 v51, 0, v253, vcc
	v_fmac_f32_e32 v51, 0x43000000, v0
	v_exp_f32_e32 v0, v51
	v_mov_b32_e32 v50, 0
	v_mov_b32_e32 v51, v50
	v_mov_b32_e32 v52, v50
	v_ldexp_f32 v80, v0, s10
	s_lshl_b32 s10, s96, 16
	v_lshl_or_b32 v0, s22, 13, v95
	s_add_u32 s20, s8, s10
	v_or_b32_e32 v54, 0x800, v0
	v_or_b32_e32 v56, 0x880, v0
	v_or_b32_e32 v58, 0x900, v0
	v_or_b32_e32 v60, 0x980, v0
	s_addc_u32 s21, s9, 0
	v_mov_b32_e32 v82, v80
	v_mov_b32_e32 v83, v80
	v_lshlrev_b32_e32 v86, 1, v54
	v_lshlrev_b32_e32 v88, 1, v56
	v_lshlrev_b32_e32 v90, 1, v58
	v_lshlrev_b32_e32 v92, 1, v60
	v_lshlrev_b32_e32 v0, 1, v0
	s_mov_b32 s22, s17
	v_mov_b32_e32 v53, v50
	v_mov_b32_e32 v62, v50
	v_mov_b32_e32 v63, v50
	v_mov_b32_e32 v64, v50
	v_mov_b32_e32 v65, v50
	v_mov_b32_e32 v58, v50
	v_mov_b32_e32 v59, v50
	v_mov_b32_e32 v60, v50
	v_mov_b32_e32 v61, v50
	v_mov_b32_e32 v54, v50
	v_mov_b32_e32 v55, v50
	v_mov_b32_e32 v56, v50
	v_mov_b32_e32 v57, v50
	s_waitcnt lgkmcnt(0)
	s_barrier
	s_branch .LBB0_284

; DEVINL void na_phase(CParams& p, const Ctx& cx, int l, const GI& gi) {
;     ...
;     const int c = cb * 16 + fr, cs = min(max(c - 8, 0), 48);
;     float mx = -1e30f;
; #pragma unroll
;     for (int t = 0; t < 16; ++t) {
;       const int ro = rs + (t >> 1) - r + 7;
; #pragma unroll
;       for (int j = 0; j < 4; ++j) {
;         const int kc = kstart + (t & 1) * 16 + fq * 4 + j;
;         const bool valid = kc >= cs && kc < cs + 16;
;         const int ci = min(max(kc - c + 15, 0), 30);
;         const float bv = rp[ro * 31 + ci];
;         const float v = valid ? s[t][j] + bv : -1e30f;
;         s[t][j] = v; mx = fmaxf(mx, v);
;       }
;     }
;     mx = fmaxf(mx, shflx(mx, 16, lane)); mx = fmaxf(mx, shflx(mx, 32, lane));
;     float sum = 0.f;
; #pragma unroll
;     for (int t = 0; t < 16; ++t)
; #pragma unroll
;       for (int j = 0; j < 4; ++j) { const float e = s[t][j] > -1e29f ? __expf(s[t][j] - mx) : 0.f; s[t][j] = e; sum += e; }
.LBB0_305:
	s_or_b64 exec, exec, s[6:7]
	s_mov_b32 s4, 0xf149f2ca
	v_max3_f32 v4, v67, s4, v66
	v_max3_f32 v4, v4, v63, v62
	v_max3_f32 v4, v4, v65, v64
	v_max3_f32 v4, v4, v58, v59
	v_max3_f32 v4, v4, v61, v60
	v_max3_f32 v4, v4, v55, v54
	v_max3_f32 v4, v4, v57, v56
	v_max3_f32 v4, v4, v51, v50
	v_max3_f32 v4, v4, v53, v52
	v_max3_f32 v4, v4, v47, v46
	v_max3_f32 v4, v4, v49, v48
	v_max3_f32 v4, v4, v43, v42
	v_max3_f32 v4, v4, v45, v44
	v_max3_f32 v4, v4, v39, v38
	v_max3_f32 v4, v4, v41, v40
	v_max3_f32 v4, v4, v35, v34
	v_max3_f32 v4, v4, v37, v36
	v_max3_f32 v4, v4, v31, v30
	v_max3_f32 v4, v4, v33, v32
	v_max3_f32 v4, v4, v27, v26
	v_max3_f32 v4, v4, v29, v28
	v_max3_f32 v4, v4, v23, v22
	v_max3_f32 v4, v4, v25, v24
	v_max3_f32 v4, v4, v19, v18
	v_max3_f32 v4, v4, v21, v20
	v_max3_f32 v4, v4, v15, v14
	v_max3_f32 v4, v4, v17, v16
	v_max3_f32 v4, v4, v11, v10
	v_max3_f32 v4, v4, v13, v12
	v_max3_f32 v4, v4, v69, v7
	v_max3_f32 v4, v4, v8, v6
	v_max3_f32 v4, v4, v2, v3
	ds_bpermute_b32 v5, v136, v4
	s_mov_b32 s93, 0xefa18f08
	v_cmp_lt_f32_e32 vcc, s93, v67
	v_cmp_lt_f32_e64 s[76:77], s93, v60
	v_cmp_lt_f32_e64 s[56:57], s93, v38
	s_waitcnt lgkmcnt(0)
	v_max_f32_e32 v5, v5, v5
	v_max_f32_e32 v4, v4, v5
	ds_bpermute_b32 v5, v137, v4
	v_cmp_lt_f32_e64 s[6:7], s93, v7
	v_cmp_lt_f32_e64 s[44:45], s93, v30
	v_cmp_lt_f32_e64 s[64:65], s93, v52
	v_cmp_lt_f32_e64 s[62:63], s93, v35
	s_waitcnt lgkmcnt(0)
	v_max_f32_e32 v5, v5, v5
	v_max_f32_e32 v4, v4, v5
	v_sub_f32_e32 v5, v67, v4
	v_mul_f32_e32 v5, 0x3fb8aa3b, v5
	v_exp_f32_e32 v5, v5
	v_sub_f32_e32 v76, v59, v4
	v_mul_f32_e32 v76, 0x3fb8aa3b, v76
	v_exp_f32_e32 v76, v76
	v_sub_f32_e32 v77, v61, v4
	v_cndmask_b32_e32 v143, 0, v5, vcc
	v_mul_f32_e32 v77, 0x3fb8aa3b, v77
	v_cmp_lt_f32_e32 vcc, s93, v59
	v_sub_f32_e32 v59, v60, v4
	v_sub_f32_e32 v60, v50, v4
	v_exp_f32_e32 v77, v77
	v_mul_f32_e32 v60, 0x3fb8aa3b, v60
	v_cndmask_b32_e32 v144, 0, v76, vcc
	v_cmp_lt_f32_e32 vcc, s93, v61
	v_exp_f32_e32 v60, v60
	v_sub_f32_e32 v61, v53, v4
	v_mul_f32_e32 v61, 0x3fb8aa3b, v61
	v_exp_f32_e32 v61, v61
	v_sub_f32_e32 v38, v38, v4
	v_cndmask_b32_e32 v142, 0, v77, vcc
	v_cmp_lt_f32_e32 vcc, s93, v50
	v_mul_f32_e32 v38, 0x3fb8aa3b, v38
	v_sub_f32_e32 v7, v7, v4
	v_cndmask_b32_e32 v146, 0, v60, vcc
	v_exp_f32_e32 v60, v38
	v_sub_f32_e32 v38, v41, v4
	v_sub_f32_e32 v30, v30, v4
	v_mul_f32_e32 v7, 0x3fb8aa3b, v7
	v_cmp_lt_f32_e32 vcc, s93, v53
	v_sub_f32_e32 v50, v52, v4
	v_sub_f32_e32 v52, v42, v4
	v_mul_f32_e32 v38, 0x3fb8aa3b, v38
	v_sub_f32_e32 v35, v35, v4
	v_mul_f32_e32 v30, 0x3fb8aa3b, v30
	v_cmp_lt_f32_e64 s[8:9], s93, v8
	v_exp_f32_e32 v202, v7
	v_sub_f32_e32 v7, v8, v4
	v_sub_f32_e32 v8, v3, v4
	v_sub_f32_e32 v68, v63, v4
	v_cndmask_b32_e32 v145, 0, v61, vcc
	v_mul_f32_e32 v52, 0x3fb8aa3b, v52
	v_sub_f32_e32 v53, v45, v4
	v_exp_f32_e32 v61, v38
	v_sub_f32_e32 v38, v40, v4
	v_mul_f32_e32 v35, 0x3fb8aa3b, v35
	v_exp_f32_e32 v80, v30
	v_sub_f32_e32 v30, v33, v4
	v_cmp_lt_f32_e64 s[28:29], s93, v22
	v_sub_f32_e32 v22, v22, v4
	v_mul_f32_e32 v8, 0x3fb8aa3b, v8
	v_sub_f32_e32 v9, v66, v4
	v_mul_f32_e32 v68, 0x3fb8aa3b, v68
	v_exp_f32_e32 v52, v52
	v_mul_f32_e32 v53, 0x3fb8aa3b, v53
	v_mul_f32_e32 v38, 0x3fb8aa3b, v38
	v_exp_f32_e32 v77, v35
	v_sub_f32_e32 v35, v34, v4
	v_mul_f32_e32 v30, 0x3fb8aa3b, v30
	v_cmp_lt_f32_e64 s[50:51], s93, v27
	v_sub_f32_e32 v27, v27, v4
	v_mul_f32_e32 v22, 0x3fb8aa3b, v22
	v_exp_f32_e32 v8, v8
	v_sub_f32_e32 v74, v65, v4
	v_mul_f32_e32 v9, 0x3fb8aa3b, v9
	v_exp_f32_e32 v68, v68
	v_exp_f32_e32 v53, v53
	v_exp_f32_e32 v76, v38
	v_mul_f32_e32 v35, 0x3fb8aa3b, v35
	v_sub_f32_e32 v38, v37, v4
	v_exp_f32_e32 v81, v30
	v_sub_f32_e32 v30, v32, v4
	v_mul_f32_e32 v27, 0x3fb8aa3b, v27
	v_exp_f32_e32 v124, v22
	v_sub_f32_e32 v22, v25, v4
	v_cmp_lt_f32_e64 s[16:17], s93, v14
	v_sub_f32_e32 v14, v14, v4
	v_sub_f32_e32 v73, v62, v4
	v_exp_f32_e32 v9, v9
	v_mul_f32_e32 v67, 0x3fb8aa3b, v74
	v_exp_f32_e32 v35, v35
	v_mul_f32_e32 v38, 0x3fb8aa3b, v38
	v_mul_f32_e32 v30, 0x3fb8aa3b, v30
	v_exp_f32_e32 v83, v27
	v_sub_f32_e32 v27, v26, v4
	v_mul_f32_e32 v22, 0x3fb8aa3b, v22
	v_cmp_lt_f32_e64 s[36:37], s93, v19
	v_sub_f32_e32 v19, v19, v4
	v_mul_f32_e32 v14, 0x3fb8aa3b, v14
	v_mul_f32_e32 v73, 0x3fb8aa3b, v73
	v_exp_f32_e32 v67, v67
	v_sub_f32_e32 v75, v58, v4
	v_cmp_lt_f32_e32 vcc, s93, v42
	v_exp_f32_e32 v38, v38
	v_exp_f32_e32 v82, v30
	v_mul_f32_e32 v27, 0x3fb8aa3b, v27
	v_sub_f32_e32 v30, v29, v4
	v_exp_f32_e32 v125, v22
	v_sub_f32_e32 v22, v24, v4
	v_mul_f32_e32 v19, 0x3fb8aa3b, v19
	v_exp_f32_e32 v179, v14
	v_sub_f32_e32 v14, v17, v4
	v_cmp_lt_f32_e64 s[38:39], s93, v3
	v_exp_f32_e32 v73, v73
	v_sub_f32_e32 v74, v64, v4
	v_mul_f32_e32 v75, 0x3fb8aa3b, v75
	v_cndmask_b32_e32 v148, 0, v52, vcc
	v_cmp_lt_f32_e32 vcc, s93, v45
	v_exp_f32_e32 v27, v27
	v_mul_f32_e32 v30, 0x3fb8aa3b, v30
	v_mul_f32_e32 v22, 0x3fb8aa3b, v22
	v_exp_f32_e32 v127, v19
	v_sub_f32_e32 v19, v18, v4
	v_mul_f32_e32 v14, 0x3fb8aa3b, v14
	v_cmp_lt_f32_e64 s[22:23], s93, v11
	v_sub_f32_e32 v11, v11, v4
	v_cndmask_b32_e64 v158, 0, v8, s[38:39]
	v_cmp_lt_f32_e64 s[38:39], s93, v63
	v_mul_f32_e32 v74, 0x3fb8aa3b, v74
	v_exp_f32_e32 v75, v75
	v_cndmask_b32_e32 v147, 0, v53, vcc
	v_cmp_lt_f32_e32 vcc, s93, v34
	v_exp_f32_e32 v30, v30
	v_exp_f32_e32 v126, v22
	v_mul_f32_e32 v19, 0x3fb8aa3b, v19
	v_sub_f32_e32 v22, v21, v4
	v_exp_f32_e32 v180, v14
	v_sub_f32_e32 v14, v16, v4
	v_mul_f32_e32 v11, 0x3fb8aa3b, v11
	v_cndmask_b32_e64 v93, 0, v68, s[38:39]
	v_cmp_lt_f32_e64 s[38:39], s93, v66
	v_exp_f32_e32 v74, v74
	v_cndmask_b32_e32 v151, 0, v35, vcc
	v_cmp_lt_f32_e32 vcc, s93, v37
	v_exp_f32_e32 v19, v19
	v_mul_f32_e32 v22, 0x3fb8aa3b, v22
; DEVINL void na_phase(CParams& p, const Ctx& cx, int l, const GI& gi) {
;     ...
;     mx = fmaxf(mx, shflx(mx, 16, lane)); mx = fmaxf(mx, shflx(mx, 32, lane));
;     float sum = 0.f;
; #pragma unroll
;     for (int t = 0; t < 16; ++t)
; #pragma unroll
;       for (int j = 0; j < 4; ++j) { const float e = s[t][j] > -1e29f ? __expf(s[t][j] - mx) : 0.f; s[t][j] = e; sum += e; }
;     sum += shflx(sum, 16, lane); sum += shflx(sum, 32, lane);
;     const float inv = 1.f / sum;
;     f32x4 o[4];
; #pragma unroll
;     for (int dt = 0; dt < 4; ++dt) o[dt] = f32x4{0.f, 0.f, 0.f, 0.f};
;     const int gq = (kstart >> 2) + fq, sx = (fr & 7) << 1;
;     const char* vb0 = Vb + (wb * 64 + fr) * 128 + ((gq ^ sx) * 8);
;     const char* vb1 = Vb + (wb * 64 + fr) * 128 + (((gq + 4) ^ sx) * 8);
; #pragma unroll
;     for (int i = 0; i < 8; ++i) {
;       bf16x8 a;
; #pragma unroll
;       for (int j = 0; j < 4; ++j) { a[j] = (short)f2bf(s[2 * i][j] * inv); a[4 + j] = (short)f2bf(s[2 * i + 1][j] * inv); }
; #pragma unroll
;       for (int dt = 0; dt < 4; ++dt) {
;         const bf16x4 b0 = *(const bf16x4*)(vb0 + (i * 64 + dt * 16) * 128), b1 = *(const bf16x4*)(vb1 + (i * 64 + dt * 16) * 128);
;         bf16x8 bb;
;         bb[0] = b0[0]; bb[1] = b0[1]; bb[2] = b0[2]; bb[3] = b0[3]; bb[4] = b1[0]; bb[5] = b1[1]; bb[6] = b1[2]; bb[7] = b1[3];
	v_mul_f32_e32 v14, 0x3fb8aa3b, v14
	v_exp_f32_e32 v182, v11
	v_sub_f32_e32 v11, v10, v4
	v_cndmask_b32_e64 v92, 0, v9, s[38:39]
	v_cmp_lt_f32_e64 s[38:39], s93, v65
	v_cndmask_b32_e32 v149, 0, v38, vcc
	v_cmp_lt_f32_e32 vcc, s93, v26
	v_exp_f32_e32 v22, v22
	v_exp_f32_e32 v181, v14
	v_mul_f32_e32 v11, 0x3fb8aa3b, v11
	v_sub_f32_e32 v14, v13, v4
	v_cndmask_b32_e64 v95, 0, v67, s[38:39]
	v_cmp_lt_f32_e64 s[38:39], s93, v62
	v_cndmask_b32_e32 v153, 0, v27, vcc
	v_cmp_lt_f32_e32 vcc, s93, v29
	v_exp_f32_e32 v11, v11
	v_mul_f32_e32 v14, 0x3fb8aa3b, v14
	v_cndmask_b32_e64 v94, 0, v73, s[38:39]
	v_cmp_lt_f32_e64 s[38:39], s93, v58
	v_cndmask_b32_e32 v152, 0, v30, vcc
	v_cmp_lt_f32_e32 vcc, s93, v18
	v_exp_f32_e32 v14, v14
	v_cndmask_b32_e64 v97, 0, v75, s[38:39]
	v_cmp_lt_f32_e64 s[38:39], s93, v64
	v_cndmask_b32_e32 v155, 0, v19, vcc
	v_cmp_lt_f32_e32 vcc, s93, v21
	v_cndmask_b32_e64 v96, 0, v74, s[38:39]
	v_cmp_lt_f32_e64 s[38:39], s93, v2
	v_sub_f32_e32 v3, v6, v4
	v_sub_f32_e32 v2, v2, v4
	v_cndmask_b32_e32 v154, 0, v22, vcc
	v_cmp_lt_f32_e32 vcc, s93, v10
	v_sub_f32_e32 v10, v12, v4
	v_mul_f32_e32 v3, 0x3fb8aa3b, v3
	v_mul_f32_e32 v2, 0x3fb8aa3b, v2
	v_cndmask_b32_e32 v157, 0, v11, vcc
	v_cmp_lt_f32_e32 vcc, s93, v13
	v_mul_f32_e32 v10, 0x3fb8aa3b, v10
	v_exp_f32_e32 v204, v3
	v_exp_f32_e32 v205, v2
	v_add_u32_e32 v2, v71, v138
	v_lshlrev_b32_e32 v3, 1, v70
	v_cmp_lt_f32_e64 s[78:79], s93, v55
	v_sub_f32_e32 v55, v55, v4
	v_cmp_lt_f32_e64 s[80:81], s93, v54
	v_cmp_lt_f32_e64 s[82:83], s93, v57
	v_sub_f32_e32 v54, v54, v4
	v_sub_f32_e32 v57, v57, v4
	v_cmp_lt_f32_e64 s[84:85], s93, v56
	v_cmp_lt_f32_e64 s[86:87], s93, v51
	v_sub_f32_e32 v56, v56, v4
	v_sub_f32_e32 v51, v51, v4
	v_cmp_lt_f32_e64 s[66:67], s93, v47
	v_sub_f32_e32 v47, v47, v4
	v_cmp_lt_f32_e64 s[68:69], s93, v46
	v_cmp_lt_f32_e64 s[70:71], s93, v49
	v_sub_f32_e32 v46, v46, v4
	v_sub_f32_e32 v49, v49, v4
	v_cmp_lt_f32_e64 s[72:73], s93, v48
	v_cmp_lt_f32_e64 s[74:75], s93, v43
	v_sub_f32_e32 v48, v48, v4
	v_sub_f32_e32 v43, v43, v4
	v_cmp_lt_f32_e64 s[52:53], s93, v44
	v_cmp_lt_f32_e64 s[54:55], s93, v39
	v_sub_f32_e32 v42, v44, v4
	v_sub_f32_e32 v39, v39, v4
	v_cmp_lt_f32_e64 s[58:59], s93, v41
	v_cmp_lt_f32_e64 s[60:61], s93, v40
	v_cmp_lt_f32_e64 s[40:41], s93, v36
	v_cmp_lt_f32_e64 s[42:43], s93, v31
	v_sub_f32_e32 v34, v36, v4
	v_sub_f32_e32 v31, v31, v4
	v_cmp_lt_f32_e64 s[46:47], s93, v33
	v_cmp_lt_f32_e64 s[48:49], s93, v32
	v_cmp_lt_f32_e64 s[24:25], s93, v28
	v_cmp_lt_f32_e64 s[26:27], s93, v23
	v_sub_f32_e32 v26, v28, v4
	v_sub_f32_e32 v23, v23, v4
	v_cmp_lt_f32_e64 s[30:31], s93, v25
	v_cmp_lt_f32_e64 s[34:35], s93, v24
	v_cmp_lt_f32_e64 s[12:13], s93, v20
	v_cmp_lt_f32_e64 s[14:15], s93, v15
	v_sub_f32_e32 v18, v20, v4
	v_sub_f32_e32 v15, v15, v4
	v_cmp_lt_f32_e64 s[18:19], s93, v17
	v_cmp_lt_f32_e64 s[20:21], s93, v16
	v_cndmask_b32_e32 v156, 0, v14, vcc
	v_cmp_lt_f32_e32 vcc, s93, v12
	v_cmp_lt_f32_e64 s[4:5], s93, v69
	v_exp_f32_e32 v200, v10
	v_sub_f32_e32 v10, v69, v4
	v_cmp_lt_f32_e64 s[10:11], s93, v6
	v_or_b32_e32 v4, v0, v72
	v_readlane_b32 s93, v255, 48
	v_bitop3_b32 v6, v2, v3, 14 bitop3:0x78
	v_add_u32_e32 v2, 4, v2
	v_add_f32_e32 v5, 0, v143
	v_lshl_add_u32 v4, v4, 7, s93
	v_bitop3_b32 v2, v2, v3, 14 bitop3:0x78
	v_lshl_add_u32 v159, v2, 3, v4
	v_add_f32_e32 v2, v92, v5
	v_mul_f32_e32 v15, 0x3fb8aa3b, v15
	v_lshl_add_u32 v160, v6, 3, v4
	v_add_f32_e32 v2, v93, v2
	v_exp_f32_e32 v178, v15
	v_add_f32_e32 v2, v94, v2
	ds_read2st64_b64 v[12:15], v160 offset1:4
	v_add_f32_e32 v2, v95, v2
	v_add_f32_e32 v2, v96, v2
	v_add_f32_e32 v6, v97, v2
	v_mul_f32_e32 v18, 0x3fb8aa3b, v18
	v_mul_f32_e32 v10, 0x3fb8aa3b, v10
	v_mul_f32_e32 v7, 0x3fb8aa3b, v7
	v_add_f32_e32 v6, v144, v6
	v_exp_f32_e32 v161, v18
	v_exp_f32_e32 v201, v10
	v_exp_f32_e32 v203, v7
	ds_read2st64_b64 v[2:5], v159 offset1:4
	v_add_f32_e32 v20, v142, v6
	s_waitcnt lgkmcnt(1)
	v_mov_b32_e32 v6, v12
	v_mov_b32_e32 v7, v13
	ds_read2st64_b64 v[16:19], v160 offset0:8 offset1:12
	ds_read2st64_b64 v[10:13], v159 offset0:8 offset1:12
	v_mul_f32_e32 v59, 0x3fb8aa3b, v59
	v_mul_f32_e32 v55, 0x3fb8aa3b, v55
	v_mul_f32_e32 v54, 0x3fb8aa3b, v54
	v_mul_f32_e32 v57, 0x3fb8aa3b, v57
	v_mul_f32_e32 v56, 0x3fb8aa3b, v56
	v_mul_f32_e32 v51, 0x3fb8aa3b, v51
	v_mul_f32_e32 v50, 0x3fb8aa3b, v50
	v_mul_f32_e32 v47, 0x3fb8aa3b, v47
	v_mul_f32_e32 v46, 0x3fb8aa3b, v46
	v_mul_f32_e32 v49, 0x3fb8aa3b, v49
	v_mul_f32_e32 v48, 0x3fb8aa3b, v48
	v_mul_f32_e32 v43, 0x3fb8aa3b, v43
	v_mul_f32_e32 v42, 0x3fb8aa3b, v42
	v_mul_f32_e32 v39, 0x3fb8aa3b, v39
	v_mul_f32_e32 v34, 0x3fb8aa3b, v34
	v_mul_f32_e32 v31, 0x3fb8aa3b, v31
	v_mul_f32_e32 v26, 0x3fb8aa3b, v26
	v_mul_f32_e32 v23, 0x3fb8aa3b, v23
	v_exp_f32_e32 v59, v59
	v_exp_f32_e32 v55, v55
	v_exp_f32_e32 v54, v54
	v_exp_f32_e32 v57, v57
	v_exp_f32_e32 v56, v56
	v_exp_f32_e32 v51, v51
	v_exp_f32_e32 v50, v50
	v_exp_f32_e32 v47, v47
	v_exp_f32_e32 v46, v46
	v_exp_f32_e32 v49, v49
	v_exp_f32_e32 v48, v48
	v_exp_f32_e32 v43, v43
	v_exp_f32_e32 v52, v42
	v_exp_f32_e32 v53, v39
	v_exp_f32_e32 v78, v34
	v_exp_f32_e32 v79, v31
	v_exp_f32_e32 v84, v26
	v_exp_f32_e32 v85, v23
	s_waitcnt lgkmcnt(2)
	v_mov_b32_e32 v8, v2
	v_mov_b32_e32 v9, v3
	v_mov_b32_e32 v2, v14
	v_mov_b32_e32 v3, v15
	s_waitcnt lgkmcnt(1)
	v_mov_b32_e32 v14, v16
	v_mov_b32_e32 v15, v17
	s_waitcnt lgkmcnt(0)
; DEVINL void na_phase(CParams& p, const Ctx& cx, int l, const GI& gi) {
;     ...
; #pragma unroll
;     for (int t = 0; t < 16; ++t)
; #pragma unroll
;       for (int j = 0; j < 4; ++j) { const float e = s[t][j] > -1e29f ? __expf(s[t][j] - mx) : 0.f; s[t][j] = e; sum += e; }
;     sum += shflx(sum, 16, lane); sum += shflx(sum, 32, lane);
;     const float inv = 1.f / sum;
;     f32x4 o[4];
; #pragma unroll
;     for (int dt = 0; dt < 4; ++dt) o[dt] = f32x4{0.f, 0.f, 0.f, 0.f};
;     const int gq = (kstart >> 2) + fq, sx = (fr & 7) << 1;
;     const char* vb0 = Vb + (wb * 64 + fr) * 128 + ((gq ^ sx) * 8);
;     const char* vb1 = Vb + (wb * 64 + fr) * 128 + (((gq + 4) ^ sx) * 8);
; #pragma unroll
;     for (int i = 0; i < 8; ++i) {
;       bf16x8 a;
; #pragma unroll
;       for (int j = 0; j < 4; ++j) { a[j] = (short)f2bf(s[2 * i][j] * inv); a[4 + j] = (short)f2bf(s[2 * i + 1][j] * inv); }
; #pragma unroll
;       for (int dt = 0; dt < 4; ++dt) {
;         const bf16x4 b0 = *(const bf16x4*)(vb0 + (i * 64 + dt * 16) * 128), b1 = *(const bf16x4*)(vb1 + (i * 64 + dt * 16) * 128);
;         bf16x8 bb;
;         bb[0] = b0[0]; bb[1] = b0[1]; bb[2] = b0[2]; bb[3] = b0[3]; bb[4] = b1[0]; bb[5] = b1[1]; bb[6] = b1[2]; bb[7] = b1[3];
	v_mov_b32_e32 v16, v10
	v_mov_b32_e32 v17, v11
	v_mov_b32_e32 v10, v18
	v_mov_b32_e32 v11, v19
	v_cndmask_b32_e64 v98, 0, v59, s[76:77]
	v_cndmask_b32_e64 v99, 0, v55, s[78:79]
	v_add_f32_e32 v18, v98, v20
	v_add_f32_e32 v18, v99, v18
	v_cndmask_b32_e64 v100, 0, v54, s[80:81]
	v_cndmask_b32_e64 v101, 0, v57, s[82:83]
	v_add_f32_e32 v18, v100, v18
	ds_read2st64_b64 v[28:31], v160 offset0:16 offset1:20
	v_add_f32_e32 v18, v101, v18
	v_cndmask_b32_e64 v102, 0, v56, s[84:85]
	v_cndmask_b32_e64 v103, 0, v51, s[86:87]
	v_add_f32_e32 v18, v102, v18
	v_add_f32_e32 v22, v103, v18
	v_add_f32_e32 v22, v146, v22
	ds_read2st64_b64 v[18:21], v159 offset0:16 offset1:20
	v_add_f32_e32 v36, v145, v22
	s_waitcnt lgkmcnt(1)
	v_mov_b32_e32 v22, v28
	v_mov_b32_e32 v23, v29
	ds_read2st64_b64 v[32:35], v160 offset0:24 offset1:28
	ds_read2st64_b64 v[26:29], v159 offset0:24 offset1:28
	s_waitcnt lgkmcnt(2)
	v_mov_b32_e32 v24, v18
	v_mov_b32_e32 v25, v19
	v_mov_b32_e32 v18, v30
	v_mov_b32_e32 v19, v31
	s_waitcnt lgkmcnt(1)
	v_mov_b32_e32 v30, v32
	v_mov_b32_e32 v31, v33
	s_waitcnt lgkmcnt(0)
	v_mov_b32_e32 v32, v26
	v_mov_b32_e32 v33, v27
	v_mov_b32_e32 v26, v34
	v_mov_b32_e32 v27, v35
	v_cndmask_b32_e64 v104, 0, v50, s[64:65]
	v_cndmask_b32_e64 v105, 0, v47, s[66:67]
	v_add_f32_e32 v34, v104, v36
	v_add_f32_e32 v34, v105, v34
	v_cndmask_b32_e64 v106, 0, v46, s[68:69]
	v_cndmask_b32_e64 v107, 0, v49, s[70:71]
	v_add_f32_e32 v34, v106, v34
	ds_read2st64_b64 v[44:47], v160 offset0:32 offset1:36
	v_add_f32_e32 v34, v107, v34
	v_cndmask_b32_e64 v108, 0, v48, s[72:73]
	v_cndmask_b32_e64 v109, 0, v43, s[74:75]
	v_add_f32_e32 v34, v108, v34
	v_add_f32_e32 v38, v109, v34
	v_add_f32_e32 v38, v148, v38
	ds_read2st64_b64 v[34:37], v159 offset0:32 offset1:36
	v_add_f32_e32 v54, v147, v38
	s_waitcnt lgkmcnt(1)
	v_mov_b32_e32 v38, v44
	v_mov_b32_e32 v39, v45
	ds_read2st64_b64 v[48:51], v160 offset0:40 offset1:44
	ds_read2st64_b64 v[42:45], v159 offset0:40 offset1:44
	s_waitcnt lgkmcnt(2)
	v_mov_b32_e32 v40, v34
	v_mov_b32_e32 v41, v35
	v_mov_b32_e32 v34, v46
	v_mov_b32_e32 v35, v47
	s_waitcnt lgkmcnt(1)
	v_mov_b32_e32 v46, v48
	v_mov_b32_e32 v47, v49
	s_waitcnt lgkmcnt(0)
	v_mov_b32_e32 v48, v42
	v_mov_b32_e32 v49, v43
	v_mov_b32_e32 v42, v50
	v_mov_b32_e32 v43, v51
	v_cndmask_b32_e64 v110, 0, v52, s[52:53]
	v_cndmask_b32_e64 v111, 0, v53, s[54:55]
	v_add_f32_e32 v50, v110, v54
	v_add_f32_e32 v50, v111, v50
	v_cndmask_b32_e64 v112, 0, v60, s[56:57]
	v_cndmask_b32_e64 v113, 0, v61, s[58:59]
	v_add_f32_e32 v50, v112, v50
	ds_read2st64_b64 v[60:63], v160 offset0:48 offset1:52
	v_add_f32_e32 v50, v113, v50
	v_cndmask_b32_e64 v114, 0, v76, s[60:61]
	v_cndmask_b32_e64 v115, 0, v77, s[62:63]
	v_add_f32_e32 v50, v114, v50
	v_add_f32_e32 v54, v115, v50
	v_add_f32_e32 v54, v151, v54
	ds_read2st64_b64 v[50:53], v159 offset0:48 offset1:52
	v_add_f32_e32 v68, v149, v54
	s_waitcnt lgkmcnt(1)
	v_mov_b32_e32 v54, v60
	v_mov_b32_e32 v55, v61
	ds_read2st64_b64 v[64:67], v160 offset0:56 offset1:60
	ds_read2st64_b64 v[58:61], v159 offset0:56 offset1:60
	s_waitcnt lgkmcnt(2)
	v_mov_b32_e32 v56, v50
	v_mov_b32_e32 v57, v51
	v_mov_b32_e32 v50, v62
	v_mov_b32_e32 v51, v63
	s_waitcnt lgkmcnt(1)
	v_mov_b32_e32 v62, v64
	v_mov_b32_e32 v63, v65
	s_waitcnt lgkmcnt(0)
	v_mov_b32_e32 v64, v58
	v_mov_b32_e32 v65, v59
	v_mov_b32_e32 v58, v66
	v_mov_b32_e32 v59, v67
	v_cndmask_b32_e64 v116, 0, v78, s[40:41]
	v_cndmask_b32_e64 v117, 0, v79, s[42:43]
	v_add_f32_e32 v66, v116, v68
	v_add_f32_e32 v66, v117, v66
	v_cndmask_b32_e64 v118, 0, v80, s[44:45]
	v_cndmask_b32_e64 v119, 0, v81, s[46:47]
	v_add_f32_e32 v66, v118, v66
	ds_read2st64_b64 v[76:79], v160 offset0:64 offset1:68
	v_add_f32_e32 v66, v119, v66
	v_cndmask_b32_e64 v120, 0, v82, s[48:49]
	v_cndmask_b32_e64 v121, 0, v83, s[50:51]
	v_add_f32_e32 v66, v120, v66
	v_add_f32_e32 v70, v121, v66
	v_add_f32_e32 v70, v153, v70
	ds_read2st64_b64 v[66:69], v159 offset0:64 offset1:68
	v_add_f32_e32 v162, v152, v70
	s_waitcnt lgkmcnt(1)
	v_mov_b32_e32 v70, v76
	v_mov_b32_e32 v71, v77
	ds_read2st64_b64 v[80:83], v160 offset0:72 offset1:76
	ds_read2st64_b64 v[74:77], v159 offset0:72 offset1:76
	s_waitcnt lgkmcnt(2)
	v_mov_b32_e32 v72, v66
	v_mov_b32_e32 v73, v67
	v_mov_b32_e32 v66, v78
	v_mov_b32_e32 v67, v79
	s_waitcnt lgkmcnt(1)
	v_mov_b32_e32 v78, v80
	v_mov_b32_e32 v79, v81
	s_waitcnt lgkmcnt(0)
	v_mov_b32_e32 v80, v74
	v_mov_b32_e32 v81, v75
	v_mov_b32_e32 v74, v82
	v_mov_b32_e32 v75, v83
	v_cndmask_b32_e64 v122, 0, v84, s[24:25]
	v_cndmask_b32_e64 v123, 0, v85, s[26:27]
	v_add_f32_e32 v82, v122, v162
	v_add_f32_e32 v82, v123, v82
	v_cndmask_b32_e64 v124, 0, v124, s[28:29]
	v_cndmask_b32_e64 v125, 0, v125, s[30:31]
	v_add_f32_e32 v82, v124, v82
	v_add_f32_e32 v82, v125, v82
	v_cndmask_b32_e64 v126, 0, v126, s[34:35]
	v_cndmask_b32_e64 v127, 0, v127, s[36:37]
	v_add_f32_e32 v82, v126, v82
	ds_read2st64_b64 v[162:165], v160 offset0:80 offset1:84
	v_add_f32_e32 v166, v127, v82
	ds_read2st64_b64 v[82:85], v159 offset0:80 offset1:84
	ds_read2st64_b64 v[170:173], v160 offset0:88 offset1:92
	ds_read2st64_b64 v[174:177], v159 offset0:88 offset1:92
	v_add_f32_e32 v166, v155, v166
	v_add_f32_e32 v183, v154, v166
	s_waitcnt lgkmcnt(3)
	v_mov_b32_e32 v166, v162
	v_mov_b32_e32 v167, v163
	s_waitcnt lgkmcnt(2)
	v_mov_b32_e32 v168, v82
	v_mov_b32_e32 v169, v83
	v_mov_b32_e32 v82, v164
	v_mov_b32_e32 v83, v165
	s_waitcnt lgkmcnt(1)
	v_mov_b32_e32 v162, v170
	v_mov_b32_e32 v163, v171
	s_waitcnt lgkmcnt(0)
; DEVINL void na_phase(CParams& p, const Ctx& cx, int l, const GI& gi) {
;     ...
;     for (int t = 0; t < 16; ++t)
; #pragma unroll
;       for (int j = 0; j < 4; ++j) { const float e = s[t][j] > -1e29f ? __expf(s[t][j] - mx) : 0.f; s[t][j] = e; sum += e; }
;     sum += shflx(sum, 16, lane); sum += shflx(sum, 32, lane);
;     const float inv = 1.f / sum;
;     f32x4 o[4];
; #pragma unroll
;     for (int dt = 0; dt < 4; ++dt) o[dt] = f32x4{0.f, 0.f, 0.f, 0.f};
;     const int gq = (kstart >> 2) + fq, sx = (fr & 7) << 1;
;     const char* vb0 = Vb + (wb * 64 + fr) * 128 + ((gq ^ sx) * 8);
;     const char* vb1 = Vb + (wb * 64 + fr) * 128 + (((gq + 4) ^ sx) * 8);
; #pragma unroll
;     for (int i = 0; i < 8; ++i) {
;       bf16x8 a;
; #pragma unroll
;       for (int j = 0; j < 4; ++j) { a[j] = (short)f2bf(s[2 * i][j] * inv); a[4 + j] = (short)f2bf(s[2 * i + 1][j] * inv); }
; #pragma unroll
;       for (int dt = 0; dt < 4; ++dt) {
;         const bf16x4 b0 = *(const bf16x4*)(vb0 + (i * 64 + dt * 16) * 128), b1 = *(const bf16x4*)(vb1 + (i * 64 + dt * 16) * 128);
;         bf16x8 bb;
;         bb[0] = b0[0]; bb[1] = b0[1]; bb[2] = b0[2]; bb[3] = b0[3]; bb[4] = b1[0]; bb[5] = b1[1]; bb[6] = b1[2]; bb[7] = b1[3];
;         o[dt] = __builtin_amdgcn_mfma_f32_16x16x32_bf16(a, bb, o[dt], 0, 0, 0);
;       }
;       __builtin_amdgcn_sched_barrier(0);
;     }
	v_mov_b32_e32 v164, v174
	v_mov_b32_e32 v165, v175
	v_mov_b32_e32 v174, v172
	v_mov_b32_e32 v175, v173
	v_cndmask_b32_e64 v194, 0, v161, s[12:13]
	v_cndmask_b32_e64 v195, 0, v178, s[14:15]
	v_add_f32_e32 v161, v194, v183
	v_add_f32_e32 v161, v195, v161
	v_cndmask_b32_e64 v196, 0, v179, s[16:17]
	v_cndmask_b32_e64 v197, 0, v180, s[18:19]
	v_add_f32_e32 v161, v196, v161
	v_cndmask_b32_e64 v198, 0, v181, s[20:21]
	ds_read2st64_b64 v[170:173], v160 offset0:96 offset1:100
	ds_read2st64_b64 v[178:181], v159 offset0:96 offset1:100
	ds_read2st64_b64 v[186:189], v160 offset0:104 offset1:108
	ds_read2st64_b64 v[190:193], v159 offset0:104 offset1:108
	v_add_f32_e32 v161, v197, v161
	v_cndmask_b32_e64 v199, 0, v182, s[22:23]
	v_add_f32_e32 v161, v198, v161
	v_add_f32_e32 v161, v199, v161
	v_add_f32_e32 v161, v157, v161
	v_add_f32_e32 v161, v156, v161
	s_waitcnt lgkmcnt(3)
	v_mov_b32_e32 v182, v170
	v_mov_b32_e32 v183, v171
	s_waitcnt lgkmcnt(2)
	v_mov_b32_e32 v184, v178
	v_mov_b32_e32 v185, v179
	v_mov_b32_e32 v178, v172
	v_mov_b32_e32 v179, v173
	s_waitcnt lgkmcnt(1)
	v_mov_b32_e32 v170, v186
	v_mov_b32_e32 v171, v187
	s_waitcnt lgkmcnt(0)
	v_mov_b32_e32 v172, v190
	v_mov_b32_e32 v173, v191
	v_mov_b32_e32 v190, v188
	v_mov_b32_e32 v191, v189
	v_cndmask_b32_e32 v186, 0, v200, vcc
	v_cndmask_b32_e64 v187, 0, v201, s[4:5]
	v_add_f32_e32 v161, v186, v161
	v_add_f32_e32 v161, v187, v161
	v_cndmask_b32_e64 v188, 0, v202, s[6:7]
	v_cndmask_b32_e64 v189, 0, v203, s[8:9]
	v_add_f32_e32 v161, v188, v161
	v_add_f32_e32 v161, v189, v161
	v_cndmask_b32_e64 v200, 0, v204, s[10:11]
	v_cndmask_b32_e64 v201, 0, v205, s[38:39]
	v_add_f32_e32 v161, v200, v161
	v_add_f32_e32 v161, v201, v161
	v_add_f32_e32 v161, v158, v161
	ds_bpermute_b32 v202, v136, v161
	s_waitcnt lgkmcnt(0)
	v_add_f32_e32 v161, v161, v202
	ds_bpermute_b32 v202, v137, v161
	s_waitcnt lgkmcnt(0)
	v_add_f32_e32 v161, v161, v202
	s_mov_b32 s4, 0x5040100
	v_rcp_f32_e32 v202, v161
	s_nop 0
	v_pk_mul_f32 v[94:95], v[94:95], v[202:203] op_sel_hi:[1,0]
	v_mul_f32_e32 v143, v143, v202
	v_pk_mul_f32 v[92:93], v[92:93], v[202:203] op_sel_hi:[1,0]
	v_pk_mul_f32 v[96:97], v[96:97], v[202:203] op_sel_hi:[1,0]
	v_cvt_pk_bf16_f32 v94, v94, v95
	v_mul_f32_e32 v95, v144, v202
	v_cvt_pk_bf16_f32 v143, v143, s0
	v_cvt_pk_bf16_f32 v93, v92, v93
	v_cvt_pk_bf16_f32 v96, v96, v97
	v_cvt_pk_bf16_f32 v95, v95, s0
	v_perm_b32 v92, v93, v143, s4
	v_alignbit_b32 v93, v94, v93, 16
	v_alignbit_b32 v94, v96, v94, 16
	v_alignbit_b32 v95, v95, v96, 16
	s_nop 1
	v_mfma_f32_16x16x32_bf16 v[6:9], v[92:95], v[6:9], 0
	v_mfma_f32_16x16x32_bf16 v[2:5], v[92:95], v[2:5], 0
	v_mfma_f32_16x16x32_bf16 v[14:17], v[92:95], v[14:17], 0
	v_mfma_f32_16x16x32_bf16 v[10:13], v[92:95], v[10:13], 0
	v_mul_f32_e32 v92, v142, v202
	v_cvt_pk_bf16_f32 v94, v92, s0
	v_pk_mul_f32 v[92:93], v[98:99], v[202:203] op_sel_hi:[1,0]
	s_nop 0
	v_cvt_pk_bf16_f32 v93, v92, v93
	v_perm_b32 v92, v93, v94, s4
	v_pk_mul_f32 v[94:95], v[102:103], v[202:203] op_sel_hi:[1,0]
	s_nop 0
	v_cvt_pk_bf16_f32 v96, v94, v95
	v_pk_mul_f32 v[94:95], v[100:101], v[202:203] op_sel_hi:[1,0]
	s_nop 0
	v_cvt_pk_bf16_f32 v94, v94, v95
	v_mul_f32_e32 v95, v146, v202
	v_cvt_pk_bf16_f32 v95, v95, s0
	v_alignbit_b32 v93, v94, v93, 16
	v_alignbit_b32 v94, v96, v94, 16
	v_alignbit_b32 v95, v95, v96, 16
	s_nop 1
	v_mfma_f32_16x16x32_bf16 v[2:5], v[92:95], v[18:21], v[2:5]
	v_mul_f32_e32 v18, v145, v202
	v_cvt_pk_bf16_f32 v20, v18, s0
	v_pk_mul_f32 v[18:19], v[104:105], v[202:203] op_sel_hi:[1,0]
	v_mfma_f32_16x16x32_bf16 v[6:9], v[92:95], v[22:25], v[6:9]
	v_cvt_pk_bf16_f32 v19, v18, v19
	v_perm_b32 v18, v19, v20, s4
	v_pk_mul_f32 v[20:21], v[108:109], v[202:203] op_sel_hi:[1,0]
	v_mfma_f32_16x16x32_bf16 v[14:17], v[92:95], v[30:33], v[14:17]
	v_cvt_pk_bf16_f32 v22, v20, v21
	v_pk_mul_f32 v[20:21], v[106:107], v[202:203] op_sel_hi:[1,0]
	s_nop 0
	v_cvt_pk_bf16_f32 v20, v20, v21
	v_mul_f32_e32 v21, v148, v202
	v_cvt_pk_bf16_f32 v21, v21, s0
	v_alignbit_b32 v19, v20, v19, 16
	v_alignbit_b32 v20, v22, v20, 16
	v_alignbit_b32 v21, v21, v22, 16
	v_mfma_f32_16x16x32_bf16 v[10:13], v[92:95], v[26:29], v[10:13]
	ds_read2st64_b64 v[26:29], v159 offset0:112 offset1:116
	s_waitcnt lgkmcnt(0)
	v_mov_b32_e32 v32, v26
	v_mfma_f32_16x16x32_bf16 v[6:9], v[18:21], v[38:41], v[6:9]
	v_mov_b32_e32 v33, v27
	v_mfma_f32_16x16x32_bf16 v[2:5], v[18:21], v[34:37], v[2:5]
	ds_read2st64_b64 v[34:37], v159 offset0:120 offset1:124
	v_mfma_f32_16x16x32_bf16 v[14:17], v[18:21], v[46:49], v[14:17]
	v_mfma_f32_16x16x32_bf16 v[10:13], v[18:21], v[42:45], v[10:13]
	v_mul_f32_e32 v18, v147, v202
	v_cvt_pk_bf16_f32 v20, v18, s0
	v_pk_mul_f32 v[18:19], v[110:111], v[202:203] op_sel_hi:[1,0]
	s_nop 0
	v_cvt_pk_bf16_f32 v19, v18, v19
	v_perm_b32 v18, v19, v20, s4
	v_pk_mul_f32 v[20:21], v[114:115], v[202:203] op_sel_hi:[1,0]
	s_nop 0
	v_cvt_pk_bf16_f32 v22, v20, v21
	v_pk_mul_f32 v[20:21], v[112:113], v[202:203] op_sel_hi:[1,0]
	s_nop 0
	v_cvt_pk_bf16_f32 v20, v20, v21
	v_mul_f32_e32 v21, v151, v202
	v_cvt_pk_bf16_f32 v21, v21, s0
	v_alignbit_b32 v19, v20, v19, 16
	v_alignbit_b32 v20, v22, v20, 16
	v_alignbit_b32 v21, v21, v22, 16
	s_nop 1
	v_mfma_f32_16x16x32_bf16 v[6:9], v[18:21], v[54:57], v[6:9]
	v_mfma_f32_16x16x32_bf16 v[2:5], v[18:21], v[50:53], v[2:5]
	v_mfma_f32_16x16x32_bf16 v[14:17], v[18:21], v[62:65], v[14:17]
	v_mfma_f32_16x16x32_bf16 v[10:13], v[18:21], v[58:61], v[10:13]
	v_mul_f32_e32 v18, v149, v202
	v_cvt_pk_bf16_f32 v20, v18, s0
	v_pk_mul_f32 v[18:19], v[116:117], v[202:203] op_sel_hi:[1,0]
	s_nop 0
	v_cvt_pk_bf16_f32 v19, v18, v19
	v_perm_b32 v18, v19, v20, s4
	v_pk_mul_f32 v[20:21], v[120:121], v[202:203] op_sel_hi:[1,0]
; DEVINL void na_phase(CParams& p, const Ctx& cx, int l, const GI& gi) {
;     ...
;     for (int i = 0; i < 8; ++i) {
;       bf16x8 a;
; #pragma unroll
;       for (int j = 0; j < 4; ++j) { a[j] = (short)f2bf(s[2 * i][j] * inv); a[4 + j] = (short)f2bf(s[2 * i + 1][j] * inv); }
; #pragma unroll
;       for (int dt = 0; dt < 4; ++dt) {
;         const bf16x4 b0 = *(const bf16x4*)(vb0 + (i * 64 + dt * 16) * 128), b1 = *(const bf16x4*)(vb1 + (i * 64 + dt * 16) * 128);
;         bf16x8 bb;
;         bb[0] = b0[0]; bb[1] = b0[1]; bb[2] = b0[2]; bb[3] = b0[3]; bb[4] = b1[0]; bb[5] = b1[1]; bb[6] = b1[2]; bb[7] = b1[3];
;         o[dt] = __builtin_amdgcn_mfma_f32_16x16x32_bf16(a, bb, o[dt], 0, 0, 0);
;       }
;       __builtin_amdgcn_sched_barrier(0);
;     }
; #pragma unroll
;     for (int dt = 0; dt < 4; ++dt)
; #pragma unroll
;       for (int j = 0; j < 4; ++j) p.nao[(size_t)(tok0 + fq * 4 + j) * 512 + h * 64 + dt * 16 + fr] = f2bf(o[dt][j]);
;     __syncthreads();
	s_nop 0
	v_cvt_pk_bf16_f32 v22, v20, v21
	v_pk_mul_f32 v[20:21], v[118:119], v[202:203] op_sel_hi:[1,0]
	s_nop 0
	v_cvt_pk_bf16_f32 v20, v20, v21
	v_mul_f32_e32 v21, v153, v202
	v_cvt_pk_bf16_f32 v21, v21, s0
	v_alignbit_b32 v19, v20, v19, 16
	v_alignbit_b32 v20, v22, v20, 16
	v_alignbit_b32 v21, v21, v22, 16
	s_nop 1
	v_mfma_f32_16x16x32_bf16 v[6:9], v[18:21], v[70:73], v[6:9]
	v_mfma_f32_16x16x32_bf16 v[2:5], v[18:21], v[66:69], v[2:5]
	v_mfma_f32_16x16x32_bf16 v[14:17], v[18:21], v[78:81], v[14:17]
	v_mfma_f32_16x16x32_bf16 v[10:13], v[18:21], v[74:77], v[10:13]
	v_mul_f32_e32 v18, v152, v202
	v_cvt_pk_bf16_f32 v20, v18, s0
	v_pk_mul_f32 v[18:19], v[122:123], v[202:203] op_sel_hi:[1,0]
	s_nop 0
	v_cvt_pk_bf16_f32 v19, v18, v19
	v_perm_b32 v18, v19, v20, s4
	v_pk_mul_f32 v[20:21], v[126:127], v[202:203] op_sel_hi:[1,0]
	s_nop 0
	v_cvt_pk_bf16_f32 v22, v20, v21
	v_pk_mul_f32 v[20:21], v[124:125], v[202:203] op_sel_hi:[1,0]
	s_nop 0
	v_cvt_pk_bf16_f32 v20, v20, v21
	v_mul_f32_e32 v21, v155, v202
	v_cvt_pk_bf16_f32 v21, v21, s0
	v_alignbit_b32 v19, v20, v19, 16
	v_alignbit_b32 v20, v22, v20, 16
	v_alignbit_b32 v21, v21, v22, 16
	s_nop 1
	v_mfma_f32_16x16x32_bf16 v[6:9], v[18:21], v[166:169], v[6:9]
	v_mfma_f32_16x16x32_bf16 v[2:5], v[18:21], v[82:85], v[2:5]
	v_mfma_f32_16x16x32_bf16 v[14:17], v[18:21], v[162:165], v[14:17]
	v_mfma_f32_16x16x32_bf16 v[10:13], v[18:21], v[174:177], v[10:13]
	v_mul_f32_e32 v18, v154, v202
	v_cvt_pk_bf16_f32 v20, v18, s0
	v_pk_mul_f32 v[18:19], v[194:195], v[202:203] op_sel_hi:[1,0]
	s_nop 0
	v_cvt_pk_bf16_f32 v19, v18, v19
	v_perm_b32 v18, v19, v20, s4
	v_pk_mul_f32 v[20:21], v[198:199], v[202:203] op_sel_hi:[1,0]
	s_nop 0
	v_cvt_pk_bf16_f32 v22, v20, v21
	v_pk_mul_f32 v[20:21], v[196:197], v[202:203] op_sel_hi:[1,0]
	s_nop 0
	v_cvt_pk_bf16_f32 v20, v20, v21
	v_mul_f32_e32 v21, v157, v202
	v_cvt_pk_bf16_f32 v21, v21, s0
	v_alignbit_b32 v19, v20, v19, 16
	v_alignbit_b32 v20, v22, v20, 16
	v_alignbit_b32 v21, v21, v22, 16
	ds_read2st64_b64 v[22:25], v160 offset0:112 offset1:116
	s_waitcnt lgkmcnt(0)
	v_mov_b32_e32 v31, v23
	v_mfma_f32_16x16x32_bf16 v[6:9], v[18:21], v[182:185], v[6:9]
	v_mov_b32_e32 v26, v24
	v_mov_b32_e32 v27, v25
	v_mov_b32_e32 v24, v34
	v_mfma_f32_16x16x32_bf16 v[2:5], v[18:21], v[178:181], v[2:5]
	v_mov_b32_e32 v25, v35
	v_mfma_f32_16x16x32_bf16 v[14:17], v[18:21], v[170:173], v[14:17]
	v_mfma_f32_16x16x32_bf16 v[10:13], v[18:21], v[190:193], v[10:13]
	v_mul_f32_e32 v18, v156, v202
	v_cvt_pk_bf16_f32 v20, v18, s0
	v_pk_mul_f32 v[18:19], v[186:187], v[202:203] op_sel_hi:[1,0]
	s_nop 0
	v_cvt_pk_bf16_f32 v19, v18, v19
	v_perm_b32 v18, v19, v20, s4
	v_pk_mul_f32 v[20:21], v[200:201], v[202:203] op_sel_hi:[1,0]
	s_nop 0
	v_cvt_pk_bf16_f32 v30, v20, v21
	v_pk_mul_f32 v[20:21], v[188:189], v[202:203] op_sel_hi:[1,0]
	s_nop 0
	v_cvt_pk_bf16_f32 v20, v20, v21
	v_mul_f32_e32 v21, v158, v202
	v_cvt_pk_bf16_f32 v21, v21, s0
	v_alignbit_b32 v19, v20, v19, 16
	v_alignbit_b32 v20, v30, v20, 16
	v_alignbit_b32 v21, v21, v30, 16
	v_mov_b32_e32 v30, v22
	s_nop 0
	v_mfma_f32_16x16x32_bf16 v[2:5], v[18:21], v[26:29], v[2:5]
	v_mfma_f32_16x16x32_bf16 v[6:9], v[18:21], v[30:33], v[6:9]
	ds_read2st64_b64 v[30:33], v160 offset0:120 offset1:124
	s_waitcnt lgkmcnt(0)
	v_mov_b32_e32 v22, v30
	v_mov_b32_e32 v23, v31
	v_mov_b32_e32 v34, v32
	v_mov_b32_e32 v35, v33
	v_mfma_f32_16x16x32_bf16 v[14:17], v[18:21], v[22:25], v[14:17]
	s_nop 0
	v_mfma_f32_16x16x32_bf16 v[10:13], v[18:21], v[34:37], v[10:13]
	v_add3_u32 v18, v129, s96, v141
	v_readlane_b32 s4, v255, 49
	v_lshlrev_b32_e32 v0, 1, v0
	v_readlane_b32 s5, v255, 50
	v_ashrrev_i32_e32 v19, 31, v18
	v_lshlrev_b64 v[22:23], 10, v[18:19]
	v_lshl_add_u64 v[20:21], s[4:5], 0, v[0:1]
	v_cvt_pk_bf16_f32 v0, v6, s0
	v_lshl_add_u64 v[22:23], v[20:21], 0, v[22:23]
	v_add_u32_e32 v6, 1, v18
	global_store_short v[22:23], v0, off
	v_cvt_pk_bf16_f32 v0, v7, s0
	v_ashrrev_i32_e32 v7, 31, v6
	v_add_u32_e32 v24, 2, v18
	v_lshlrev_b64 v[6:7], 10, v[6:7]
	v_ashrrev_i32_e32 v25, 31, v24
	v_lshl_add_u64 v[6:7], v[20:21], 0, v[6:7]
	v_lshlrev_b64 v[24:25], 10, v[24:25]
	global_store_short v[6:7], v0, off
	v_cvt_pk_bf16_f32 v0, v8, s0
	v_lshl_add_u64 v[24:25], v[20:21], 0, v[24:25]
	v_add_u32_e32 v8, 3, v18
	global_store_short v[24:25], v0, off
	v_cvt_pk_bf16_f32 v0, v9, s0
	v_ashrrev_i32_e32 v9, 31, v8
	v_lshlrev_b64 v[8:9], 10, v[8:9]
	v_lshl_add_u64 v[8:9], v[20:21], 0, v[8:9]
	global_store_short v[8:9], v0, off
	v_cvt_pk_bf16_f32 v0, v2, s0
	global_store_short v[22:23], v0, off offset:32
	v_cvt_pk_bf16_f32 v0, v3, s0
	global_store_short v[6:7], v0, off offset:32
	v_cvt_pk_bf16_f32 v0, v4, s0
	global_store_short v[24:25], v0, off offset:32
	v_cvt_pk_bf16_f32 v0, v5, s0
	global_store_short v[8:9], v0, off offset:32
	v_cvt_pk_bf16_f32 v0, v14, s0
	global_store_short v[22:23], v0, off offset:64
	v_cvt_pk_bf16_f32 v0, v15, s0
	global_store_short v[6:7], v0, off offset:64
	v_cvt_pk_bf16_f32 v0, v16, s0
	global_store_short v[24:25], v0, off offset:64
	v_cvt_pk_bf16_f32 v0, v17, s0
	global_store_short v[8:9], v0, off offset:64
	v_cvt_pk_bf16_f32 v0, v10, s0
	v_readlane_b32 s4, v255, 19
	v_readlane_b32 s24, v255, 52
	global_store_short v[22:23], v0, off offset:96
	v_cvt_pk_bf16_f32 v0, v11, s0
	s_add_i32 s24, s24, s4
	v_readlane_b32 s4, v255, 20
	global_store_short v[6:7], v0, off offset:96
	v_cvt_pk_bf16_f32 v0, v12, s0
	s_add_i32 s96, s96, s4
	v_readlane_b32 s4, v255, 46
	global_store_short v[24:25], v0, off offset:96
	v_cvt_pk_bf16_f32 v0, v13, s0
	s_cmp_lt_i32 s24, s4
	global_store_short v[8:9], v0, off offset:96
	s_barrier
	s_cbranch_scc0 .LBB0_434
; DEVINL void na_phase(CParams& p, const Ctx& cx, int l, const GI& gi) {
;     ...
;   auto gload = [&](int pr) {
;     const int tokp = pr * 128, seqbase = (tokp / L) * L, r0 = (tokp - seqbase) >> 6;
;     const int w0 = min(max(r0 - 4, 0), rows - 8), w1 = min(max(r0 - 3, 0), rows - 8) + 8;
;     const int g0 = (seqbase >> 6) + w0, nwin = w1 - w0;
; #pragma unroll
;     for (int i = 0; i < 9; ++i) {
;       const int gr = g0 + min(i, nwin - 1);
;       rk[i] = *(const bf16x8*)(p.kn + ((size_t)gr * 64 + st_r) * 512 + h * 64 + st_c * 8);
;       rv[i] = *(const bf16x8*)(p.vnT + (((size_t)gr * 512 + h * 64 + st_r) << 6) + st_c * 8);
;     }
;     const u16* qp = p.qn + (size_t)(tokp + wave * 16 + (lane & 15)) * 512 + h * 64 + (lane >> 4) * 8;
;     rq0 = *(const bf16x8*)qp; rq1 = *(const bf16x8*)(qp + 32);
;   };
;   for (int pr = cx.bid >> 3; pr < npairs; pr += nbh) {
;     gload(pr);
;     const int sw = (st_c ^ (st_r & 7)) * 16;
; #pragma unroll
;     for (int i = 0; i < 9; ++i) {
;       *(bf16x8*)(Kb + (i * 64 + st_r) * 128 + sw) = rk[i];
;       *(bf16x8*)(Vb + (i * 64 + st_r) * 128 + sw) = rv[i];
;     }
;     const bf16x8 bq0 = rq0, bq1 = rq1;
;     __syncthreads();
;     int lane_o = lane; asm volatile("" : "+v"(lane_o));
;     const int fr = lane_o & 15, fq = lane_o >> 4;
;     const int tokp = pr * 128, seqbase = (tokp / L) * L, r0 = (tokp - seqbase) >> 6;
;     const int w0 = min(max(r0 - 4, 0), rows - 8);
;     const int tok0 = tokp + wave * 16, r = r0 + (wave >> 2), cb = wave & 3;
;     const int rs = min(max(r - 4, 0), rows - 8);
;     const int kstart = min(max(cb * 16 - 8, 0), 32);
;     const int wb = rs - w0;
.LBB0_306:
	v_readfirstlane_b32 s100, v234
	s_nop 3
	s_lshr_b32 s100, s100, 6
	s_cmp_ge_u32 s100, 4
	s_cbranch_scc1 .Lprio_306_done
	s_setprio 1
.Lprio_306_done:
	s_abs_i32 s5, s96
	v_readlane_b32 s6, v255, 51
	s_mul_hi_u32 s6, s5, s6
	v_readlane_b32 s7, v255, 45
	s_mul_i32 s6, s6, s7
	s_sub_i32 s5, s5, s6
	s_ashr_i32 s4, s96, 31
	s_sub_i32 s6, s5, s7
	s_cmp_ge_u32 s5, s7
	s_cselect_b32 s5, s6, s5
	s_sub_i32 s6, s5, s7
	s_cmp_ge_u32 s5, s7
	s_cselect_b32 s5, s6, s5
	s_xor_b32 s5, s5, s4
	s_sub_i32 s6, s5, s4
	s_ashr_i32 s6, s6, 6
	s_sub_i32 s4, s4, s5
	s_max_i32 s5, s6, 4
	s_add_i32 s5, s5, -4
	v_readlane_b32 s10, v255, 47
	s_min_i32 s7, s5, s10
	s_max_i32 s5, s6, 3
	s_add_i32 s5, s5, -3
	s_min_i32 s5, s5, s10
	s_not_b32 s8, s7
	s_add_i32 s4, s96, s4
	s_add_i32 s5, s5, s8
	s_ashr_i32 s4, s4, 6
	s_add_i32 s9, s5, 8
	s_add_i32 s8, s7, s4
	s_min_i32 s4, s9, 0
	s_add_i32 s4, s4, s8
	s_ashr_i32 s5, s4, 31
	s_lshl_b64 s[4:5], s[4:5], 16
	v_lshl_add_u64 v[2:3], v[86:87], 0, s[4:5]
	global_load_dwordx4 v[6:9], v[2:3], off
	v_lshl_add_u64 v[2:3], v[90:91], 0, s[4:5]
	s_min_i32 s4, s9, 1
	s_add_i32 s4, s4, s8
	s_ashr_i32 s5, s4, 31
	s_lshl_b64 s[4:5], s[4:5], 16
	global_load_dwordx4 v[10:13], v[2:3], off
	v_lshl_add_u64 v[2:3], v[86:87], 0, s[4:5]
	global_load_dwordx4 v[14:17], v[2:3], off
	v_lshl_add_u64 v[2:3], v[90:91], 0, s[4:5]
	s_min_i32 s4, s9, 2
	s_add_i32 s4, s4, s8
	s_ashr_i32 s5, s4, 31
	s_lshl_b64 s[4:5], s[4:5], 16
	global_load_dwordx4 v[18:21], v[2:3], off
	v_lshl_add_u64 v[2:3], v[86:87], 0, s[4:5]
	global_load_dwordx4 v[22:25], v[2:3], off
	v_lshl_add_u64 v[2:3], v[90:91], 0, s[4:5]
	s_min_i32 s4, s9, 3
	s_add_i32 s4, s4, s8
	s_ashr_i32 s5, s4, 31
	s_lshl_b64 s[4:5], s[4:5], 16
	global_load_dwordx4 v[26:29], v[2:3], off
	v_lshl_add_u64 v[2:3], v[86:87], 0, s[4:5]
	global_load_dwordx4 v[30:33], v[2:3], off
	v_lshl_add_u64 v[2:3], v[90:91], 0, s[4:5]
	s_min_i32 s4, s9, 4
	s_add_i32 s4, s4, s8
	s_ashr_i32 s5, s4, 31
	s_lshl_b64 s[4:5], s[4:5], 16
	global_load_dwordx4 v[34:37], v[2:3], off
	v_lshl_add_u64 v[2:3], v[86:87], 0, s[4:5]
	global_load_dwordx4 v[38:41], v[2:3], off
	v_lshl_add_u64 v[2:3], v[90:91], 0, s[4:5]
	s_min_i32 s4, s9, 5
	s_add_i32 s4, s4, s8
	s_ashr_i32 s5, s4, 31
	s_lshl_b64 s[4:5], s[4:5], 16
	global_load_dwordx4 v[42:45], v[2:3], off
	v_lshl_add_u64 v[2:3], v[86:87], 0, s[4:5]
	global_load_dwordx4 v[46:49], v[2:3], off
	v_lshl_add_u64 v[2:3], v[90:91], 0, s[4:5]
	s_min_i32 s4, s9, 6
	s_add_i32 s4, s4, s8
	s_ashr_i32 s5, s4, 31
	s_lshl_b64 s[4:5], s[4:5], 16
	global_load_dwordx4 v[50:53], v[2:3], off
	v_lshl_add_u64 v[2:3], v[86:87], 0, s[4:5]
	global_load_dwordx4 v[54:57], v[2:3], off
	v_lshl_add_u64 v[2:3], v[90:91], 0, s[4:5]
	s_min_i32 s4, s9, 7
	s_add_i32 s4, s4, s8
	s_ashr_i32 s5, s4, 31
	s_lshl_b64 s[4:5], s[4:5], 16
	global_load_dwordx4 v[58:61], v[2:3], off
	v_lshl_add_u64 v[2:3], v[86:87], 0, s[4:5]
	global_load_dwordx4 v[62:65], v[2:3], off
	v_lshl_add_u64 v[2:3], v[90:91], 0, s[4:5]
	s_min_i32 s4, s9, 8
	s_add_i32 s4, s4, s8
	s_ashr_i32 s5, s4, 31
	s_lshl_b64 s[4:5], s[4:5], 16
	global_load_dwordx4 v[70:73], v[2:3], off
	v_lshl_add_u64 v[2:3], v[86:87], 0, s[4:5]
	global_load_dwordx4 v[74:77], v[2:3], off
	v_lshl_add_u64 v[2:3], v[90:91], 0, s[4:5]
	global_load_dwordx4 v[78:81], v[2:3], off
	v_add_u32_e32 v2, s96, v140
	v_ashrrev_i32_e32 v3, 31, v2
	v_lshlrev_b64 v[2:3], 10, v[2:3]
	v_lshl_add_u64 v[2:3], v[88:89], 0, v[2:3]
	global_load_dwordx4 v[66:69], v[2:3], off
	s_nop 0
	global_load_dwordx4 v[2:5], v[2:3], off offset:64
	v_add_u32_e32 v0, v131, v130
	s_waitcnt vmcnt(19)
	ds_write_b128 v0, v[6:9]
	v_add_u32_e32 v6, v132, v130
	s_waitcnt vmcnt(18)
	ds_write_b128 v6, v[10:13]
	s_waitcnt vmcnt(17)
	ds_write_b128 v0, v[14:17] offset:8192
	s_waitcnt vmcnt(16)
	ds_write_b128 v6, v[18:21] offset:8192
	s_waitcnt vmcnt(15)
	ds_write_b128 v0, v[22:25] offset:16384
	s_waitcnt vmcnt(14)
	ds_write_b128 v6, v[26:29] offset:16384
	s_waitcnt vmcnt(13)
	ds_write_b128 v0, v[30:33] offset:24576
	s_waitcnt vmcnt(12)
	ds_write_b128 v6, v[34:37] offset:24576
	s_waitcnt vmcnt(11)
	ds_write_b128 v0, v[38:41] offset:32768
	s_waitcnt vmcnt(10)
	ds_write_b128 v6, v[42:45] offset:32768
	s_waitcnt vmcnt(9)
	ds_write_b128 v0, v[46:49] offset:40960
	s_waitcnt vmcnt(8)
	ds_write_b128 v6, v[50:53] offset:40960
	s_waitcnt vmcnt(7)
	ds_write_b128 v0, v[54:57] offset:49152
	s_waitcnt vmcnt(6)
	ds_write_b128 v6, v[58:61] offset:49152
	s_waitcnt vmcnt(5)
	ds_write_b128 v0, v[62:65] offset:57344
	s_waitcnt vmcnt(4)
	ds_write_b128 v6, v[70:73] offset:57344
	v_add_u32_e32 v73, s6, v133
	v_add_u32_e32 v0, v131, v139
	v_max_i32_e32 v6, 4, v73
	v_add_u32_e32 v6, -4, v6
	v_mov_b32_e32 v70, v128
	s_waitcnt vmcnt(3)
	ds_write_b128 v0, v[74:77]
	v_add_u32_e32 v0, v132, v139
	s_waitcnt vmcnt(2)
	ds_write_b128 v0, v[78:81]
	v_min_i32_e32 v78, s10, v6
	v_subrev_u32_e32 v6, s7, v78
	v_lshlrev_b32_e32 v72, 6, v6
	s_waitcnt lgkmcnt(0)
	s_barrier
; DEVINL void na_phase(CParams& p, const Ctx& cx, int l, const GI& gi) {
;     ...
;     f32x4 s[16];
;     const int x7 = (kstart + fr) & 7;
;     const char* kb0 = Kb + (wb * 64 + kstart + fr) * 128 + ((fq ^ x7) * 16);
;     const char* kb1 = Kb + (wb * 64 + kstart + fr) * 128 + (((4 + fq) ^ x7) * 16);
; #pragma unroll
;     for (int t = 0; t < 16; ++t) {
;       const bf16x8 a0 = *(const bf16x8*)(kb0 + ((t >> 1) * 64 + (t & 1) * 16) * 128), a1 = *(const bf16x8*)(kb1 + ((t >> 1) * 64 + (t & 1) * 16) * 128);
;       f32x4 z = {0.f, 0.f, 0.f, 0.f};
;       z = __builtin_amdgcn_mfma_f32_16x16x32_bf16(a0, bq0, z, 0, 0, 0);
;       s[t] = __builtin_amdgcn_mfma_f32_16x16x32_bf16(a1, bq1, z, 0, 0, 0);
;       if ((t & 3) == 3) __builtin_amdgcn_sched_barrier(0);
;     }
;     const int c = cb * 16 + fr, cs = min(max(c - 8, 0), 48);
;     float mx = -1e30f;
; #pragma unroll
;     for (int t = 0; t < 16; ++t) {
;       const int ro = rs + (t >> 1) - r + 7;
; #pragma unroll
;       for (int j = 0; j < 4; ++j) {
;         const int kc = kstart + (t & 1) * 16 + fq * 4 + j;
;         const bool valid = kc >= cs && kc < cs + 16;
;         const int ci = min(max(kc - c + 15, 0), 30);
;         const float bv = rp[ro * 31 + ci];
	v_or_b32_e32 v6, v72, v135
	v_and_b32_e32 v0, 15, v70
	v_ashrrev_i32_e32 v71, 4, v70
	v_add_u32_e32 v6, v6, v0
	v_lshl_add_u32 v10, v6, 7, 0
	v_bitop3_b32 v6, v71, v70, 7 bitop3:0x78
	v_lshl_add_u32 v79, v6, 4, v10
	ds_read_b128 v[6:9], v79
	v_add_u32_e32 v11, 4, v71
	v_bitop3_b32 v11, v11, v70, 7 bitop3:0x78
	v_lshl_add_u32 v80, v11, 4, v10
	ds_read_b128 v[10:13], v79 offset:2048
	s_waitcnt vmcnt(1) lgkmcnt(1)
	v_mfma_f32_16x16x32_bf16 v[6:9], v[6:9], v[66:69], 0
	ds_read_b128 v[14:17], v80
	ds_read_b128 v[18:21], v80 offset:2048
	s_waitcnt vmcnt(0) lgkmcnt(1)
	v_mfma_f32_16x16x32_bf16 v[62:65], v[14:17], v[2:5], v[6:9]
	v_mfma_f32_16x16x32_bf16 v[6:9], v[10:13], v[66:69], 0
	s_waitcnt lgkmcnt(0)
	v_mfma_f32_16x16x32_bf16 v[58:61], v[18:21], v[2:5], v[6:9]
	s_nop 5
	ds_read_b128 v[6:9], v79 offset:8192
	ds_read_b128 v[10:13], v79 offset:10240
	ds_read_b128 v[14:17], v80 offset:8192
	ds_read_b128 v[18:21], v80 offset:10240
	s_waitcnt lgkmcnt(3)
	v_mfma_f32_16x16x32_bf16 v[6:9], v[6:9], v[66:69], 0
	s_waitcnt lgkmcnt(1)
	v_mfma_f32_16x16x32_bf16 v[54:57], v[14:17], v[2:5], v[6:9]
	v_mfma_f32_16x16x32_bf16 v[6:9], v[10:13], v[66:69], 0
	s_waitcnt lgkmcnt(0)
	v_mfma_f32_16x16x32_bf16 v[50:53], v[18:21], v[2:5], v[6:9]
	s_nop 5
	ds_read_b128 v[6:9], v79 offset:16384
	ds_read_b128 v[10:13], v80 offset:16384
	s_waitcnt lgkmcnt(1)
	v_mfma_f32_16x16x32_bf16 v[6:9], v[6:9], v[66:69], 0
	s_waitcnt lgkmcnt(0)
	v_mfma_f32_16x16x32_bf16 v[46:49], v[10:13], v[2:5], v[6:9]
	s_nop 5
	ds_read_b128 v[6:9], v80 offset:18432
	ds_read_b128 v[10:13], v79 offset:18432
	s_waitcnt lgkmcnt(0)
	v_mfma_f32_16x16x32_bf16 v[10:13], v[10:13], v[66:69], 0
	v_mfma_f32_16x16x32_bf16 v[42:45], v[6:9], v[2:5], v[10:13]
	ds_read_b128 v[6:9], v80 offset:24576
	s_nop 5
	ds_read_b128 v[10:13], v79 offset:24576
	s_waitcnt lgkmcnt(0)
	v_mfma_f32_16x16x32_bf16 v[10:13], v[10:13], v[66:69], 0
	v_mfma_f32_16x16x32_bf16 v[38:41], v[6:9], v[2:5], v[10:13]
	ds_read_b128 v[6:9], v80 offset:26624
	s_nop 5
	ds_read_b128 v[10:13], v79 offset:26624
	s_waitcnt lgkmcnt(0)
	v_mfma_f32_16x16x32_bf16 v[10:13], v[10:13], v[66:69], 0
	v_mfma_f32_16x16x32_bf16 v[34:37], v[6:9], v[2:5], v[10:13]
	ds_read_b128 v[6:9], v79 offset:32768
	s_nop 5
	ds_read_b128 v[10:13], v80 offset:32768
	s_waitcnt lgkmcnt(1)
	v_mfma_f32_16x16x32_bf16 v[6:9], v[6:9], v[66:69], 0
	s_waitcnt lgkmcnt(0)
	v_mfma_f32_16x16x32_bf16 v[30:33], v[10:13], v[2:5], v[6:9]
	s_nop 5
	ds_read_b128 v[6:9], v80 offset:34816
	ds_read_b128 v[10:13], v79 offset:34816
	s_waitcnt lgkmcnt(0)
	v_mfma_f32_16x16x32_bf16 v[10:13], v[10:13], v[66:69], 0
	v_mfma_f32_16x16x32_bf16 v[26:29], v[6:9], v[2:5], v[10:13]
	ds_read_b128 v[6:9], v80 offset:40960
	s_nop 5
	ds_read_b128 v[10:13], v79 offset:40960
	s_waitcnt lgkmcnt(0)
	v_mfma_f32_16x16x32_bf16 v[10:13], v[10:13], v[66:69], 0
	v_mfma_f32_16x16x32_bf16 v[22:25], v[6:9], v[2:5], v[10:13]
	ds_read_b128 v[6:9], v80 offset:43008
	s_nop 5
	ds_read_b128 v[10:13], v79 offset:43008
	s_waitcnt lgkmcnt(0)
	v_mfma_f32_16x16x32_bf16 v[10:13], v[10:13], v[66:69], 0
	v_mfma_f32_16x16x32_bf16 v[18:21], v[6:9], v[2:5], v[10:13]
	ds_read_b128 v[6:9], v79 offset:49152
	s_nop 5
	ds_read_b128 v[10:13], v79 offset:51200
	ds_read_b128 v[14:17], v80 offset:49152
	s_waitcnt lgkmcnt(2)
	v_mfma_f32_16x16x32_bf16 v[6:9], v[6:9], v[66:69], 0
	ds_read_b128 v[74:77], v80 offset:57344
	s_waitcnt lgkmcnt(1)
	v_mfma_f32_16x16x32_bf16 v[14:17], v[14:17], v[2:5], v[6:9]
	s_nop 4
	ds_read_b128 v[6:9], v80 offset:51200
	v_mfma_f32_16x16x32_bf16 v[10:13], v[10:13], v[66:69], 0
	s_waitcnt lgkmcnt(0)
	v_mfma_f32_16x16x32_bf16 v[10:13], v[6:9], v[2:5], v[10:13]
	ds_read_b128 v[6:9], v79 offset:57344
	s_waitcnt lgkmcnt(0)
	v_mfma_f32_16x16x32_bf16 v[6:9], v[6:9], v[66:69], 0
	v_mfma_f32_16x16x32_bf16 v[6:9], v[74:77], v[2:5], v[6:9]
	ds_read_b128 v[74:77], v79 offset:59392
	s_waitcnt lgkmcnt(0)
	v_mfma_f32_16x16x32_bf16 v[66:69], v[74:77], v[66:69], 0
	ds_read_b128 v[74:77], v80 offset:59392
	s_waitcnt lgkmcnt(0)
	v_mfma_f32_16x16x32_bf16 v[2:5], v[74:77], v[2:5], v[66:69]
	v_or_b32_e32 v79, v0, v134
	s_nop 3
	v_max_i32_e32 v66, 8, v79
	v_add_u32_e32 v66, -8, v66
	v_min_u32_e32 v80, 48, v66
	v_sub_u32_e32 v66, v78, v73
	v_lshlrev_b32_e32 v141, 2, v71
	s_movk_i32 s4, 0x7c
	v_add_u32_e32 v82, v141, v135
	v_add_u32_e32 v81, 16, v80
	v_mul_lo_u32 v66, v66, s4
	v_readlane_b32 s4, v255, 29
	v_mov_b32_e32 v190, 0xf149f2ca
	s_nop 0
	v_add_u32_e32 v68, s4, v66
	v_cmp_ge_i32_e32 vcc, v82, v80
	v_cmp_lt_i32_e64 s[4:5], v82, v81
	v_sub_u32_e32 v189, v82, v79
	s_and_b64 s[4:5], vcc, s[4:5]
	v_max_i32_e32 v189, -15, v189
	v_add_u32_e32 v189, 15, v189
	v_min_u32_e32 v189, 30, v189
	v_lshl_add_u32 v180, v189, 2, v68
	v_add_u32_e32 v188, 1, v82
	v_cmp_ge_i32_e32 vcc, v188, v80
	v_cmp_lt_i32_e64 s[8:9], v188, v81
	v_sub_u32_e32 v189, v188, v79
	s_and_b64 s[8:9], vcc, s[8:9]
	v_max_i32_e32 v189, -15, v189
	v_add_u32_e32 v189, 15, v189
	v_min_u32_e32 v189, 30, v189
	v_lshl_add_u32 v181, v189, 2, v68
	v_add_u32_e32 v188, 2, v82
	v_cmp_ge_i32_e32 vcc, v188, v80
	v_cmp_lt_i32_e64 s[10:11], v188, v81
	v_sub_u32_e32 v189, v188, v79
	s_and_b64 s[10:11], vcc, s[10:11]
	v_max_i32_e32 v189, -15, v189
	v_add_u32_e32 v189, 15, v189
	v_min_u32_e32 v189, 30, v189
	v_lshl_add_u32 v182, v189, 2, v68
	v_add_u32_e32 v188, 3, v82
	v_cmp_ge_i32_e32 vcc, v188, v80
	v_cmp_lt_i32_e64 s[12:13], v188, v81
	v_sub_u32_e32 v189, v188, v79
	s_and_b64 s[12:13], vcc, s[12:13]
	v_max_i32_e32 v189, -15, v189
	v_add_u32_e32 v189, 15, v189
	v_min_u32_e32 v189, 30, v189
	v_lshl_add_u32 v183, v189, 2, v68
	v_add_u32_e32 v188, 16, v82
	v_cmp_ge_i32_e32 vcc, v188, v80
	v_cmp_lt_i32_e64 s[14:15], v188, v81
; DEVINL void na_phase(CParams& p, const Ctx& cx, int l, const GI& gi) {
;     ...
;     const int c = cb * 16 + fr, cs = min(max(c - 8, 0), 48);
;     float mx = -1e30f;
; #pragma unroll
;     for (int t = 0; t < 16; ++t) {
;       const int ro = rs + (t >> 1) - r + 7;
; #pragma unroll
;       for (int j = 0; j < 4; ++j) {
;         const int kc = kstart + (t & 1) * 16 + fq * 4 + j;
;         const bool valid = kc >= cs && kc < cs + 16;
;         const int ci = min(max(kc - c + 15, 0), 30);
;         const float bv = rp[ro * 31 + ci];
	v_sub_u32_e32 v189, v188, v79
	s_and_b64 s[14:15], vcc, s[14:15]
	v_max_i32_e32 v189, -15, v189
	v_add_u32_e32 v189, 15, v189
	v_min_u32_e32 v189, 30, v189
	v_lshl_add_u32 v184, v189, 2, v68
	v_add_u32_e32 v188, 17, v82
	v_cmp_ge_i32_e32 vcc, v188, v80
	v_cmp_lt_i32_e64 s[16:17], v188, v81
	v_sub_u32_e32 v189, v188, v79
	s_and_b64 s[16:17], vcc, s[16:17]
	v_max_i32_e32 v189, -15, v189
	v_add_u32_e32 v189, 15, v189
	v_min_u32_e32 v189, 30, v189
	v_lshl_add_u32 v185, v189, 2, v68
	v_add_u32_e32 v188, 18, v82
	v_cmp_ge_i32_e32 vcc, v188, v80
	v_cmp_lt_i32_e64 s[18:19], v188, v81
	v_sub_u32_e32 v189, v188, v79
	s_and_b64 s[18:19], vcc, s[18:19]
	v_max_i32_e32 v189, -15, v189
	v_add_u32_e32 v189, 15, v189
	v_min_u32_e32 v189, 30, v189
	v_lshl_add_u32 v186, v189, 2, v68
	v_add_u32_e32 v188, 19, v82
	v_cmp_ge_i32_e32 vcc, v188, v80
	v_cmp_lt_i32_e64 s[6:7], v188, v81
	v_sub_u32_e32 v189, v188, v79
	s_and_b64 s[6:7], vcc, s[6:7]
	v_max_i32_e32 v189, -15, v189
	v_add_u32_e32 v189, 15, v189
	v_min_u32_e32 v189, 30, v189
	v_lshl_add_u32 v187, v189, 2, v68
	ds_read_b32 v92, v180 offset:868
	ds_read_b32 v93, v181 offset:868
	ds_read_b32 v94, v182 offset:868
	ds_read_b32 v95, v183 offset:868
	ds_read_b32 v96, v184 offset:868
	ds_read_b32 v97, v185 offset:868
	ds_read_b32 v98, v186 offset:868
	ds_read_b32 v99, v187 offset:868
	ds_read_b32 v100, v180 offset:992
	ds_read_b32 v101, v181 offset:992
	ds_read_b32 v102, v182 offset:992
	ds_read_b32 v103, v183 offset:992
	ds_read_b32 v104, v184 offset:992
	ds_read_b32 v105, v185 offset:992
	ds_read_b32 v106, v186 offset:992
	ds_read_b32 v107, v187 offset:992
	ds_read_b32 v108, v180 offset:1116
	ds_read_b32 v109, v181 offset:1116
	ds_read_b32 v110, v182 offset:1116
	ds_read_b32 v111, v183 offset:1116
	ds_read_b32 v112, v184 offset:1116
	ds_read_b32 v113, v185 offset:1116
	ds_read_b32 v114, v186 offset:1116
	ds_read_b32 v115, v187 offset:1116
	ds_read_b32 v116, v180 offset:1240
	ds_read_b32 v117, v181 offset:1240
	ds_read_b32 v118, v182 offset:1240
	ds_read_b32 v119, v183 offset:1240
	ds_read_b32 v120, v184 offset:1240
	ds_read_b32 v121, v185 offset:1240
	ds_read_b32 v122, v186 offset:1240
	ds_read_b32 v123, v187 offset:1240
	ds_read_b32 v124, v180 offset:1364
	ds_read_b32 v125, v181 offset:1364
	ds_read_b32 v126, v182 offset:1364
	ds_read_b32 v127, v183 offset:1364
	ds_read_b32 v152, v184 offset:1364
	ds_read_b32 v153, v185 offset:1364
	ds_read_b32 v154, v186 offset:1364
	ds_read_b32 v155, v187 offset:1364
	ds_read_b32 v156, v180 offset:1488
	ds_read_b32 v157, v181 offset:1488
	ds_read_b32 v158, v182 offset:1488
	ds_read_b32 v159, v183 offset:1488
	ds_read_b32 v160, v184 offset:1488
	ds_read_b32 v161, v185 offset:1488
	ds_read_b32 v162, v186 offset:1488
	ds_read_b32 v163, v187 offset:1488
	ds_read_b32 v164, v180 offset:1612
	ds_read_b32 v165, v181 offset:1612
	ds_read_b32 v166, v182 offset:1612
	ds_read_b32 v167, v183 offset:1612
	ds_read_b32 v168, v184 offset:1612
	ds_read_b32 v169, v185 offset:1612
	ds_read_b32 v170, v186 offset:1612
	ds_read_b32 v171, v187 offset:1612
	ds_read_b32 v172, v180 offset:1736
	ds_read_b32 v173, v181 offset:1736
	ds_read_b32 v174, v182 offset:1736
	ds_read_b32 v175, v183 offset:1736
	ds_read_b32 v176, v184 offset:1736
	ds_read_b32 v177, v185 offset:1736
	ds_read_b32 v178, v186 offset:1736
	ds_read_b32 v179, v187 offset:1736
	s_waitcnt lgkmcnt(0)
; DEVINL void na_phase(CParams& p, const Ctx& cx, int l, const GI& gi) {
;     ...
;         const float v = valid ? s[t][j] + bv : -1e30f;
;         s[t][j] = v; mx = fmaxf(mx, v);
	v_add_f32_e32 v92, v62, v92
	v_cndmask_b32_e64 v67, v190, v92, s[4:5]
	v_add_f32_e32 v93, v63, v93
	v_cndmask_b32_e64 v66, v190, v93, s[8:9]
	v_add_f32_e32 v94, v64, v94
	v_cndmask_b32_e64 v63, v190, v94, s[10:11]
	v_add_f32_e32 v95, v65, v95
	v_cndmask_b32_e64 v62, v190, v95, s[12:13]
	v_add_f32_e32 v96, v58, v96
	v_cndmask_b32_e64 v65, v190, v96, s[14:15]
	v_add_f32_e32 v97, v59, v97
	v_cndmask_b32_e64 v64, v190, v97, s[16:17]
	v_add_f32_e32 v98, v60, v98
	v_cndmask_b32_e64 v58, v190, v98, s[18:19]
	v_add_f32_e32 v99, v61, v99
	v_cndmask_b32_e64 v59, v190, v99, s[6:7]
	v_add_f32_e32 v100, v54, v100
	v_cndmask_b32_e64 v61, v190, v100, s[4:5]
	v_add_f32_e32 v101, v55, v101
	v_cndmask_b32_e64 v60, v190, v101, s[8:9]
	v_add_f32_e32 v102, v56, v102
	v_cndmask_b32_e64 v55, v190, v102, s[10:11]
	v_add_f32_e32 v103, v57, v103
	v_cndmask_b32_e64 v54, v190, v103, s[12:13]
	v_add_f32_e32 v104, v50, v104
	v_cndmask_b32_e64 v57, v190, v104, s[14:15]
	v_add_f32_e32 v105, v51, v105
	v_cndmask_b32_e64 v56, v190, v105, s[16:17]
	v_add_f32_e32 v106, v52, v106
	v_cndmask_b32_e64 v51, v190, v106, s[18:19]
	v_add_f32_e32 v107, v53, v107
	v_cndmask_b32_e64 v50, v190, v107, s[6:7]
	v_add_f32_e32 v108, v46, v108
	v_cndmask_b32_e64 v53, v190, v108, s[4:5]
	v_add_f32_e32 v109, v47, v109
	v_cndmask_b32_e64 v52, v190, v109, s[8:9]
	v_add_f32_e32 v110, v48, v110
	v_cndmask_b32_e64 v47, v190, v110, s[10:11]
	v_add_f32_e32 v111, v49, v111
	v_cndmask_b32_e64 v46, v190, v111, s[12:13]
	v_add_f32_e32 v112, v42, v112
	v_cndmask_b32_e64 v49, v190, v112, s[14:15]
	v_add_f32_e32 v113, v43, v113
	v_cndmask_b32_e64 v48, v190, v113, s[16:17]
	v_add_f32_e32 v114, v44, v114
	v_cndmask_b32_e64 v43, v190, v114, s[18:19]
	v_add_f32_e32 v115, v45, v115
	v_cndmask_b32_e64 v42, v190, v115, s[6:7]
	v_add_f32_e32 v116, v38, v116
	v_cndmask_b32_e64 v45, v190, v116, s[4:5]
	v_add_f32_e32 v117, v39, v117
	v_cndmask_b32_e64 v44, v190, v117, s[8:9]
	v_add_f32_e32 v118, v40, v118
	v_cndmask_b32_e64 v39, v190, v118, s[10:11]
	v_add_f32_e32 v119, v41, v119
	v_cndmask_b32_e64 v38, v190, v119, s[12:13]
	v_add_f32_e32 v120, v34, v120
	v_cndmask_b32_e64 v41, v190, v120, s[14:15]
	v_add_f32_e32 v121, v35, v121
	v_cndmask_b32_e64 v40, v190, v121, s[16:17]
	v_add_f32_e32 v122, v36, v122
	v_cndmask_b32_e64 v35, v190, v122, s[18:19]
	v_add_f32_e32 v123, v37, v123
	v_cndmask_b32_e64 v34, v190, v123, s[6:7]
	v_add_f32_e32 v124, v30, v124
	v_cndmask_b32_e64 v37, v190, v124, s[4:5]
	v_add_f32_e32 v125, v31, v125
	v_cndmask_b32_e64 v36, v190, v125, s[8:9]
	v_add_f32_e32 v126, v32, v126
	v_cndmask_b32_e64 v31, v190, v126, s[10:11]
	v_add_f32_e32 v127, v33, v127
	v_cndmask_b32_e64 v30, v190, v127, s[12:13]
	v_add_f32_e32 v152, v26, v152
	v_cndmask_b32_e64 v33, v190, v152, s[14:15]
	v_add_f32_e32 v153, v27, v153
	v_cndmask_b32_e64 v32, v190, v153, s[16:17]
	v_add_f32_e32 v154, v28, v154
	v_cndmask_b32_e64 v27, v190, v154, s[18:19]
	v_add_f32_e32 v155, v29, v155
	v_cndmask_b32_e64 v26, v190, v155, s[6:7]
	v_add_f32_e32 v156, v22, v156
	v_cndmask_b32_e64 v29, v190, v156, s[4:5]
	v_add_f32_e32 v157, v23, v157
	v_cndmask_b32_e64 v28, v190, v157, s[8:9]
	v_add_f32_e32 v158, v24, v158
	v_cndmask_b32_e64 v23, v190, v158, s[10:11]
	v_add_f32_e32 v159, v25, v159
	v_cndmask_b32_e64 v22, v190, v159, s[12:13]
	v_add_f32_e32 v160, v18, v160
	v_cndmask_b32_e64 v25, v190, v160, s[14:15]
	v_add_f32_e32 v161, v19, v161
	v_cndmask_b32_e64 v24, v190, v161, s[16:17]
	v_add_f32_e32 v162, v20, v162
	v_cndmask_b32_e64 v19, v190, v162, s[18:19]
	v_add_f32_e32 v163, v21, v163
	v_cndmask_b32_e64 v18, v190, v163, s[6:7]
	v_add_f32_e32 v164, v14, v164
	v_cndmask_b32_e64 v21, v190, v164, s[4:5]
	v_add_f32_e32 v165, v15, v165
	v_cndmask_b32_e64 v20, v190, v165, s[8:9]
	v_add_f32_e32 v166, v16, v166
	v_cndmask_b32_e64 v15, v190, v166, s[10:11]
	v_add_f32_e32 v167, v17, v167
	v_cndmask_b32_e64 v14, v190, v167, s[12:13]
	v_add_f32_e32 v168, v10, v168
	v_cndmask_b32_e64 v17, v190, v168, s[14:15]
	v_add_f32_e32 v169, v11, v169
	v_cndmask_b32_e64 v16, v190, v169, s[16:17]
	v_add_f32_e32 v170, v12, v170
	v_cndmask_b32_e64 v11, v190, v170, s[18:19]
	v_add_f32_e32 v171, v13, v171
	v_cndmask_b32_e64 v10, v190, v171, s[6:7]
	v_add_f32_e32 v172, v6, v172
	v_cndmask_b32_e64 v13, v190, v172, s[4:5]
	v_add_f32_e32 v173, v7, v173
	v_cndmask_b32_e64 v12, v190, v173, s[8:9]
	v_add_f32_e32 v174, v8, v174
	v_cndmask_b32_e64 v69, v190, v174, s[10:11]
	v_add_f32_e32 v175, v9, v175
	v_cndmask_b32_e64 v7, v190, v175, s[12:13]
	v_add_f32_e32 v176, v2, v176
	v_cndmask_b32_e64 v8, v190, v176, s[14:15]
	v_add_f32_e32 v177, v3, v177
	v_cndmask_b32_e64 v6, v190, v177, s[16:17]
	v_add_f32_e32 v178, v4, v178
	v_cndmask_b32_e64 v2, v190, v178, s[18:19]
	v_add_f32_e32 v179, v5, v179
	v_cndmask_b32_e64 v3, v190, v179, s[6:7]
	v_writelane_b32 v255, s24, 52
	s_branch .LBB0_305
